# accumulator offset splats as v_mov_b32 + seven v_mov_b64 also in the P10 tile bodies and the P2/P7 memory-attention tasks
# speedup vs baseline: 1.0025x; 1.0005x over previous
.LBB0_284:
	s_lshl_b32 s12, s17, 3
	s_andn2_b32 s12, s12, 31
	v_or_b32_e32 v178, s12, v181
	v_ashrrev_i32_e32 v179, 31, v178
	v_lshlrev_b64 v[4:5], 9, v[178:179]
	v_lshl_add_u64 v[4:5], v[164:165], 0, v[4:5]
	global_load_dwordx4 v[52:55], v[4:5], off
	global_load_dwordx4 v[56:59], v[4:5], off offset:32
	global_load_dwordx4 v[60:63], v[4:5], off offset:64
	global_load_dwordx4 v[64:67], v[4:5], off offset:96
	global_load_dwordx4 v[100:103], v[166:167], off
	global_load_dwordx4 v[104:107], v[166:167], off offset:1024
	global_load_dwordx4 v[108:111], v[166:167], off offset:2048
	global_load_dwordx4 v[112:115], v[166:167], off offset:3072
	global_load_dwordx4 v[80:83], v[168:169], off
	global_load_dwordx4 v[76:79], v[168:169], off offset:1024
	global_load_dwordx4 v[72:75], v[168:169], off offset:2048
	global_load_dwordx4 v[68:71], v[168:169], off offset:3072
	global_load_dwordx4 v[116:119], v[170:171], off
	global_load_dwordx4 v[120:123], v[170:171], off offset:1024
	global_load_dwordx4 v[124:127], v[170:171], off offset:2048
	global_load_dwordx4 v[128:131], v[170:171], off offset:3072
	global_load_dwordx4 v[96:99], v[172:173], off
	global_load_dwordx4 v[92:95], v[172:173], off offset:1024
	global_load_dwordx4 v[88:91], v[172:173], off offset:2048
	global_load_dwordx4 v[84:87], v[172:173], off offset:3072
	global_load_dwordx4 v[144:147], v[174:175], off
	global_load_dwordx4 v[140:143], v[174:175], off offset:1024
	global_load_dwordx4 v[136:139], v[174:175], off offset:2048
	global_load_dwordx4 v[132:135], v[174:175], off offset:3072
	v_mov_b32_e32 v3, v2
	v_mov_b64_e32 v[4:5], v[2:3]
	v_mov_b64_e32 v[6:7], v[2:3]
	v_mov_b64_e32 v[8:9], v[2:3]
	v_mov_b64_e32 v[10:11], v[2:3]
	v_mov_b64_e32 v[12:13], v[2:3]
	v_mov_b64_e32 v[14:15], v[2:3]
	v_mov_b64_e32 v[16:17], v[2:3]
	v_mov_b64_e32 v[34:35], v[16:17]
	v_mov_b64_e32 v[32:33], v[14:15]
	v_mov_b64_e32 v[30:31], v[12:13]
	v_mov_b64_e32 v[28:29], v[10:11]
	v_mov_b64_e32 v[26:27], v[8:9]
	v_mov_b64_e32 v[24:25], v[6:7]
	v_mov_b64_e32 v[22:23], v[4:5]
	v_mov_b64_e32 v[20:21], v[2:3]
	v_mov_b64_e32 v[18:19], v[16:17]
	s_mov_b32 s19, 0
	s_movk_i32 s18, 0x1800
	v_mov_b32_e32 v183, 0
	s_mov_b64 s[14:15], s[8:9]
	v_mov_b64_e32 v[16:17], v[14:15]
	v_mov_b64_e32 v[14:15], v[12:13]
	v_mov_b64_e32 v[12:13], v[10:11]
	v_mov_b64_e32 v[10:11], v[8:9]
	v_mov_b64_e32 v[8:9], v[6:7]
	v_mov_b64_e32 v[6:7], v[4:5]
	v_mov_b64_e32 v[4:5], v[2:3]
.LBB0_285:
	global_load_dwordx4 v[160:163], v182, s[14:15]
	global_load_dwordx4 v[156:159], v182, s[14:15] offset:1024
	global_load_dwordx4 v[152:155], v182, s[14:15] offset:2048
	global_load_dwordx4 v[148:151], v182, s[14:15] offset:3072
	v_mov_b32 v3, 0
	s_cmp_gt_u32 s19, 4
	v_sub_f32_e32 v36, v3, v180
	v_mov_b32_e32 v37, v36
	v_mov_b64_e32 v[38:39], v[36:37]
	v_mov_b64_e32 v[40:41], v[36:37]
	v_mov_b64_e32 v[42:43], v[36:37]
	v_mov_b64_e32 v[44:45], v[36:37]
	v_mov_b64_e32 v[46:47], v[36:37]
	v_mov_b64_e32 v[48:49], v[36:37]
	v_mov_b64_e32 v[50:51], v[36:37]
	s_cselect_b64 s[12:13], -1, 0
	s_cmp_lt_u32 s19, 5
	s_waitcnt vmcnt(23)
	v_mfma_f32_32x32x16_bf16 v[36:51], v[100:103], v[52:55], v[36:51]
	s_cselect_b32 s14, s18, 0x3800
	s_and_b32 s15, s14, 0x7000
	s_lshl_b32 s20, s15, 1
	s_add_u32 s15, s4, s20
	s_addc_u32 s21, s5, 0
	s_and_b32 s14, s14, 0x800
	s_lshl_b32 s22, s14, 1
	s_waitcnt vmcnt(22)
	v_mfma_f32_32x32x16_bf16 v[36:51], v[104:107], v[56:59], v[36:51]
	s_add_u32 s14, s15, s22
	s_addc_u32 s15, s21, 0
	s_waitcnt vmcnt(21)
	v_mfma_f32_32x32x16_bf16 v[36:51], v[108:111], v[60:63], v[36:51]
	s_waitcnt vmcnt(20)
	v_mfma_f32_32x32x16_bf16 v[36:51], v[112:115], v[64:67], v[36:51]
	global_load_dwordx4 v[100:103], v182, s[14:15]
	global_load_dwordx4 v[104:107], v182, s[14:15] offset:1024
	global_load_dwordx4 v[108:111], v182, s[14:15] offset:2048
	global_load_dwordx4 v[112:115], v182, s[14:15] offset:3072
	s_add_u32 s14, s6, s20
	s_addc_u32 s15, s7, 0
	s_add_u32 s14, s14, s22
	s_addc_u32 s15, s15, 0
	s_nop 3
	v_exp_f32_e32 v3, v36
	v_exp_f32_e32 v177, v37
	v_exp_f32_e32 v184, v38
	v_exp_f32_e32 v185, v39
	v_exp_f32_e32 v186, v40
	v_exp_f32_e32 v187, v41
	v_exp_f32_e32 v188, v42
	v_exp_f32_e32 v189, v43
	v_cvt_pk_bf16_f32 v36, v3, v177
	v_cvt_pk_bf16_f32 v37, v184, v185
	v_cvt_pk_bf16_f32 v38, v186, v187
	v_cvt_pk_bf16_f32 v39, v188, v189
	v_exp_f32_e32 v190, v44
	v_exp_f32_e32 v191, v45
	s_waitcnt vmcnt(23)
	v_mfma_f32_32x32x16_bf16 v[20:35], v[80:83], v[36:39], v[20:35]
	v_exp_f32_e32 v192, v46
	v_exp_f32_e32 v193, v47
	v_exp_f32_e32 v194, v48
	v_exp_f32_e32 v195, v49
	v_exp_f32_e32 v196, v50
	v_exp_f32_e32 v197, v51
	v_add_f32_e32 v3, v183, v3
	s_waitcnt vmcnt(22)
	v_mfma_f32_32x32x16_bf16 v[4:19], v[76:79], v[36:39], v[4:19]
	v_cvt_pk_bf16_f32 v36, v190, v191
	v_cvt_pk_bf16_f32 v37, v192, v193
	v_cvt_pk_bf16_f32 v38, v194, v195
	v_cvt_pk_bf16_f32 v39, v196, v197
	v_add_f32_e32 v3, v177, v3
	v_add_f32_e32 v3, v184, v3
	v_add_f32_e32 v3, v185, v3
	s_waitcnt vmcnt(21)
	v_mfma_f32_32x32x16_bf16 v[20:35], v[72:75], v[36:39], v[20:35]
	v_add_f32_e32 v3, v186, v3
	v_add_f32_e32 v3, v187, v3
	v_add_f32_e32 v3, v188, v3
	v_add_f32_e32 v3, v189, v3
	v_add_f32_e32 v3, v190, v3
	v_add_f32_e32 v3, v191, v3
	v_add_f32_e32 v3, v192, v3
	s_waitcnt vmcnt(20)
	v_mfma_f32_32x32x16_bf16 v[4:19], v[68:71], v[36:39], v[4:19]
	global_load_dwordx4 v[80:83], v182, s[14:15]
	global_load_dwordx4 v[76:79], v182, s[14:15] offset:1024
	global_load_dwordx4 v[72:75], v182, s[14:15] offset:2048
	global_load_dwordx4 v[68:71], v182, s[14:15] offset:3072
	v_mov_b32 v36, 0
	s_min_u32 s14, s19, 3
	v_sub_f32_e32 v36, v36, v180
	v_mov_b32_e32 v37, v36
	v_mov_b64_e32 v[38:39], v[36:37]
	v_mov_b64_e32 v[40:41], v[36:37]
	v_mov_b64_e32 v[42:43], v[36:37]
	v_mov_b64_e32 v[44:45], v[36:37]
	v_mov_b64_e32 v[46:47], v[36:37]
	v_mov_b64_e32 v[48:49], v[36:37]
	v_mov_b64_e32 v[50:51], v[36:37]
	s_lshl_b32 s14, s14, 12
	s_and_b32 s15, s14, 0x2000
	s_waitcnt vmcnt(23)
	v_mfma_f32_32x32x16_bf16 v[36:51], v[116:119], v[52:55], v[36:51]
	s_or_b32 s20, s15, 0x4000
	s_add_u32 s15, s4, s20
	s_addc_u32 s21, s5, 0
	s_and_b32 s22, s14, 0x1000
	s_add_u32 s14, s15, s22
	s_addc_u32 s15, s21, 0
	v_add_f32_e32 v3, v193, v3
	s_waitcnt vmcnt(22)
	v_mfma_f32_32x32x16_bf16 v[36:51], v[120:123], v[56:59], v[36:51]
	v_add_f32_e32 v3, v194, v3
	v_add_f32_e32 v3, v195, v3
	v_add_f32_e32 v3, v196, v3
	v_add_f32_e32 v3, v197, v3
	s_waitcnt vmcnt(21)
	v_mfma_f32_32x32x16_bf16 v[36:51], v[124:127], v[60:63], v[36:51]
	s_waitcnt vmcnt(20)
	v_mfma_f32_32x32x16_bf16 v[36:51], v[128:131], v[64:67], v[36:51]
	global_load_dwordx4 v[116:119], v182, s[14:15]
	global_load_dwordx4 v[120:123], v182, s[14:15] offset:1024
	global_load_dwordx4 v[124:127], v182, s[14:15] offset:2048
	global_load_dwordx4 v[128:131], v182, s[14:15] offset:3072
	s_add_u32 s14, s6, s20
	s_addc_u32 s15, s7, 0
	s_add_u32 s14, s14, s22
	s_addc_u32 s15, s15, 0
	s_cmp_gt_u32 s19, 5
	s_nop 2
	v_exp_f32_e32 v200, v36
	v_exp_f32_e32 v201, v37
	v_exp_f32_e32 v202, v38
	v_exp_f32_e32 v203, v39
	v_exp_f32_e32 v40, v40
	v_exp_f32_e32 v41, v41
	v_exp_f32_e32 v42, v42
	v_exp_f32_e32 v43, v43
	v_cvt_pk_bf16_f32 v36, v200, v201
	v_cvt_pk_bf16_f32 v37, v202, v203
	v_cvt_pk_bf16_f32 v38, v40, v41
	v_cvt_pk_bf16_f32 v39, v42, v43
	v_exp_f32_e32 v44, v44
	v_exp_f32_e32 v45, v45
	s_waitcnt vmcnt(23)
	v_mfma_f32_32x32x16_bf16 v[20:35], v[96:99], v[36:39], v[20:35]
	v_exp_f32_e32 v46, v46
	v_exp_f32_e32 v47, v47
	v_exp_f32_e32 v48, v48
	v_exp_f32_e32 v49, v49
	v_exp_f32_e32 v50, v50
	v_exp_f32_e32 v51, v51
	v_add_f32_e32 v3, v3, v200
	s_waitcnt vmcnt(22)
	v_mfma_f32_32x32x16_bf16 v[4:19], v[92:95], v[36:39], v[4:19]
	v_cvt_pk_bf16_f32 v36, v44, v45
	v_cvt_pk_bf16_f32 v37, v46, v47
	v_cvt_pk_bf16_f32 v38, v48, v49
	v_cvt_pk_bf16_f32 v39, v50, v51
	v_add_f32_e32 v3, v201, v3
	v_add_f32_e32 v3, v202, v3
	v_add_f32_e32 v3, v203, v3
	s_waitcnt vmcnt(21)
	v_mfma_f32_32x32x16_bf16 v[20:35], v[88:91], v[36:39], v[20:35]
	v_add_f32_e32 v3, v40, v3
	v_add_f32_e32 v3, v41, v3
	v_add_f32_e32 v3, v42, v3
	v_add_f32_e32 v3, v43, v3
	v_add_f32_e32 v3, v44, v3
	v_add_f32_e32 v3, v45, v3
	v_add_f32_e32 v3, v46, v3
	s_waitcnt vmcnt(20)
	v_mfma_f32_32x32x16_bf16 v[4:19], v[84:87], v[36:39], v[4:19]
	global_load_dwordx4 v[96:99], v182, s[14:15]
	global_load_dwordx4 v[92:95], v182, s[14:15] offset:1024
	global_load_dwordx4 v[88:91], v182, s[14:15] offset:2048
	global_load_dwordx4 v[84:87], v182, s[14:15] offset:3072
	v_add_f32_e32 v3, v47, v3
	v_add_f32_e32 v3, v48, v3
	v_add_f32_e32 v3, v49, v3
	v_add_f32_e32 v3, v50, v3
	v_add_f32_e32 v183, v51, v3
	s_cbranch_scc1 .LBB0_287
	v_mov_b32 v3, 0
	s_nop 0
	v_sub_f32_e32 v36, v3, v180
	v_mov_b32_e32 v37, v36
	v_mov_b64_e32 v[38:39], v[36:37]
	v_mov_b64_e32 v[40:41], v[36:37]
	v_mov_b64_e32 v[42:43], v[36:37]
	v_mov_b64_e32 v[44:45], v[36:37]
	v_mov_b64_e32 v[46:47], v[36:37]
	v_mov_b64_e32 v[48:49], v[36:37]
	v_mov_b64_e32 v[50:51], v[36:37]
	s_waitcnt vmcnt(19)
	s_nop 0
	v_mfma_f32_32x32x16_bf16 v[36:51], v[160:163], v[52:55], v[36:51]
	s_waitcnt vmcnt(18)
	v_mfma_f32_32x32x16_bf16 v[36:51], v[156:159], v[56:59], v[36:51]
	s_waitcnt vmcnt(17)
	v_mfma_f32_32x32x16_bf16 v[36:51], v[152:155], v[60:63], v[36:51]
	s_waitcnt vmcnt(16)
	v_mfma_f32_32x32x16_bf16 v[36:51], v[148:151], v[64:67], v[36:51]
	s_nop 11
	v_exp_f32_e32 v3, v36
	v_exp_f32_e32 v148, v37
	v_exp_f32_e32 v149, v38
	v_exp_f32_e32 v150, v39
	v_exp_f32_e32 v40, v40
	v_exp_f32_e32 v41, v41
	v_exp_f32_e32 v42, v42
	v_exp_f32_e32 v43, v43
	v_add_f32_e32 v151, v183, v3
	v_cvt_pk_bf16_f32 v36, v3, v148
	v_add_f32_e32 v3, v148, v151
	v_cvt_pk_bf16_f32 v37, v149, v150
	v_cvt_pk_bf16_f32 v38, v40, v41
	v_cvt_pk_bf16_f32 v39, v42, v43
	v_add_f32_e32 v3, v149, v3
	v_add_f32_e32 v3, v150, v3
	v_mfma_f32_32x32x16_bf16 v[20:35], v[144:147], v[36:39], v[20:35]
	v_add_f32_e32 v3, v40, v3
	v_add_f32_e32 v3, v41, v3
	v_exp_f32_e32 v44, v44
	v_exp_f32_e32 v45, v45
	v_exp_f32_e32 v46, v46
	v_exp_f32_e32 v47, v47
	v_exp_f32_e32 v48, v48
	v_mfma_f32_32x32x16_bf16 v[4:19], v[140:143], v[36:39], v[4:19]
	v_add_f32_e32 v3, v42, v3
	v_exp_f32_e32 v40, v49
	v_exp_f32_e32 v41, v50
	v_exp_f32_e32 v42, v51
	v_add_f32_e32 v3, v43, v3
	v_cvt_pk_bf16_f32 v36, v44, v45
	v_cvt_pk_bf16_f32 v37, v46, v47
	v_cvt_pk_bf16_f32 v38, v48, v40
	v_cvt_pk_bf16_f32 v39, v41, v42
	v_add_f32_e32 v3, v44, v3
	v_add_f32_e32 v3, v45, v3
	v_mfma_f32_32x32x16_bf16 v[20:35], v[136:139], v[36:39], v[20:35]
	v_add_f32_e32 v3, v46, v3
	v_add_f32_e32 v3, v47, v3
	v_add_f32_e32 v3, v48, v3
	v_add_f32_e32 v3, v40, v3
	v_add_f32_e32 v3, v41, v3
	v_add_f32_e32 v183, v42, v3
	v_mfma_f32_32x32x16_bf16 v[4:19], v[132:135], v[36:39], v[4:19]

.LBB0_925:
	s_lshl_b32 s12, s19, 3
	s_andn2_b32 s12, s12, 31
	v_or_b32_e32 v178, s12, v181
	v_ashrrev_i32_e32 v179, 31, v178
	v_lshlrev_b64 v[4:5], 9, v[178:179]
	v_lshl_add_u64 v[4:5], v[164:165], 0, v[4:5]
	global_load_dwordx4 v[52:55], v[4:5], off
	global_load_dwordx4 v[56:59], v[4:5], off offset:32
	global_load_dwordx4 v[60:63], v[4:5], off offset:64
	global_load_dwordx4 v[64:67], v[4:5], off offset:96
	global_load_dwordx4 v[100:103], v[166:167], off
	global_load_dwordx4 v[104:107], v[166:167], off offset:1024
	global_load_dwordx4 v[108:111], v[166:167], off offset:2048
	global_load_dwordx4 v[112:115], v[166:167], off offset:3072
	global_load_dwordx4 v[80:83], v[168:169], off
	global_load_dwordx4 v[76:79], v[168:169], off offset:1024
	global_load_dwordx4 v[72:75], v[168:169], off offset:2048
	global_load_dwordx4 v[68:71], v[168:169], off offset:3072
	global_load_dwordx4 v[116:119], v[170:171], off
	global_load_dwordx4 v[120:123], v[170:171], off offset:1024
	global_load_dwordx4 v[124:127], v[170:171], off offset:2048
	global_load_dwordx4 v[128:131], v[170:171], off offset:3072
	global_load_dwordx4 v[96:99], v[172:173], off
	global_load_dwordx4 v[92:95], v[172:173], off offset:1024
	global_load_dwordx4 v[88:91], v[172:173], off offset:2048
	global_load_dwordx4 v[84:87], v[172:173], off offset:3072
	global_load_dwordx4 v[144:147], v[174:175], off
	global_load_dwordx4 v[140:143], v[174:175], off offset:1024
	global_load_dwordx4 v[136:139], v[174:175], off offset:2048
	global_load_dwordx4 v[132:135], v[174:175], off offset:3072
	v_mov_b32_e32 v3, v2
	v_mov_b64_e32 v[4:5], v[2:3]
	v_mov_b64_e32 v[6:7], v[2:3]
	v_mov_b64_e32 v[8:9], v[2:3]
	v_mov_b64_e32 v[10:11], v[2:3]
	v_mov_b64_e32 v[12:13], v[2:3]
	v_mov_b64_e32 v[14:15], v[2:3]
	v_mov_b64_e32 v[16:17], v[2:3]
	v_mov_b64_e32 v[34:35], v[16:17]
	v_mov_b64_e32 v[32:33], v[14:15]
	v_mov_b64_e32 v[30:31], v[12:13]
	v_mov_b64_e32 v[28:29], v[10:11]
	v_mov_b64_e32 v[26:27], v[8:9]
	v_mov_b64_e32 v[24:25], v[6:7]
	v_mov_b64_e32 v[22:23], v[4:5]
	v_mov_b64_e32 v[20:21], v[2:3]
	v_mov_b64_e32 v[18:19], v[16:17]
	s_mov_b32 s21, 0
	s_movk_i32 s20, 0x1800
	v_mov_b32_e32 v183, 0
	s_mov_b64 s[14:15], s[8:9]
	v_mov_b64_e32 v[16:17], v[14:15]
	v_mov_b64_e32 v[14:15], v[12:13]
	v_mov_b64_e32 v[12:13], v[10:11]
	v_mov_b64_e32 v[10:11], v[8:9]
	v_mov_b64_e32 v[8:9], v[6:7]
	v_mov_b64_e32 v[6:7], v[4:5]
	v_mov_b64_e32 v[4:5], v[2:3]
.LBB0_926:
	global_load_dwordx4 v[160:163], v182, s[14:15]
	global_load_dwordx4 v[156:159], v182, s[14:15] offset:1024
	global_load_dwordx4 v[152:155], v182, s[14:15] offset:2048
	global_load_dwordx4 v[148:151], v182, s[14:15] offset:3072
	v_mov_b32 v3, 0
	s_cmp_gt_u32 s21, 4
	v_sub_f32_e32 v36, v3, v180
	v_mov_b32_e32 v37, v36
	v_mov_b64_e32 v[38:39], v[36:37]
	v_mov_b64_e32 v[40:41], v[36:37]
	v_mov_b64_e32 v[42:43], v[36:37]
	v_mov_b64_e32 v[44:45], v[36:37]
	v_mov_b64_e32 v[46:47], v[36:37]
	v_mov_b64_e32 v[48:49], v[36:37]
	v_mov_b64_e32 v[50:51], v[36:37]
	s_cselect_b64 s[12:13], -1, 0
	s_cmp_lt_u32 s21, 5
	s_waitcnt vmcnt(23)
	v_mfma_f32_32x32x16_bf16 v[36:51], v[100:103], v[52:55], v[36:51]
	s_cselect_b32 s14, s20, 0x3800
	s_and_b32 s15, s14, 0x7000
	s_lshl_b32 s22, s15, 1
	s_add_u32 s15, s4, s22
	s_addc_u32 s23, s5, 0
	s_and_b32 s14, s14, 0x800
	s_lshl_b32 s24, s14, 1
	s_waitcnt vmcnt(22)
	v_mfma_f32_32x32x16_bf16 v[36:51], v[104:107], v[56:59], v[36:51]
	s_add_u32 s14, s15, s24
	s_addc_u32 s15, s23, 0
	s_waitcnt vmcnt(21)
	v_mfma_f32_32x32x16_bf16 v[36:51], v[108:111], v[60:63], v[36:51]
	s_waitcnt vmcnt(20)
	v_mfma_f32_32x32x16_bf16 v[36:51], v[112:115], v[64:67], v[36:51]
	global_load_dwordx4 v[100:103], v182, s[14:15]
	global_load_dwordx4 v[104:107], v182, s[14:15] offset:1024
	global_load_dwordx4 v[108:111], v182, s[14:15] offset:2048
	global_load_dwordx4 v[112:115], v182, s[14:15] offset:3072
	s_add_u32 s14, s6, s22
	s_addc_u32 s15, s7, 0
	s_add_u32 s14, s14, s24
	s_addc_u32 s15, s15, 0
	s_nop 3
	v_exp_f32_e32 v3, v36
	v_exp_f32_e32 v177, v37
	v_exp_f32_e32 v184, v38
	v_exp_f32_e32 v185, v39
	v_exp_f32_e32 v186, v40
	v_exp_f32_e32 v187, v41
	v_exp_f32_e32 v188, v42
	v_exp_f32_e32 v189, v43
	v_cvt_pk_bf16_f32 v36, v3, v177
	v_cvt_pk_bf16_f32 v37, v184, v185
	v_cvt_pk_bf16_f32 v38, v186, v187
	v_cvt_pk_bf16_f32 v39, v188, v189
	v_exp_f32_e32 v190, v44
	v_exp_f32_e32 v191, v45
	s_waitcnt vmcnt(23)
	v_mfma_f32_32x32x16_bf16 v[20:35], v[80:83], v[36:39], v[20:35]
	v_exp_f32_e32 v192, v46
	v_exp_f32_e32 v193, v47
	v_exp_f32_e32 v194, v48
	v_exp_f32_e32 v195, v49
	v_exp_f32_e32 v196, v50
	v_exp_f32_e32 v197, v51
	v_add_f32_e32 v3, v183, v3
	s_waitcnt vmcnt(22)
	v_mfma_f32_32x32x16_bf16 v[4:19], v[76:79], v[36:39], v[4:19]
	v_cvt_pk_bf16_f32 v36, v190, v191
	v_cvt_pk_bf16_f32 v37, v192, v193
	v_cvt_pk_bf16_f32 v38, v194, v195
	v_cvt_pk_bf16_f32 v39, v196, v197
	v_add_f32_e32 v3, v177, v3
	v_add_f32_e32 v3, v184, v3
	v_add_f32_e32 v3, v185, v3
	s_waitcnt vmcnt(21)
	v_mfma_f32_32x32x16_bf16 v[20:35], v[72:75], v[36:39], v[20:35]
	v_add_f32_e32 v3, v186, v3
	v_add_f32_e32 v3, v187, v3
	v_add_f32_e32 v3, v188, v3
	v_add_f32_e32 v3, v189, v3
	v_add_f32_e32 v3, v190, v3
	v_add_f32_e32 v3, v191, v3
	v_add_f32_e32 v3, v192, v3
	s_waitcnt vmcnt(20)
	v_mfma_f32_32x32x16_bf16 v[4:19], v[68:71], v[36:39], v[4:19]
	global_load_dwordx4 v[80:83], v182, s[14:15]
	global_load_dwordx4 v[76:79], v182, s[14:15] offset:1024
	global_load_dwordx4 v[72:75], v182, s[14:15] offset:2048
	global_load_dwordx4 v[68:71], v182, s[14:15] offset:3072
	v_mov_b32 v36, 0
	s_min_u32 s14, s21, 3
	v_sub_f32_e32 v36, v36, v180
	v_mov_b32_e32 v37, v36
	v_mov_b64_e32 v[38:39], v[36:37]
	v_mov_b64_e32 v[40:41], v[36:37]
	v_mov_b64_e32 v[42:43], v[36:37]
	v_mov_b64_e32 v[44:45], v[36:37]
	v_mov_b64_e32 v[46:47], v[36:37]
	v_mov_b64_e32 v[48:49], v[36:37]
	v_mov_b64_e32 v[50:51], v[36:37]
	s_lshl_b32 s14, s14, 12
	s_and_b32 s15, s14, 0x2000
	s_waitcnt vmcnt(23)
	v_mfma_f32_32x32x16_bf16 v[36:51], v[116:119], v[52:55], v[36:51]
	s_or_b32 s22, s15, 0x4000
	s_add_u32 s15, s4, s22
	s_addc_u32 s23, s5, 0
	s_and_b32 s24, s14, 0x1000
	s_add_u32 s14, s15, s24
	s_addc_u32 s15, s23, 0
	v_add_f32_e32 v3, v193, v3
	s_waitcnt vmcnt(22)
	v_mfma_f32_32x32x16_bf16 v[36:51], v[120:123], v[56:59], v[36:51]
	v_add_f32_e32 v3, v194, v3
	v_add_f32_e32 v3, v195, v3
	v_add_f32_e32 v3, v196, v3
	v_add_f32_e32 v3, v197, v3
	s_waitcnt vmcnt(21)
	v_mfma_f32_32x32x16_bf16 v[36:51], v[124:127], v[60:63], v[36:51]
	s_waitcnt vmcnt(20)
	v_mfma_f32_32x32x16_bf16 v[36:51], v[128:131], v[64:67], v[36:51]
	global_load_dwordx4 v[116:119], v182, s[14:15]
	global_load_dwordx4 v[120:123], v182, s[14:15] offset:1024
	global_load_dwordx4 v[124:127], v182, s[14:15] offset:2048
	global_load_dwordx4 v[128:131], v182, s[14:15] offset:3072
	s_add_u32 s14, s6, s22
	s_addc_u32 s15, s7, 0
	s_add_u32 s14, s14, s24
	s_addc_u32 s15, s15, 0
	s_cmp_gt_u32 s21, 5
	s_nop 2
	v_exp_f32_e32 v200, v36
	v_exp_f32_e32 v201, v37
	v_exp_f32_e32 v202, v38
	v_exp_f32_e32 v203, v39
	v_exp_f32_e32 v40, v40
	v_exp_f32_e32 v41, v41
	v_exp_f32_e32 v42, v42
	v_exp_f32_e32 v43, v43
	v_cvt_pk_bf16_f32 v36, v200, v201
	v_cvt_pk_bf16_f32 v37, v202, v203
	v_cvt_pk_bf16_f32 v38, v40, v41
	v_cvt_pk_bf16_f32 v39, v42, v43
	v_exp_f32_e32 v44, v44
	v_exp_f32_e32 v45, v45
	s_waitcnt vmcnt(23)
	v_mfma_f32_32x32x16_bf16 v[20:35], v[96:99], v[36:39], v[20:35]
	v_exp_f32_e32 v46, v46
	v_exp_f32_e32 v47, v47
	v_exp_f32_e32 v48, v48
	v_exp_f32_e32 v49, v49
	v_exp_f32_e32 v50, v50
	v_exp_f32_e32 v51, v51
	v_add_f32_e32 v3, v3, v200
	s_waitcnt vmcnt(22)
	v_mfma_f32_32x32x16_bf16 v[4:19], v[92:95], v[36:39], v[4:19]
	v_cvt_pk_bf16_f32 v36, v44, v45
	v_cvt_pk_bf16_f32 v37, v46, v47
	v_cvt_pk_bf16_f32 v38, v48, v49
	v_cvt_pk_bf16_f32 v39, v50, v51
	v_add_f32_e32 v3, v201, v3
	v_add_f32_e32 v3, v202, v3
	v_add_f32_e32 v3, v203, v3
	s_waitcnt vmcnt(21)
	v_mfma_f32_32x32x16_bf16 v[20:35], v[88:91], v[36:39], v[20:35]
	v_add_f32_e32 v3, v40, v3
	v_add_f32_e32 v3, v41, v3
	v_add_f32_e32 v3, v42, v3
	v_add_f32_e32 v3, v43, v3
	v_add_f32_e32 v3, v44, v3
	v_add_f32_e32 v3, v45, v3
	v_add_f32_e32 v3, v46, v3
	s_waitcnt vmcnt(20)
	v_mfma_f32_32x32x16_bf16 v[4:19], v[84:87], v[36:39], v[4:19]
	global_load_dwordx4 v[96:99], v182, s[14:15]
	global_load_dwordx4 v[92:95], v182, s[14:15] offset:1024
	global_load_dwordx4 v[88:91], v182, s[14:15] offset:2048
	global_load_dwordx4 v[84:87], v182, s[14:15] offset:3072
	v_add_f32_e32 v3, v47, v3
	v_add_f32_e32 v3, v48, v3
	v_add_f32_e32 v3, v49, v3
	v_add_f32_e32 v3, v50, v3
	v_add_f32_e32 v183, v51, v3
	s_cbranch_scc1 .LBB0_928
	v_mov_b32 v3, 0
	s_nop 0
	v_sub_f32_e32 v36, v3, v180
	v_mov_b32_e32 v37, v36
	v_mov_b64_e32 v[38:39], v[36:37]
	v_mov_b64_e32 v[40:41], v[36:37]
	v_mov_b64_e32 v[42:43], v[36:37]
	v_mov_b64_e32 v[44:45], v[36:37]
	v_mov_b64_e32 v[46:47], v[36:37]
	v_mov_b64_e32 v[48:49], v[36:37]
	v_mov_b64_e32 v[50:51], v[36:37]
	s_waitcnt vmcnt(19)
	s_nop 0
	v_mfma_f32_32x32x16_bf16 v[36:51], v[160:163], v[52:55], v[36:51]
	s_waitcnt vmcnt(18)
	v_mfma_f32_32x32x16_bf16 v[36:51], v[156:159], v[56:59], v[36:51]
	s_waitcnt vmcnt(17)
	v_mfma_f32_32x32x16_bf16 v[36:51], v[152:155], v[60:63], v[36:51]
	s_waitcnt vmcnt(16)
	v_mfma_f32_32x32x16_bf16 v[36:51], v[148:151], v[64:67], v[36:51]
	s_nop 11
	v_exp_f32_e32 v3, v36
	v_exp_f32_e32 v148, v37
	v_exp_f32_e32 v149, v38
	v_exp_f32_e32 v150, v39
	v_exp_f32_e32 v40, v40
	v_exp_f32_e32 v41, v41
	v_exp_f32_e32 v42, v42
	v_exp_f32_e32 v43, v43
	v_add_f32_e32 v151, v183, v3
	v_cvt_pk_bf16_f32 v36, v3, v148
	v_add_f32_e32 v3, v148, v151
	v_cvt_pk_bf16_f32 v37, v149, v150
	v_cvt_pk_bf16_f32 v38, v40, v41
	v_cvt_pk_bf16_f32 v39, v42, v43
	v_add_f32_e32 v3, v149, v3
	v_add_f32_e32 v3, v150, v3
	v_mfma_f32_32x32x16_bf16 v[20:35], v[144:147], v[36:39], v[20:35]
	v_add_f32_e32 v3, v40, v3
	v_add_f32_e32 v3, v41, v3
	v_exp_f32_e32 v44, v44
	v_exp_f32_e32 v45, v45
	v_exp_f32_e32 v46, v46
	v_exp_f32_e32 v47, v47
	v_exp_f32_e32 v48, v48
	v_mfma_f32_32x32x16_bf16 v[4:19], v[140:143], v[36:39], v[4:19]
	v_add_f32_e32 v3, v42, v3
	v_exp_f32_e32 v40, v49
	v_exp_f32_e32 v41, v50
	v_exp_f32_e32 v42, v51
	v_add_f32_e32 v3, v43, v3
	v_cvt_pk_bf16_f32 v36, v44, v45
	v_cvt_pk_bf16_f32 v37, v46, v47
	v_cvt_pk_bf16_f32 v38, v48, v40
	v_cvt_pk_bf16_f32 v39, v41, v42
	v_add_f32_e32 v3, v44, v3
	v_add_f32_e32 v3, v45, v3
	v_mfma_f32_32x32x16_bf16 v[20:35], v[136:139], v[36:39], v[20:35]
	v_add_f32_e32 v3, v46, v3
	v_add_f32_e32 v3, v47, v3
	v_add_f32_e32 v3, v48, v3
	v_add_f32_e32 v3, v40, v3
	v_add_f32_e32 v3, v41, v3
	v_add_f32_e32 v183, v42, v3
	v_mfma_f32_32x32x16_bf16 v[4:19], v[132:135], v[36:39], v[4:19]

.LBB0_936:
	s_lshl_b32 s12, s18, 3
	s_andn2_b32 s12, s12, 31
	v_or_b32_e32 v178, s12, v181
	v_ashrrev_i32_e32 v179, 31, v178
	v_lshlrev_b64 v[4:5], 9, v[178:179]
	v_lshl_add_u64 v[4:5], v[164:165], 0, v[4:5]
	global_load_dwordx4 v[52:55], v[4:5], off
	global_load_dwordx4 v[56:59], v[4:5], off offset:32
	global_load_dwordx4 v[60:63], v[4:5], off offset:64
	global_load_dwordx4 v[64:67], v[4:5], off offset:96
	global_load_dwordx4 v[100:103], v[166:167], off
	global_load_dwordx4 v[104:107], v[166:167], off offset:1024
	global_load_dwordx4 v[108:111], v[166:167], off offset:2048
	global_load_dwordx4 v[112:115], v[166:167], off offset:3072
	global_load_dwordx4 v[80:83], v[168:169], off
	global_load_dwordx4 v[76:79], v[168:169], off offset:1024
	global_load_dwordx4 v[72:75], v[168:169], off offset:2048
	global_load_dwordx4 v[68:71], v[168:169], off offset:3072
	global_load_dwordx4 v[116:119], v[170:171], off
	global_load_dwordx4 v[120:123], v[170:171], off offset:1024
	global_load_dwordx4 v[124:127], v[170:171], off offset:2048
	global_load_dwordx4 v[128:131], v[170:171], off offset:3072
	global_load_dwordx4 v[96:99], v[172:173], off
	global_load_dwordx4 v[92:95], v[172:173], off offset:1024
	global_load_dwordx4 v[88:91], v[172:173], off offset:2048
	global_load_dwordx4 v[84:87], v[172:173], off offset:3072
	global_load_dwordx4 v[144:147], v[174:175], off
	global_load_dwordx4 v[140:143], v[174:175], off offset:1024
	global_load_dwordx4 v[136:139], v[174:175], off offset:2048
	global_load_dwordx4 v[132:135], v[174:175], off offset:3072
	v_mov_b32_e32 v3, v2
	v_mov_b64_e32 v[4:5], v[2:3]
	v_mov_b64_e32 v[6:7], v[2:3]
	v_mov_b64_e32 v[8:9], v[2:3]
	v_mov_b64_e32 v[10:11], v[2:3]
	v_mov_b64_e32 v[12:13], v[2:3]
	v_mov_b64_e32 v[14:15], v[2:3]
	v_mov_b64_e32 v[16:17], v[2:3]
	v_mov_b64_e32 v[34:35], v[16:17]
	v_mov_b64_e32 v[32:33], v[14:15]
	v_mov_b64_e32 v[30:31], v[12:13]
	v_mov_b64_e32 v[28:29], v[10:11]
	v_mov_b64_e32 v[26:27], v[8:9]
	v_mov_b64_e32 v[24:25], v[6:7]
	v_mov_b64_e32 v[22:23], v[4:5]
	v_mov_b64_e32 v[20:21], v[2:3]
	v_mov_b64_e32 v[18:19], v[16:17]
	s_mov_b32 s20, 0
	s_movk_i32 s17, 0x1800
	v_mov_b32_e32 v183, 0
	s_mov_b64 s[14:15], s[8:9]
	v_mov_b64_e32 v[16:17], v[14:15]
	v_mov_b64_e32 v[14:15], v[12:13]
	v_mov_b64_e32 v[12:13], v[10:11]
	v_mov_b64_e32 v[10:11], v[8:9]
	v_mov_b64_e32 v[8:9], v[6:7]
	v_mov_b64_e32 v[6:7], v[4:5]
	v_mov_b64_e32 v[4:5], v[2:3]
.LBB0_937:
	global_load_dwordx4 v[160:163], v182, s[14:15]
	global_load_dwordx4 v[156:159], v182, s[14:15] offset:1024
	global_load_dwordx4 v[152:155], v182, s[14:15] offset:2048
	global_load_dwordx4 v[148:151], v182, s[14:15] offset:3072
	v_mov_b32 v3, 0
	s_cmp_gt_u32 s20, 4
	v_sub_f32_e32 v36, v3, v180
	v_mov_b32_e32 v37, v36
	v_mov_b64_e32 v[38:39], v[36:37]
	v_mov_b64_e32 v[40:41], v[36:37]
	v_mov_b64_e32 v[42:43], v[36:37]
	v_mov_b64_e32 v[44:45], v[36:37]
	v_mov_b64_e32 v[46:47], v[36:37]
	v_mov_b64_e32 v[48:49], v[36:37]
	v_mov_b64_e32 v[50:51], v[36:37]
	s_cselect_b64 s[12:13], -1, 0
	s_cmp_lt_u32 s20, 5
	s_waitcnt vmcnt(23)
	v_mfma_f32_32x32x16_bf16 v[36:51], v[100:103], v[52:55], v[36:51]
	s_cselect_b32 s14, s17, 0x3800
	s_and_b32 s15, s14, 0x7000
	s_lshl_b32 s21, s15, 1
	s_add_u32 s15, s4, s21
	s_addc_u32 s22, s5, 0
	s_and_b32 s14, s14, 0x800
	s_lshl_b32 s23, s14, 1
	s_waitcnt vmcnt(22)
	v_mfma_f32_32x32x16_bf16 v[36:51], v[104:107], v[56:59], v[36:51]
	s_add_u32 s14, s15, s23
	s_addc_u32 s15, s22, 0
	s_waitcnt vmcnt(21)
	v_mfma_f32_32x32x16_bf16 v[36:51], v[108:111], v[60:63], v[36:51]
	s_waitcnt vmcnt(20)
	v_mfma_f32_32x32x16_bf16 v[36:51], v[112:115], v[64:67], v[36:51]
	global_load_dwordx4 v[100:103], v182, s[14:15]
	global_load_dwordx4 v[104:107], v182, s[14:15] offset:1024
	global_load_dwordx4 v[108:111], v182, s[14:15] offset:2048
	global_load_dwordx4 v[112:115], v182, s[14:15] offset:3072
	s_add_u32 s14, s6, s21
	s_addc_u32 s15, s7, 0
	s_add_u32 s14, s14, s23
	s_addc_u32 s15, s15, 0
	s_nop 3
	v_exp_f32_e32 v3, v36
	v_exp_f32_e32 v177, v37
	v_exp_f32_e32 v184, v38
	v_exp_f32_e32 v185, v39
	v_exp_f32_e32 v186, v40
	v_exp_f32_e32 v187, v41
	v_exp_f32_e32 v188, v42
	v_exp_f32_e32 v189, v43
	v_cvt_pk_bf16_f32 v36, v3, v177
	v_cvt_pk_bf16_f32 v37, v184, v185
	v_cvt_pk_bf16_f32 v38, v186, v187
	v_cvt_pk_bf16_f32 v39, v188, v189
	v_exp_f32_e32 v190, v44
	v_exp_f32_e32 v191, v45
	s_waitcnt vmcnt(23)
	v_mfma_f32_32x32x16_bf16 v[20:35], v[80:83], v[36:39], v[20:35]
	v_exp_f32_e32 v192, v46
	v_exp_f32_e32 v193, v47
	v_exp_f32_e32 v194, v48
	v_exp_f32_e32 v195, v49
	v_exp_f32_e32 v196, v50
	v_exp_f32_e32 v197, v51
	v_add_f32_e32 v3, v183, v3
	s_waitcnt vmcnt(22)
	v_mfma_f32_32x32x16_bf16 v[4:19], v[76:79], v[36:39], v[4:19]
	v_cvt_pk_bf16_f32 v36, v190, v191
	v_cvt_pk_bf16_f32 v37, v192, v193
	v_cvt_pk_bf16_f32 v38, v194, v195
	v_cvt_pk_bf16_f32 v39, v196, v197
	v_add_f32_e32 v3, v177, v3
	v_add_f32_e32 v3, v184, v3
	v_add_f32_e32 v3, v185, v3
	s_waitcnt vmcnt(21)
	v_mfma_f32_32x32x16_bf16 v[20:35], v[72:75], v[36:39], v[20:35]
	v_add_f32_e32 v3, v186, v3
	v_add_f32_e32 v3, v187, v3
	v_add_f32_e32 v3, v188, v3
	v_add_f32_e32 v3, v189, v3
	v_add_f32_e32 v3, v190, v3
	v_add_f32_e32 v3, v191, v3
	v_add_f32_e32 v3, v192, v3
	s_waitcnt vmcnt(20)
	v_mfma_f32_32x32x16_bf16 v[4:19], v[68:71], v[36:39], v[4:19]
	global_load_dwordx4 v[80:83], v182, s[14:15]
	global_load_dwordx4 v[76:79], v182, s[14:15] offset:1024
	global_load_dwordx4 v[72:75], v182, s[14:15] offset:2048
	global_load_dwordx4 v[68:71], v182, s[14:15] offset:3072
	v_mov_b32 v36, 0
	s_min_u32 s14, s20, 3
	v_sub_f32_e32 v36, v36, v180
	v_mov_b32_e32 v37, v36
	v_mov_b64_e32 v[38:39], v[36:37]
	v_mov_b64_e32 v[40:41], v[36:37]
	v_mov_b64_e32 v[42:43], v[36:37]
	v_mov_b64_e32 v[44:45], v[36:37]
	v_mov_b64_e32 v[46:47], v[36:37]
	v_mov_b64_e32 v[48:49], v[36:37]
	v_mov_b64_e32 v[50:51], v[36:37]
	s_lshl_b32 s14, s14, 12
	s_and_b32 s15, s14, 0x2000
	s_waitcnt vmcnt(23)
	v_mfma_f32_32x32x16_bf16 v[36:51], v[116:119], v[52:55], v[36:51]
	s_or_b32 s21, s15, 0x4000
	s_add_u32 s15, s4, s21
	s_addc_u32 s22, s5, 0
	s_and_b32 s23, s14, 0x1000
	s_add_u32 s14, s15, s23
	s_addc_u32 s15, s22, 0
	v_add_f32_e32 v3, v193, v3
	s_waitcnt vmcnt(22)
	v_mfma_f32_32x32x16_bf16 v[36:51], v[120:123], v[56:59], v[36:51]
	v_add_f32_e32 v3, v194, v3
	v_add_f32_e32 v3, v195, v3
	v_add_f32_e32 v3, v196, v3
	v_add_f32_e32 v3, v197, v3
	s_waitcnt vmcnt(21)
	v_mfma_f32_32x32x16_bf16 v[36:51], v[124:127], v[60:63], v[36:51]
	s_waitcnt vmcnt(20)
	v_mfma_f32_32x32x16_bf16 v[36:51], v[128:131], v[64:67], v[36:51]
	global_load_dwordx4 v[116:119], v182, s[14:15]
	global_load_dwordx4 v[120:123], v182, s[14:15] offset:1024
	global_load_dwordx4 v[124:127], v182, s[14:15] offset:2048
	global_load_dwordx4 v[128:131], v182, s[14:15] offset:3072
	s_add_u32 s14, s6, s21
	s_addc_u32 s15, s7, 0
	s_add_u32 s14, s14, s23
	s_addc_u32 s15, s15, 0
	s_cmp_gt_u32 s20, 5
	s_nop 2
	v_exp_f32_e32 v200, v36
	v_exp_f32_e32 v201, v37
	v_exp_f32_e32 v202, v38
	v_exp_f32_e32 v203, v39
	v_exp_f32_e32 v40, v40
	v_exp_f32_e32 v41, v41
	v_exp_f32_e32 v42, v42
	v_exp_f32_e32 v43, v43
	v_cvt_pk_bf16_f32 v36, v200, v201
	v_cvt_pk_bf16_f32 v37, v202, v203
	v_cvt_pk_bf16_f32 v38, v40, v41
	v_cvt_pk_bf16_f32 v39, v42, v43
	v_exp_f32_e32 v44, v44
	v_exp_f32_e32 v45, v45
	s_waitcnt vmcnt(23)
	v_mfma_f32_32x32x16_bf16 v[20:35], v[96:99], v[36:39], v[20:35]
	v_exp_f32_e32 v46, v46
	v_exp_f32_e32 v47, v47
	v_exp_f32_e32 v48, v48
	v_exp_f32_e32 v49, v49
	v_exp_f32_e32 v50, v50
	v_exp_f32_e32 v51, v51
	v_add_f32_e32 v3, v3, v200
	s_waitcnt vmcnt(22)
	v_mfma_f32_32x32x16_bf16 v[4:19], v[92:95], v[36:39], v[4:19]
	v_cvt_pk_bf16_f32 v36, v44, v45
	v_cvt_pk_bf16_f32 v37, v46, v47
	v_cvt_pk_bf16_f32 v38, v48, v49
	v_cvt_pk_bf16_f32 v39, v50, v51
	v_add_f32_e32 v3, v201, v3
	v_add_f32_e32 v3, v202, v3
	v_add_f32_e32 v3, v203, v3
	s_waitcnt vmcnt(21)
	v_mfma_f32_32x32x16_bf16 v[20:35], v[88:91], v[36:39], v[20:35]
	v_add_f32_e32 v3, v40, v3
	v_add_f32_e32 v3, v41, v3
	v_add_f32_e32 v3, v42, v3
	v_add_f32_e32 v3, v43, v3
	v_add_f32_e32 v3, v44, v3
	v_add_f32_e32 v3, v45, v3
	v_add_f32_e32 v3, v46, v3
	s_waitcnt vmcnt(20)
	v_mfma_f32_32x32x16_bf16 v[4:19], v[84:87], v[36:39], v[4:19]
	global_load_dwordx4 v[96:99], v182, s[14:15]
	global_load_dwordx4 v[92:95], v182, s[14:15] offset:1024
	global_load_dwordx4 v[88:91], v182, s[14:15] offset:2048
	global_load_dwordx4 v[84:87], v182, s[14:15] offset:3072
	v_add_f32_e32 v3, v47, v3
	v_add_f32_e32 v3, v48, v3
	v_add_f32_e32 v3, v49, v3
	v_add_f32_e32 v3, v50, v3
	v_add_f32_e32 v183, v51, v3
	s_cbranch_scc1 .LBB0_939
	v_mov_b32 v3, 0
	s_nop 0
	v_sub_f32_e32 v36, v3, v180
	v_mov_b32_e32 v37, v36
	v_mov_b64_e32 v[38:39], v[36:37]
	v_mov_b64_e32 v[40:41], v[36:37]
	v_mov_b64_e32 v[42:43], v[36:37]
	v_mov_b64_e32 v[44:45], v[36:37]
	v_mov_b64_e32 v[46:47], v[36:37]
	v_mov_b64_e32 v[48:49], v[36:37]
	v_mov_b64_e32 v[50:51], v[36:37]
	s_waitcnt vmcnt(19)
	s_nop 0
	v_mfma_f32_32x32x16_bf16 v[36:51], v[160:163], v[52:55], v[36:51]
	s_waitcnt vmcnt(18)
	v_mfma_f32_32x32x16_bf16 v[36:51], v[156:159], v[56:59], v[36:51]
	s_waitcnt vmcnt(17)
	v_mfma_f32_32x32x16_bf16 v[36:51], v[152:155], v[60:63], v[36:51]
	s_waitcnt vmcnt(16)
	v_mfma_f32_32x32x16_bf16 v[36:51], v[148:151], v[64:67], v[36:51]
	s_nop 11
	v_exp_f32_e32 v3, v36
	v_exp_f32_e32 v148, v37
	v_exp_f32_e32 v149, v38
	v_exp_f32_e32 v150, v39
	v_exp_f32_e32 v40, v40
	v_exp_f32_e32 v41, v41
	v_exp_f32_e32 v42, v42
	v_exp_f32_e32 v43, v43
	v_add_f32_e32 v151, v183, v3
	v_cvt_pk_bf16_f32 v36, v3, v148
	v_add_f32_e32 v3, v148, v151
	v_cvt_pk_bf16_f32 v37, v149, v150
	v_cvt_pk_bf16_f32 v38, v40, v41
	v_cvt_pk_bf16_f32 v39, v42, v43
	v_add_f32_e32 v3, v149, v3
	v_add_f32_e32 v3, v150, v3
	v_mfma_f32_32x32x16_bf16 v[20:35], v[144:147], v[36:39], v[20:35]
	v_add_f32_e32 v3, v40, v3
	v_add_f32_e32 v3, v41, v3
	v_exp_f32_e32 v44, v44
	v_exp_f32_e32 v45, v45
	v_exp_f32_e32 v46, v46
	v_exp_f32_e32 v47, v47
	v_exp_f32_e32 v48, v48
	v_mfma_f32_32x32x16_bf16 v[4:19], v[140:143], v[36:39], v[4:19]
	v_add_f32_e32 v3, v42, v3
	v_exp_f32_e32 v40, v49
	v_exp_f32_e32 v41, v50
	v_exp_f32_e32 v42, v51
	v_add_f32_e32 v3, v43, v3
	v_cvt_pk_bf16_f32 v36, v44, v45
	v_cvt_pk_bf16_f32 v37, v46, v47
	v_cvt_pk_bf16_f32 v38, v48, v40
	v_cvt_pk_bf16_f32 v39, v41, v42
	v_add_f32_e32 v3, v44, v3
	v_add_f32_e32 v3, v45, v3
	v_mfma_f32_32x32x16_bf16 v[20:35], v[136:139], v[36:39], v[20:35]
	v_add_f32_e32 v3, v46, v3
	v_add_f32_e32 v3, v47, v3
	v_add_f32_e32 v3, v48, v3
	v_add_f32_e32 v3, v40, v3
	v_add_f32_e32 v3, v41, v3
	v_add_f32_e32 v183, v42, v3
	v_mfma_f32_32x32x16_bf16 v[4:19], v[132:135], v[36:39], v[4:19]

.Lq_wd_k0p0:
	v_bfe_u32 v28, s57, v18, 6
	v_lshl_add_u32 v218, s99, 6, v28
	v_mad_u32_u24 v21, v28, s82, v19
	v_mad_u32_u24 v32, v28, s82, v31
	v_and_b32_e32 v29, s18, v23
	v_cmp_ne_u32_e64 s[54:55], 0, v29
	s_and_b64 s[54:55], s[54:55], s[94:95]
	s_min_u32 s14, s85, 63
	s_nop 3
	v_readlane_b32 s30, v26, s14
	v_readlane_b32 s31, v27, s14
	s_nop 1
	v_bfe_u32 v28, s31, v18, 6
	v_lshl_add_u32 v29, s99, 6, v28
	v_mad_u32_u24 v29, v29, s47, v20
	global_load_dwordx4 v[238:241], v29, s[20:21]
	global_load_dwordx4 v[242:245], v29, s[20:21] offset:32
	global_load_dwordx4 v[246:249], v29, s[20:21] offset:64
	global_load_dwordx4 v[250:253], v29, s[20:21] offset:96
	s_lshl_b32 s0, s100, 6
	v_or_b32_e32 v237, s0, v206
	v_mov_b32_e32 v221, 0
	s_cmp_lg_u32 s100, s99
	s_cbranch_scc1 .Lq_s0n_k0p0
	v_and_b32_e32 v82, s18, v23
	v_cmp_ne_u32_e32 vcc, 0, v82
	s_and_b64 vcc, s[94:95], vcc
	v_mov_b32 v83, 0
	v_or_b32_e32 v16, 2, v237
	v_cndmask_b32_e32 v82, v236, v222, vcc
	v_sub_f32_e32 v82, v83, v82
	v_mov_b32_e32 v83, v82
	v_mov_b64_e32 v[84:85], v[82:83]
	v_mov_b64_e32 v[86:87], v[82:83]
	v_mov_b64_e32 v[88:89], v[82:83]
	v_mov_b64_e32 v[90:91], v[82:83]
	v_mov_b64_e32 v[92:93], v[82:83]
	v_mov_b64_e32 v[94:95], v[82:83]
	v_mov_b64_e32 v[96:97], v[82:83]
	v_cmp_le_i32_e32 vcc, v237, v218
	v_or_b32_e32 v17, 3, v237
	v_mfma_f32_32x32x16_bf16 v[82:97], v[178:181], v[4:7], v[82:97]
	v_or_b32_e32 v30, 8, v237
	v_mfma_f32_32x32x16_bf16 v[82:97], v[174:177], v[8:11], v[82:97]
	v_mfma_f32_32x32x16_bf16 v[82:97], v[170:173], v[12:15], v[82:97]
	v_mfma_f32_32x32x16_bf16 v[82:97], v[166:169], v[98:101], v[82:97]
	s_nop 11
	v_exp_f32_e32 v82, v82
	v_exp_f32_e32 v83, v83
	v_exp_f32_e32 v84, v84
	v_exp_f32_e32 v85, v85
	v_exp_f32_e32 v86, v86
	v_cndmask_b32_e32 v82, 0, v82, vcc
	v_cmp_lt_i32_e32 vcc, v237, v218
	v_exp_f32_e32 v87, v87
	v_exp_f32_e32 v88, v88
	v_cndmask_b32_e32 v83, 0, v83, vcc
	v_cmp_le_i32_e32 vcc, v16, v218
	v_or_b32_e32 v16, 9, v237
	v_exp_f32_e32 v89, v89
	v_cndmask_b32_e32 v84, 0, v84, vcc
	v_cmp_le_i32_e32 vcc, v17, v218
	v_exp_f32_e32 v90, v90
	v_exp_f32_e32 v91, v91
	v_cndmask_b32_e32 v85, 0, v85, vcc
	v_cmp_le_i32_e32 vcc, v30, v218
	v_add_f32_e32 v221, v221, v82
	v_exp_f32_e32 v92, v92
	v_cndmask_b32_e32 v86, 0, v86, vcc
	v_cmp_le_i32_e32 vcc, v16, v218
	v_or_b32_e32 v16, 10, v237
	v_add_f32_e32 v221, v83, v221
	v_cndmask_b32_e32 v87, 0, v87, vcc
	v_cmp_le_i32_e32 vcc, v16, v218
	v_or_b32_e32 v16, 11, v237
	v_exp_f32_e32 v93, v93
	v_cndmask_b32_e32 v88, 0, v88, vcc
	v_cmp_le_i32_e32 vcc, v16, v218
	v_or_b32_e32 v16, 16, v237
	v_add_f32_e32 v221, v84, v221
	v_cndmask_b32_e32 v89, 0, v89, vcc
	v_cmp_le_i32_e32 vcc, v16, v218
	v_or_b32_e32 v16, 17, v237
	v_exp_f32_e32 v94, v94
	v_cndmask_b32_e32 v90, 0, v90, vcc
	v_cmp_le_i32_e32 vcc, v16, v218
	v_or_b32_e32 v16, 18, v237
	v_add_f32_e32 v221, v85, v221
	v_cndmask_b32_e32 v91, 0, v91, vcc
	v_cmp_le_i32_e32 vcc, v16, v218
	v_or_b32_e32 v16, 19, v237
	v_exp_f32_e32 v95, v95
	v_add_f32_e32 v221, v86, v221
	v_cndmask_b32_e32 v92, 0, v92, vcc
	v_cmp_le_i32_e32 vcc, v16, v218
	v_or_b32_e32 v16, 24, v237
	v_cvt_pk_bf16_f32 v82, v82, v83
	v_cvt_pk_bf16_f32 v83, v84, v85
	v_cvt_pk_bf16_f32 v84, v86, v87
	v_cvt_pk_bf16_f32 v85, v88, v89
	v_add_f32_e32 v221, v87, v221
	v_cndmask_b32_e32 v93, 0, v93, vcc
	v_cmp_le_i32_e32 vcc, v16, v218
	v_or_b32_e32 v16, 25, v237
	v_mfma_f32_32x32x16_bf16 v[66:81], v[146:149], v[82:85], 0
	v_add_f32_e32 v221, v88, v221
	v_cndmask_b32_e32 v94, 0, v94, vcc
	v_exp_f32_e32 v86, v96
	v_cmp_le_i32_e32 vcc, v16, v218
	v_or_b32_e32 v88, 26, v237
	v_add_f32_e32 v221, v89, v221
	v_cndmask_b32_e32 v87, 0, v95, vcc
	v_mfma_f32_32x32x16_bf16 v[50:65], v[142:145], v[82:85], 0
	v_cmp_le_i32_e32 vcc, v88, v218
	v_exp_f32_e32 v88, v97
	v_or_b32_e32 v82, 27, v237
	v_cndmask_b32_e32 v86, 0, v86, vcc
	v_cmp_le_i32_e32 vcc, v82, v218
	v_cvt_pk_bf16_f32 v82, v90, v91
	v_cvt_pk_bf16_f32 v83, v92, v93
	v_cndmask_b32_e32 v88, 0, v88, vcc
	v_cvt_pk_bf16_f32 v84, v94, v87
	v_cvt_pk_bf16_f32 v85, v86, v88
	v_add_f32_e32 v221, v90, v221
	v_add_f32_e32 v89, v91, v221
	v_mfma_f32_32x32x16_bf16 v[66:81], v[126:129], v[82:85], v[66:81]
	v_add_f32_e32 v89, v92, v89
	v_add_f32_e32 v89, v93, v89
	v_add_f32_e32 v89, v94, v89
	v_add_f32_e32 v87, v87, v89
	v_add_f32_e32 v86, v86, v87
	v_add_f32_e32 v221, v88, v86
	v_mfma_f32_32x32x16_bf16 v[50:65], v[114:117], v[82:85], v[50:65]
	s_cmp_lg_u32 s85, s86
	s_cbranch_scc1 .Lq_nl0_k0p0
	s_min_u32 s14, s87, 63
	s_nop 3
	v_readlane_b32 s30, v33, s14
	s_and_b32 s30, s30, 0xff
	s_lshl_b32 s30, s30, 13
	s_or_b32 s30, s30, 0x1000
	s_add_u32 s64, s11, s30
	s_addc_u32 s65, s12, 0
	s_add_u32 s66, s8, s30
	s_addc_u32 s67, s9, 0
	global_load_dwordx4 v[178:181], v2, s[64:65]
	global_load_dwordx4 v[174:177], v2, s[64:65] offset:1024
	global_load_dwordx4 v[170:173], v2, s[64:65] offset:2048
	global_load_dwordx4 v[166:169], v2, s[64:65] offset:3072
	global_load_dwordx4 v[146:149], v2, s[66:67]
	global_load_dwordx4 v[142:145], v2, s[66:67] offset:1024
	global_load_dwordx4 v[126:129], v2, s[66:67] offset:2048
	global_load_dwordx4 v[114:117], v2, s[66:67] offset:3072
	s_waitcnt vmcnt(20)
	s_branch .Lq_nl0d_k0p0

.Lq_nl0d_k0p0:
	s_lshl_b32 s0, s100, 6
	s_or_b32 s0, s0, 32
	v_or_b32_e32 v237, s0, v206
	v_and_b32_e32 v82, s18, v23
	v_cmp_ne_u32_e32 vcc, 0, v82
	s_and_b64 vcc, s[94:95], vcc
	v_mov_b32 v83, 0
	v_or_b32_e32 v16, 2, v237
	v_cndmask_b32_e32 v82, v236, v222, vcc
	v_sub_f32_e32 v82, v83, v82
	v_mov_b32_e32 v83, v82
	v_mov_b64_e32 v[84:85], v[82:83]
	v_mov_b64_e32 v[86:87], v[82:83]
	v_mov_b64_e32 v[88:89], v[82:83]
	v_mov_b64_e32 v[90:91], v[82:83]
	v_mov_b64_e32 v[92:93], v[82:83]
	v_mov_b64_e32 v[94:95], v[82:83]
	v_mov_b64_e32 v[96:97], v[82:83]
	v_cmp_le_i32_e32 vcc, v237, v218
	v_or_b32_e32 v17, 3, v237
	v_mfma_f32_32x32x16_bf16 v[82:97], v[162:165], v[4:7], v[82:97]
	v_or_b32_e32 v30, 8, v237
	v_mfma_f32_32x32x16_bf16 v[82:97], v[154:157], v[8:11], v[82:97]
	v_mfma_f32_32x32x16_bf16 v[82:97], v[150:153], v[12:15], v[82:97]
	v_mfma_f32_32x32x16_bf16 v[82:97], v[158:161], v[98:101], v[82:97]
	s_nop 11
	v_exp_f32_e32 v82, v82
	v_exp_f32_e32 v83, v83
	v_exp_f32_e32 v84, v84
	v_exp_f32_e32 v85, v85
	v_exp_f32_e32 v86, v86
	v_cndmask_b32_e32 v82, 0, v82, vcc
	v_cmp_lt_i32_e32 vcc, v237, v218
	v_exp_f32_e32 v87, v87
	v_exp_f32_e32 v88, v88
	v_cndmask_b32_e32 v83, 0, v83, vcc
	v_cmp_le_i32_e32 vcc, v16, v218
	v_or_b32_e32 v16, 9, v237
	v_exp_f32_e32 v89, v89
	v_cndmask_b32_e32 v84, 0, v84, vcc
	v_cmp_le_i32_e32 vcc, v17, v218
	v_exp_f32_e32 v90, v90
	v_exp_f32_e32 v91, v91
	v_cndmask_b32_e32 v85, 0, v85, vcc
	v_cmp_le_i32_e32 vcc, v30, v218
	v_add_f32_e32 v221, v221, v82
	v_exp_f32_e32 v92, v92
	v_cndmask_b32_e32 v86, 0, v86, vcc
	v_cmp_le_i32_e32 vcc, v16, v218
	v_or_b32_e32 v16, 10, v237
	v_add_f32_e32 v221, v83, v221
	v_cndmask_b32_e32 v87, 0, v87, vcc
	v_cmp_le_i32_e32 vcc, v16, v218
	v_or_b32_e32 v16, 11, v237
	v_exp_f32_e32 v93, v93
	v_cndmask_b32_e32 v88, 0, v88, vcc
	v_cmp_le_i32_e32 vcc, v16, v218
	v_or_b32_e32 v16, 16, v237
	v_add_f32_e32 v221, v84, v221
	v_cndmask_b32_e32 v89, 0, v89, vcc
	v_cmp_le_i32_e32 vcc, v16, v218
	v_or_b32_e32 v16, 17, v237
	v_exp_f32_e32 v94, v94
	v_cndmask_b32_e32 v90, 0, v90, vcc
	v_cmp_le_i32_e32 vcc, v16, v218
	v_or_b32_e32 v16, 18, v237
	v_add_f32_e32 v221, v85, v221
	v_cndmask_b32_e32 v91, 0, v91, vcc
	v_cmp_le_i32_e32 vcc, v16, v218
	v_or_b32_e32 v16, 19, v237
	v_exp_f32_e32 v95, v95
	v_add_f32_e32 v221, v86, v221
	v_cndmask_b32_e32 v92, 0, v92, vcc
	v_cmp_le_i32_e32 vcc, v16, v218
	v_or_b32_e32 v16, 24, v237
	v_cvt_pk_bf16_f32 v82, v82, v83
	v_cvt_pk_bf16_f32 v83, v84, v85
	v_cvt_pk_bf16_f32 v84, v86, v87
	v_cvt_pk_bf16_f32 v85, v88, v89
	v_add_f32_e32 v221, v87, v221
	v_cndmask_b32_e32 v93, 0, v93, vcc
	v_cmp_le_i32_e32 vcc, v16, v218
	v_or_b32_e32 v16, 25, v237
	v_mfma_f32_32x32x16_bf16 v[66:81], v[138:141], v[82:85], v[66:81]
	v_add_f32_e32 v221, v88, v221
	v_cndmask_b32_e32 v94, 0, v94, vcc
	v_exp_f32_e32 v86, v96
	v_cmp_le_i32_e32 vcc, v16, v218
	v_or_b32_e32 v88, 26, v237
	v_add_f32_e32 v221, v89, v221
	v_cndmask_b32_e32 v87, 0, v95, vcc
	v_mfma_f32_32x32x16_bf16 v[50:65], v[122:125], v[82:85], v[50:65]
	v_cmp_le_i32_e32 vcc, v88, v218
	v_exp_f32_e32 v88, v97
	v_or_b32_e32 v82, 27, v237
	v_cndmask_b32_e32 v86, 0, v86, vcc
	v_cmp_le_i32_e32 vcc, v82, v218
	v_cvt_pk_bf16_f32 v82, v90, v91
	v_cvt_pk_bf16_f32 v83, v92, v93
	v_cndmask_b32_e32 v88, 0, v88, vcc
	v_cvt_pk_bf16_f32 v84, v94, v87
	v_cvt_pk_bf16_f32 v85, v86, v88
	v_add_f32_e32 v221, v90, v221
	v_add_f32_e32 v89, v91, v221
	v_mfma_f32_32x32x16_bf16 v[66:81], v[110:113], v[82:85], v[66:81]
	v_add_f32_e32 v89, v92, v89
	v_add_f32_e32 v89, v93, v89
	v_add_f32_e32 v89, v94, v89
	v_add_f32_e32 v87, v87, v89
	v_add_f32_e32 v86, v86, v87
	v_add_f32_e32 v221, v88, v86
	v_mfma_f32_32x32x16_bf16 v[50:65], v[106:109], v[82:85], v[50:65]
	s_cmp_lg_u32 s85, s86
	s_cbranch_scc1 .Lq_nl1_k0p0
	s_min_u32 s14, s88, 63
	s_nop 3
	v_readlane_b32 s30, v33, s14
	s_and_b32 s30, s30, 0xff
	s_lshl_b32 s30, s30, 13
	s_add_u32 s64, s11, s30
	s_addc_u32 s65, s12, 0
	s_add_u32 s66, s8, s30
	s_addc_u32 s67, s9, 0
	global_load_dwordx4 v[162:165], v2, s[64:65]
	global_load_dwordx4 v[154:157], v2, s[64:65] offset:1024
	global_load_dwordx4 v[150:153], v2, s[64:65] offset:2048
	global_load_dwordx4 v[158:161], v2, s[64:65] offset:3072
	global_load_dwordx4 v[138:141], v2, s[66:67]
	global_load_dwordx4 v[122:125], v2, s[66:67] offset:1024
	global_load_dwordx4 v[110:113], v2, s[66:67] offset:2048
	global_load_dwordx4 v[106:109], v2, s[66:67] offset:3072
	s_branch .Lq_nl1_k0p0
.Lq_s0n_k0p0:
	v_and_b32_e32 v82, s18, v23
	v_cmp_ne_u32_e32 vcc, 0, v82
	s_and_b64 vcc, s[94:95], vcc
	v_mov_b32 v83, 0
	v_cndmask_b32_e32 v82, v236, v222, vcc
	v_sub_f32_e32 v82, v83, v82
	v_mov_b32_e32 v83, v82
	v_mov_b64_e32 v[84:85], v[82:83]
	v_mov_b64_e32 v[86:87], v[82:83]
	v_mov_b64_e32 v[88:89], v[82:83]
	v_mov_b64_e32 v[90:91], v[82:83]
	v_mov_b64_e32 v[92:93], v[82:83]
	v_mov_b64_e32 v[94:95], v[82:83]
	v_mov_b64_e32 v[96:97], v[82:83]
	s_nop 1
	v_mfma_f32_32x32x16_bf16 v[82:97], v[178:181], v[4:7], v[82:97]
	v_mfma_f32_32x32x16_bf16 v[82:97], v[174:177], v[8:11], v[82:97]
	v_mfma_f32_32x32x16_bf16 v[82:97], v[170:173], v[12:15], v[82:97]
	v_mfma_f32_32x32x16_bf16 v[82:97], v[166:169], v[98:101], v[82:97]
	s_waitcnt vmcnt(12)
	v_mov_b32_e32 v28, 0
	v_and_b32_e32 v34, s18, v23
	v_cmp_ne_u32_e32 vcc, 0, v34
	s_and_b64 vcc, s[94:95], vcc
	v_mov_b32 v35, 0
	v_cndmask_b32_e32 v34, v236, v222, vcc
	v_sub_f32_e32 v34, v35, v34
	v_mov_b32_e32 v35, v34
	v_mov_b64_e32 v[36:37], v[34:35]
	v_mov_b64_e32 v[38:39], v[34:35]
	v_mov_b64_e32 v[40:41], v[34:35]
	v_mov_b64_e32 v[42:43], v[34:35]
	v_mov_b64_e32 v[44:45], v[34:35]
	v_mov_b64_e32 v[46:47], v[34:35]
	v_mov_b64_e32 v[48:49], v[34:35]
	s_nop 1
	v_mfma_f32_32x32x16_bf16 v[34:49], v[162:165], v[4:7], v[34:49]
	v_mfma_f32_32x32x16_bf16 v[34:49], v[154:157], v[8:11], v[34:49]
	v_mfma_f32_32x32x16_bf16 v[34:49], v[150:153], v[12:15], v[34:49]
	v_mfma_f32_32x32x16_bf16 v[34:49], v[158:161], v[98:101], v[34:49]
	v_exp_f32_e32 v82, v82
	v_exp_f32_e32 v83, v83
	v_exp_f32_e32 v84, v84
	v_exp_f32_e32 v85, v85
	v_exp_f32_e32 v86, v86
	v_exp_f32_e32 v87, v87
	v_exp_f32_e32 v88, v88
	v_exp_f32_e32 v89, v89
	v_exp_f32_e32 v90, v90
	v_exp_f32_e32 v91, v91
	v_add_f32_e32 v221, v221, v82
	v_exp_f32_e32 v92, v92
	v_exp_f32_e32 v34, v34
	v_add_f32_e32 v221, v83, v221
	v_exp_f32_e32 v35, v35
	v_exp_f32_e32 v93, v93
	v_exp_f32_e32 v36, v36
	v_add_f32_e32 v221, v84, v221
	v_exp_f32_e32 v37, v37
	v_exp_f32_e32 v94, v94
	v_exp_f32_e32 v38, v38
	v_add_f32_e32 v221, v85, v221
	v_exp_f32_e32 v39, v39
	v_exp_f32_e32 v95, v95
	v_exp_f32_e32 v40, v40
	v_add_f32_e32 v221, v86, v221
	v_exp_f32_e32 v41, v41
	v_cvt_pk_bf16_f32 v82, v82, v83
	v_exp_f32_e32 v42, v42
	v_cvt_pk_bf16_f32 v83, v84, v85
	v_exp_f32_e32 v43, v43
	v_cvt_pk_bf16_f32 v84, v86, v87
	v_add_f32_e32 v28, v28, v34
	v_cvt_pk_bf16_f32 v85, v88, v89
	v_exp_f32_e32 v44, v44
	v_add_f32_e32 v221, v87, v221
	v_add_f32_e32 v28, v35, v28
	v_mfma_f32_32x32x16_bf16 v[66:81], v[146:149], v[82:85], 0
	v_exp_f32_e32 v45, v45
	v_add_f32_e32 v221, v88, v221
	v_add_f32_e32 v28, v36, v28
	v_exp_f32_e32 v86, v96
	v_exp_f32_e32 v46, v46
	v_add_f32_e32 v221, v89, v221
	v_add_f32_e32 v28, v37, v28
	v_mov_b32_e32 v87, v95
	v_exp_f32_e32 v47, v47
	v_mfma_f32_32x32x16_bf16 v[50:65], v[142:145], v[82:85], 0
	v_add_f32_e32 v28, v38, v28
	v_exp_f32_e32 v88, v97
	v_cvt_pk_bf16_f32 v34, v34, v35
	v_cvt_pk_bf16_f32 v82, v90, v91
	v_cvt_pk_bf16_f32 v35, v36, v37
	v_cvt_pk_bf16_f32 v83, v92, v93
	v_cvt_pk_bf16_f32 v36, v38, v39
	v_cvt_pk_bf16_f32 v84, v94, v87
	v_cvt_pk_bf16_f32 v37, v40, v41
	v_cvt_pk_bf16_f32 v85, v86, v88
	v_add_f32_e32 v28, v39, v28
	v_add_f32_e32 v221, v90, v221
	v_mfma_f32_32x32x16_bf16 v[66:81], v[138:141], v[34:37], v[66:81]
	v_add_f32_e32 v89, v91, v221
	v_add_f32_e32 v28, v40, v28
	v_mfma_f32_32x32x16_bf16 v[66:81], v[126:129], v[82:85], v[66:81]
	v_exp_f32_e32 v38, v48
	v_add_f32_e32 v89, v92, v89
	v_add_f32_e32 v28, v41, v28
	v_add_f32_e32 v89, v93, v89
	v_mov_b32_e32 v39, v47
	v_add_f32_e32 v89, v94, v89
	v_mfma_f32_32x32x16_bf16 v[50:65], v[122:125], v[34:37], v[50:65]
	v_add_f32_e32 v87, v87, v89
	v_exp_f32_e32 v40, v49
	v_add_f32_e32 v86, v86, v87
	v_cvt_pk_bf16_f32 v34, v42, v43
	v_add_f32_e32 v221, v88, v86
	v_cvt_pk_bf16_f32 v35, v44, v45
	v_mfma_f32_32x32x16_bf16 v[50:65], v[114:117], v[82:85], v[50:65]
	v_cvt_pk_bf16_f32 v36, v46, v39
	v_cvt_pk_bf16_f32 v37, v38, v40
	v_add_f32_e32 v28, v42, v28
	v_add_f32_e32 v41, v43, v28
	v_mfma_f32_32x32x16_bf16 v[66:81], v[110:113], v[34:37], v[66:81]
	v_add_f32_e32 v41, v44, v41
	v_add_f32_e32 v41, v45, v41
	v_add_f32_e32 v41, v46, v41
	v_add_f32_e32 v39, v39, v41
	v_add_f32_e32 v38, v38, v39
	v_add_f32_e32 v28, v40, v38
	v_mfma_f32_32x32x16_bf16 v[50:65], v[106:109], v[34:37], v[50:65]
	v_add_f32_e32 v221, v221, v28
	s_cmp_lg_u32 s85, s86
	s_cbranch_scc1 .Lq_nl1_k0p0
	s_min_u32 s14, s87, 63
	s_nop 3
	v_readlane_b32 s30, v33, s14
	s_and_b32 s30, s30, 0xff
	s_lshl_b32 s30, s30, 13
	s_or_b32 s30, s30, 0x1000
	s_add_u32 s64, s11, s30
	s_addc_u32 s65, s12, 0
	s_add_u32 s66, s8, s30
	s_addc_u32 s67, s9, 0
	global_load_dwordx4 v[178:181], v2, s[64:65]
	global_load_dwordx4 v[174:177], v2, s[64:65] offset:1024
	global_load_dwordx4 v[170:173], v2, s[64:65] offset:2048
	global_load_dwordx4 v[166:169], v2, s[64:65] offset:3072
	global_load_dwordx4 v[146:149], v2, s[66:67]
	global_load_dwordx4 v[142:145], v2, s[66:67] offset:1024
	global_load_dwordx4 v[126:129], v2, s[66:67] offset:2048
	global_load_dwordx4 v[114:117], v2, s[66:67] offset:3072
	s_min_u32 s14, s88, 63
	s_nop 3
	v_readlane_b32 s30, v33, s14
	s_and_b32 s30, s30, 0xff
	s_lshl_b32 s30, s30, 13
	s_add_u32 s64, s11, s30
	s_addc_u32 s65, s12, 0
	s_add_u32 s66, s8, s30
	s_addc_u32 s67, s9, 0
	global_load_dwordx4 v[162:165], v2, s[64:65]
	global_load_dwordx4 v[154:157], v2, s[64:65] offset:1024
	global_load_dwordx4 v[150:153], v2, s[64:65] offset:2048
	global_load_dwordx4 v[158:161], v2, s[64:65] offset:3072
	global_load_dwordx4 v[138:141], v2, s[66:67]
	global_load_dwordx4 v[122:125], v2, s[66:67] offset:1024
	global_load_dwordx4 v[110:113], v2, s[66:67] offset:2048
	global_load_dwordx4 v[106:109], v2, s[66:67] offset:3072

.Lq_wd_k0p1:
	v_bfe_u32 v28, s57, v18, 6
	v_lshl_add_u32 v218, s99, 6, v28
	v_mad_u32_u24 v21, v28, s82, v19
	v_mad_u32_u24 v32, v28, s82, v31
	v_and_b32_e32 v29, s18, v23
	v_cmp_ne_u32_e64 s[54:55], 0, v29
	s_and_b64 s[54:55], s[54:55], s[94:95]
	s_min_u32 s14, s85, 63
	s_nop 3
	v_readlane_b32 s30, v26, s14
	v_readlane_b32 s31, v27, s14
	s_nop 1
	v_bfe_u32 v28, s31, v18, 6
	v_lshl_add_u32 v29, s99, 6, v28
	v_mad_u32_u24 v29, v29, s47, v20
	global_load_dwordx4 v[4:7], v29, s[20:21]
	global_load_dwordx4 v[8:11], v29, s[20:21] offset:32
	global_load_dwordx4 v[12:15], v29, s[20:21] offset:64
	global_load_dwordx4 v[98:101], v29, s[20:21] offset:96
	s_lshl_b32 s0, s100, 6
	v_or_b32_e32 v237, s0, v206
	v_mov_b32_e32 v221, 0
	s_cmp_lg_u32 s100, s99
	s_cbranch_scc1 .Lq_s0n_k0p1
	v_and_b32_e32 v82, s18, v23
	v_cmp_ne_u32_e32 vcc, 0, v82
	s_and_b64 vcc, s[94:95], vcc
	v_mov_b32 v83, 0
	v_or_b32_e32 v16, 2, v237
	v_cndmask_b32_e32 v82, v236, v222, vcc
	v_sub_f32_e32 v82, v83, v82
	v_mov_b32_e32 v83, v82
	v_mov_b64_e32 v[84:85], v[82:83]
	v_mov_b64_e32 v[86:87], v[82:83]
	v_mov_b64_e32 v[88:89], v[82:83]
	v_mov_b64_e32 v[90:91], v[82:83]
	v_mov_b64_e32 v[92:93], v[82:83]
	v_mov_b64_e32 v[94:95], v[82:83]
	v_mov_b64_e32 v[96:97], v[82:83]
	v_cmp_le_i32_e32 vcc, v237, v218
	v_or_b32_e32 v17, 3, v237
	v_mfma_f32_32x32x16_bf16 v[82:97], v[178:181], v[238:241], v[82:97]
	v_or_b32_e32 v30, 8, v237
	v_mfma_f32_32x32x16_bf16 v[82:97], v[174:177], v[242:245], v[82:97]
	v_mfma_f32_32x32x16_bf16 v[82:97], v[170:173], v[246:249], v[82:97]
	v_mfma_f32_32x32x16_bf16 v[82:97], v[166:169], v[250:253], v[82:97]
	s_nop 11
	v_exp_f32_e32 v82, v82
	v_exp_f32_e32 v83, v83
	v_exp_f32_e32 v84, v84
	v_exp_f32_e32 v85, v85
	v_exp_f32_e32 v86, v86
	v_cndmask_b32_e32 v82, 0, v82, vcc
	v_cmp_lt_i32_e32 vcc, v237, v218
	v_exp_f32_e32 v87, v87
	v_exp_f32_e32 v88, v88
	v_cndmask_b32_e32 v83, 0, v83, vcc
	v_cmp_le_i32_e32 vcc, v16, v218
	v_or_b32_e32 v16, 9, v237
	v_exp_f32_e32 v89, v89
	v_cndmask_b32_e32 v84, 0, v84, vcc
	v_cmp_le_i32_e32 vcc, v17, v218
	v_exp_f32_e32 v90, v90
	v_exp_f32_e32 v91, v91
	v_cndmask_b32_e32 v85, 0, v85, vcc
	v_cmp_le_i32_e32 vcc, v30, v218
	v_add_f32_e32 v221, v221, v82
	v_exp_f32_e32 v92, v92
	v_cndmask_b32_e32 v86, 0, v86, vcc
	v_cmp_le_i32_e32 vcc, v16, v218
	v_or_b32_e32 v16, 10, v237
	v_add_f32_e32 v221, v83, v221
	v_cndmask_b32_e32 v87, 0, v87, vcc
	v_cmp_le_i32_e32 vcc, v16, v218
	v_or_b32_e32 v16, 11, v237
	v_exp_f32_e32 v93, v93
	v_cndmask_b32_e32 v88, 0, v88, vcc
	v_cmp_le_i32_e32 vcc, v16, v218
	v_or_b32_e32 v16, 16, v237
	v_add_f32_e32 v221, v84, v221
	v_cndmask_b32_e32 v89, 0, v89, vcc
	v_cmp_le_i32_e32 vcc, v16, v218
	v_or_b32_e32 v16, 17, v237
	v_exp_f32_e32 v94, v94
	v_cndmask_b32_e32 v90, 0, v90, vcc
	v_cmp_le_i32_e32 vcc, v16, v218
	v_or_b32_e32 v16, 18, v237
	v_add_f32_e32 v221, v85, v221
	v_cndmask_b32_e32 v91, 0, v91, vcc
	v_cmp_le_i32_e32 vcc, v16, v218
	v_or_b32_e32 v16, 19, v237
	v_exp_f32_e32 v95, v95
	v_add_f32_e32 v221, v86, v221
	v_cndmask_b32_e32 v92, 0, v92, vcc
	v_cmp_le_i32_e32 vcc, v16, v218
	v_or_b32_e32 v16, 24, v237
	v_cvt_pk_bf16_f32 v82, v82, v83
	v_cvt_pk_bf16_f32 v83, v84, v85
	v_cvt_pk_bf16_f32 v84, v86, v87
	v_cvt_pk_bf16_f32 v85, v88, v89
	v_add_f32_e32 v221, v87, v221
	v_cndmask_b32_e32 v93, 0, v93, vcc
	v_cmp_le_i32_e32 vcc, v16, v218
	v_or_b32_e32 v16, 25, v237
	v_mfma_f32_32x32x16_bf16 v[66:81], v[146:149], v[82:85], 0
	v_add_f32_e32 v221, v88, v221
	v_cndmask_b32_e32 v94, 0, v94, vcc
	v_exp_f32_e32 v86, v96
	v_cmp_le_i32_e32 vcc, v16, v218
	v_or_b32_e32 v88, 26, v237
	v_add_f32_e32 v221, v89, v221
	v_cndmask_b32_e32 v87, 0, v95, vcc
	v_mfma_f32_32x32x16_bf16 v[50:65], v[142:145], v[82:85], 0
	v_cmp_le_i32_e32 vcc, v88, v218
	v_exp_f32_e32 v88, v97
	v_or_b32_e32 v82, 27, v237
	v_cndmask_b32_e32 v86, 0, v86, vcc
	v_cmp_le_i32_e32 vcc, v82, v218
	v_cvt_pk_bf16_f32 v82, v90, v91
	v_cvt_pk_bf16_f32 v83, v92, v93
	v_cndmask_b32_e32 v88, 0, v88, vcc
	v_cvt_pk_bf16_f32 v84, v94, v87
	v_cvt_pk_bf16_f32 v85, v86, v88
	v_add_f32_e32 v221, v90, v221
	v_add_f32_e32 v89, v91, v221
	v_mfma_f32_32x32x16_bf16 v[66:81], v[126:129], v[82:85], v[66:81]
	v_add_f32_e32 v89, v92, v89
	v_add_f32_e32 v89, v93, v89
	v_add_f32_e32 v89, v94, v89
	v_add_f32_e32 v87, v87, v89
	v_add_f32_e32 v86, v86, v87
	v_add_f32_e32 v221, v88, v86
	v_mfma_f32_32x32x16_bf16 v[50:65], v[114:117], v[82:85], v[50:65]
	s_cmp_lg_u32 s85, s86
	s_cbranch_scc1 .Lq_nl0_k0p1
	s_min_u32 s14, s87, 63
	s_nop 3
	v_readlane_b32 s30, v33, s14
	s_and_b32 s30, s30, 0xff
	s_lshl_b32 s30, s30, 13
	s_or_b32 s30, s30, 0x1000
	s_add_u32 s64, s11, s30
	s_addc_u32 s65, s12, 0
	s_add_u32 s66, s8, s30
	s_addc_u32 s67, s9, 0
	global_load_dwordx4 v[178:181], v2, s[64:65]
	global_load_dwordx4 v[174:177], v2, s[64:65] offset:1024
	global_load_dwordx4 v[170:173], v2, s[64:65] offset:2048
	global_load_dwordx4 v[166:169], v2, s[64:65] offset:3072
	global_load_dwordx4 v[146:149], v2, s[66:67]
	global_load_dwordx4 v[142:145], v2, s[66:67] offset:1024
	global_load_dwordx4 v[126:129], v2, s[66:67] offset:2048
	global_load_dwordx4 v[114:117], v2, s[66:67] offset:3072
	s_waitcnt vmcnt(20)
	s_branch .Lq_nl0d_k0p1

.Lq_nl0d_k0p1:
	s_lshl_b32 s0, s100, 6
	s_or_b32 s0, s0, 32
	v_or_b32_e32 v237, s0, v206
	v_and_b32_e32 v82, s18, v23
	v_cmp_ne_u32_e32 vcc, 0, v82
	s_and_b64 vcc, s[94:95], vcc
	v_mov_b32 v83, 0
	v_or_b32_e32 v16, 2, v237
	v_cndmask_b32_e32 v82, v236, v222, vcc
	v_sub_f32_e32 v82, v83, v82
	v_mov_b32_e32 v83, v82
	v_mov_b64_e32 v[84:85], v[82:83]
	v_mov_b64_e32 v[86:87], v[82:83]
	v_mov_b64_e32 v[88:89], v[82:83]
	v_mov_b64_e32 v[90:91], v[82:83]
	v_mov_b64_e32 v[92:93], v[82:83]
	v_mov_b64_e32 v[94:95], v[82:83]
	v_mov_b64_e32 v[96:97], v[82:83]
	v_cmp_le_i32_e32 vcc, v237, v218
	v_or_b32_e32 v17, 3, v237
	v_mfma_f32_32x32x16_bf16 v[82:97], v[162:165], v[238:241], v[82:97]
	v_or_b32_e32 v30, 8, v237
	v_mfma_f32_32x32x16_bf16 v[82:97], v[154:157], v[242:245], v[82:97]
	v_mfma_f32_32x32x16_bf16 v[82:97], v[150:153], v[246:249], v[82:97]
	v_mfma_f32_32x32x16_bf16 v[82:97], v[158:161], v[250:253], v[82:97]
	s_nop 11
	v_exp_f32_e32 v82, v82
	v_exp_f32_e32 v83, v83
	v_exp_f32_e32 v84, v84
	v_exp_f32_e32 v85, v85
	v_exp_f32_e32 v86, v86
	v_cndmask_b32_e32 v82, 0, v82, vcc
	v_cmp_lt_i32_e32 vcc, v237, v218
	v_exp_f32_e32 v87, v87
	v_exp_f32_e32 v88, v88
	v_cndmask_b32_e32 v83, 0, v83, vcc
	v_cmp_le_i32_e32 vcc, v16, v218
	v_or_b32_e32 v16, 9, v237
	v_exp_f32_e32 v89, v89
	v_cndmask_b32_e32 v84, 0, v84, vcc
	v_cmp_le_i32_e32 vcc, v17, v218
	v_exp_f32_e32 v90, v90
	v_exp_f32_e32 v91, v91
	v_cndmask_b32_e32 v85, 0, v85, vcc
	v_cmp_le_i32_e32 vcc, v30, v218
	v_add_f32_e32 v221, v221, v82
	v_exp_f32_e32 v92, v92
	v_cndmask_b32_e32 v86, 0, v86, vcc
	v_cmp_le_i32_e32 vcc, v16, v218
	v_or_b32_e32 v16, 10, v237
	v_add_f32_e32 v221, v83, v221
	v_cndmask_b32_e32 v87, 0, v87, vcc
	v_cmp_le_i32_e32 vcc, v16, v218
	v_or_b32_e32 v16, 11, v237
	v_exp_f32_e32 v93, v93
	v_cndmask_b32_e32 v88, 0, v88, vcc
	v_cmp_le_i32_e32 vcc, v16, v218
	v_or_b32_e32 v16, 16, v237
	v_add_f32_e32 v221, v84, v221
	v_cndmask_b32_e32 v89, 0, v89, vcc
	v_cmp_le_i32_e32 vcc, v16, v218
	v_or_b32_e32 v16, 17, v237
	v_exp_f32_e32 v94, v94
	v_cndmask_b32_e32 v90, 0, v90, vcc
	v_cmp_le_i32_e32 vcc, v16, v218
	v_or_b32_e32 v16, 18, v237
	v_add_f32_e32 v221, v85, v221
	v_cndmask_b32_e32 v91, 0, v91, vcc
	v_cmp_le_i32_e32 vcc, v16, v218
	v_or_b32_e32 v16, 19, v237
	v_exp_f32_e32 v95, v95
	v_add_f32_e32 v221, v86, v221
	v_cndmask_b32_e32 v92, 0, v92, vcc
	v_cmp_le_i32_e32 vcc, v16, v218
	v_or_b32_e32 v16, 24, v237
	v_cvt_pk_bf16_f32 v82, v82, v83
	v_cvt_pk_bf16_f32 v83, v84, v85
	v_cvt_pk_bf16_f32 v84, v86, v87
	v_cvt_pk_bf16_f32 v85, v88, v89
	v_add_f32_e32 v221, v87, v221
	v_cndmask_b32_e32 v93, 0, v93, vcc
	v_cmp_le_i32_e32 vcc, v16, v218
	v_or_b32_e32 v16, 25, v237
	v_mfma_f32_32x32x16_bf16 v[66:81], v[138:141], v[82:85], v[66:81]
	v_add_f32_e32 v221, v88, v221
	v_cndmask_b32_e32 v94, 0, v94, vcc
	v_exp_f32_e32 v86, v96
	v_cmp_le_i32_e32 vcc, v16, v218
	v_or_b32_e32 v88, 26, v237
	v_add_f32_e32 v221, v89, v221
	v_cndmask_b32_e32 v87, 0, v95, vcc
	v_mfma_f32_32x32x16_bf16 v[50:65], v[122:125], v[82:85], v[50:65]
	v_cmp_le_i32_e32 vcc, v88, v218
	v_exp_f32_e32 v88, v97
	v_or_b32_e32 v82, 27, v237
	v_cndmask_b32_e32 v86, 0, v86, vcc
	v_cmp_le_i32_e32 vcc, v82, v218
	v_cvt_pk_bf16_f32 v82, v90, v91
	v_cvt_pk_bf16_f32 v83, v92, v93
	v_cndmask_b32_e32 v88, 0, v88, vcc
	v_cvt_pk_bf16_f32 v84, v94, v87
	v_cvt_pk_bf16_f32 v85, v86, v88
	v_add_f32_e32 v221, v90, v221
	v_add_f32_e32 v89, v91, v221
	v_mfma_f32_32x32x16_bf16 v[66:81], v[110:113], v[82:85], v[66:81]
	v_add_f32_e32 v89, v92, v89
	v_add_f32_e32 v89, v93, v89
	v_add_f32_e32 v89, v94, v89
	v_add_f32_e32 v87, v87, v89
	v_add_f32_e32 v86, v86, v87
	v_add_f32_e32 v221, v88, v86
	v_mfma_f32_32x32x16_bf16 v[50:65], v[106:109], v[82:85], v[50:65]
	s_cmp_lg_u32 s85, s86
	s_cbranch_scc1 .Lq_nl1_k0p1
	s_min_u32 s14, s88, 63
	s_nop 3
	v_readlane_b32 s30, v33, s14
	s_and_b32 s30, s30, 0xff
	s_lshl_b32 s30, s30, 13
	s_add_u32 s64, s11, s30
	s_addc_u32 s65, s12, 0
	s_add_u32 s66, s8, s30
	s_addc_u32 s67, s9, 0
	global_load_dwordx4 v[162:165], v2, s[64:65]
	global_load_dwordx4 v[154:157], v2, s[64:65] offset:1024
	global_load_dwordx4 v[150:153], v2, s[64:65] offset:2048
	global_load_dwordx4 v[158:161], v2, s[64:65] offset:3072
	global_load_dwordx4 v[138:141], v2, s[66:67]
	global_load_dwordx4 v[122:125], v2, s[66:67] offset:1024
	global_load_dwordx4 v[110:113], v2, s[66:67] offset:2048
	global_load_dwordx4 v[106:109], v2, s[66:67] offset:3072
	s_branch .Lq_nl1_k0p1
.Lq_s0n_k0p1:
	v_and_b32_e32 v82, s18, v23
	v_cmp_ne_u32_e32 vcc, 0, v82
	s_and_b64 vcc, s[94:95], vcc
	v_mov_b32 v83, 0
	v_cndmask_b32_e32 v82, v236, v222, vcc
	v_sub_f32_e32 v82, v83, v82
	v_mov_b32_e32 v83, v82
	v_mov_b64_e32 v[84:85], v[82:83]
	v_mov_b64_e32 v[86:87], v[82:83]
	v_mov_b64_e32 v[88:89], v[82:83]
	v_mov_b64_e32 v[90:91], v[82:83]
	v_mov_b64_e32 v[92:93], v[82:83]
	v_mov_b64_e32 v[94:95], v[82:83]
	v_mov_b64_e32 v[96:97], v[82:83]
	s_nop 1
	v_mfma_f32_32x32x16_bf16 v[82:97], v[178:181], v[238:241], v[82:97]
	v_mfma_f32_32x32x16_bf16 v[82:97], v[174:177], v[242:245], v[82:97]
	v_mfma_f32_32x32x16_bf16 v[82:97], v[170:173], v[246:249], v[82:97]
	v_mfma_f32_32x32x16_bf16 v[82:97], v[166:169], v[250:253], v[82:97]
	s_waitcnt vmcnt(12)
	v_mov_b32_e32 v28, 0
	v_and_b32_e32 v34, s18, v23
	v_cmp_ne_u32_e32 vcc, 0, v34
	s_and_b64 vcc, s[94:95], vcc
	v_mov_b32 v35, 0
	v_cndmask_b32_e32 v34, v236, v222, vcc
	v_sub_f32_e32 v34, v35, v34
	v_mov_b32_e32 v35, v34
	v_mov_b64_e32 v[36:37], v[34:35]
	v_mov_b64_e32 v[38:39], v[34:35]
	v_mov_b64_e32 v[40:41], v[34:35]
	v_mov_b64_e32 v[42:43], v[34:35]
	v_mov_b64_e32 v[44:45], v[34:35]
	v_mov_b64_e32 v[46:47], v[34:35]
	v_mov_b64_e32 v[48:49], v[34:35]
	s_nop 1
	v_mfma_f32_32x32x16_bf16 v[34:49], v[162:165], v[238:241], v[34:49]
	v_mfma_f32_32x32x16_bf16 v[34:49], v[154:157], v[242:245], v[34:49]
	v_mfma_f32_32x32x16_bf16 v[34:49], v[150:153], v[246:249], v[34:49]
	v_mfma_f32_32x32x16_bf16 v[34:49], v[158:161], v[250:253], v[34:49]
	v_exp_f32_e32 v82, v82
	v_exp_f32_e32 v83, v83
	v_exp_f32_e32 v84, v84
	v_exp_f32_e32 v85, v85
	v_exp_f32_e32 v86, v86
	v_exp_f32_e32 v87, v87
	v_exp_f32_e32 v88, v88
	v_exp_f32_e32 v89, v89
	v_exp_f32_e32 v90, v90
	v_exp_f32_e32 v91, v91
	v_add_f32_e32 v221, v221, v82
	v_exp_f32_e32 v92, v92
	v_exp_f32_e32 v34, v34
	v_add_f32_e32 v221, v83, v221
	v_exp_f32_e32 v35, v35
	v_exp_f32_e32 v93, v93
	v_exp_f32_e32 v36, v36
	v_add_f32_e32 v221, v84, v221
	v_exp_f32_e32 v37, v37
	v_exp_f32_e32 v94, v94
	v_exp_f32_e32 v38, v38
	v_add_f32_e32 v221, v85, v221
	v_exp_f32_e32 v39, v39
	v_exp_f32_e32 v95, v95
	v_exp_f32_e32 v40, v40
	v_add_f32_e32 v221, v86, v221
	v_exp_f32_e32 v41, v41
	v_cvt_pk_bf16_f32 v82, v82, v83
	v_exp_f32_e32 v42, v42
	v_cvt_pk_bf16_f32 v83, v84, v85
	v_exp_f32_e32 v43, v43
	v_cvt_pk_bf16_f32 v84, v86, v87
	v_add_f32_e32 v28, v28, v34
	v_cvt_pk_bf16_f32 v85, v88, v89
	v_exp_f32_e32 v44, v44
	v_add_f32_e32 v221, v87, v221
	v_add_f32_e32 v28, v35, v28
	v_mfma_f32_32x32x16_bf16 v[66:81], v[146:149], v[82:85], 0
	v_exp_f32_e32 v45, v45
	v_add_f32_e32 v221, v88, v221
	v_add_f32_e32 v28, v36, v28
	v_exp_f32_e32 v86, v96
	v_exp_f32_e32 v46, v46
	v_add_f32_e32 v221, v89, v221
	v_add_f32_e32 v28, v37, v28
	v_mov_b32_e32 v87, v95
	v_exp_f32_e32 v47, v47
	v_mfma_f32_32x32x16_bf16 v[50:65], v[142:145], v[82:85], 0
	v_add_f32_e32 v28, v38, v28
	v_exp_f32_e32 v88, v97
	v_cvt_pk_bf16_f32 v34, v34, v35
	v_cvt_pk_bf16_f32 v82, v90, v91
	v_cvt_pk_bf16_f32 v35, v36, v37
	v_cvt_pk_bf16_f32 v83, v92, v93
	v_cvt_pk_bf16_f32 v36, v38, v39
	v_cvt_pk_bf16_f32 v84, v94, v87
	v_cvt_pk_bf16_f32 v37, v40, v41
	v_cvt_pk_bf16_f32 v85, v86, v88
	v_add_f32_e32 v28, v39, v28
	v_add_f32_e32 v221, v90, v221
	v_mfma_f32_32x32x16_bf16 v[66:81], v[138:141], v[34:37], v[66:81]
	v_add_f32_e32 v89, v91, v221
	v_add_f32_e32 v28, v40, v28
	v_mfma_f32_32x32x16_bf16 v[66:81], v[126:129], v[82:85], v[66:81]
	v_exp_f32_e32 v38, v48
	v_add_f32_e32 v89, v92, v89
	v_add_f32_e32 v28, v41, v28
	v_add_f32_e32 v89, v93, v89
	v_mov_b32_e32 v39, v47
	v_add_f32_e32 v89, v94, v89
	v_mfma_f32_32x32x16_bf16 v[50:65], v[122:125], v[34:37], v[50:65]
	v_add_f32_e32 v87, v87, v89
	v_exp_f32_e32 v40, v49
	v_add_f32_e32 v86, v86, v87
	v_cvt_pk_bf16_f32 v34, v42, v43
	v_add_f32_e32 v221, v88, v86
	v_cvt_pk_bf16_f32 v35, v44, v45
	v_mfma_f32_32x32x16_bf16 v[50:65], v[114:117], v[82:85], v[50:65]
	v_cvt_pk_bf16_f32 v36, v46, v39
	v_cvt_pk_bf16_f32 v37, v38, v40
	v_add_f32_e32 v28, v42, v28
	v_add_f32_e32 v41, v43, v28
	v_mfma_f32_32x32x16_bf16 v[66:81], v[110:113], v[34:37], v[66:81]
	v_add_f32_e32 v41, v44, v41
	v_add_f32_e32 v41, v45, v41
	v_add_f32_e32 v41, v46, v41
	v_add_f32_e32 v39, v39, v41
	v_add_f32_e32 v38, v38, v39
	v_add_f32_e32 v28, v40, v38
	v_mfma_f32_32x32x16_bf16 v[50:65], v[106:109], v[34:37], v[50:65]
	v_add_f32_e32 v221, v221, v28
	s_cmp_lg_u32 s85, s86
	s_cbranch_scc1 .Lq_nl1_k0p1
	s_min_u32 s14, s87, 63
	s_nop 3
	v_readlane_b32 s30, v33, s14
	s_and_b32 s30, s30, 0xff
	s_lshl_b32 s30, s30, 13
	s_or_b32 s30, s30, 0x1000
	s_add_u32 s64, s11, s30
	s_addc_u32 s65, s12, 0
	s_add_u32 s66, s8, s30
	s_addc_u32 s67, s9, 0
	global_load_dwordx4 v[178:181], v2, s[64:65]
	global_load_dwordx4 v[174:177], v2, s[64:65] offset:1024
	global_load_dwordx4 v[170:173], v2, s[64:65] offset:2048
	global_load_dwordx4 v[166:169], v2, s[64:65] offset:3072
	global_load_dwordx4 v[146:149], v2, s[66:67]
	global_load_dwordx4 v[142:145], v2, s[66:67] offset:1024
	global_load_dwordx4 v[126:129], v2, s[66:67] offset:2048
	global_load_dwordx4 v[114:117], v2, s[66:67] offset:3072
	s_min_u32 s14, s88, 63
	s_nop 3
	v_readlane_b32 s30, v33, s14
	s_and_b32 s30, s30, 0xff
	s_lshl_b32 s30, s30, 13
	s_add_u32 s64, s11, s30
	s_addc_u32 s65, s12, 0
	s_add_u32 s66, s8, s30
	s_addc_u32 s67, s9, 0
	global_load_dwordx4 v[162:165], v2, s[64:65]
	global_load_dwordx4 v[154:157], v2, s[64:65] offset:1024
	global_load_dwordx4 v[150:153], v2, s[64:65] offset:2048
	global_load_dwordx4 v[158:161], v2, s[64:65] offset:3072
	global_load_dwordx4 v[138:141], v2, s[66:67]
	global_load_dwordx4 v[122:125], v2, s[66:67] offset:1024
	global_load_dwordx4 v[110:113], v2, s[66:67] offset:2048
	global_load_dwordx4 v[106:109], v2, s[66:67] offset:3072

.Lq_wd_k1p0:
	v_bfe_u32 v28, s57, v18, 6
	v_lshl_add_u32 v218, s99, 6, v28
	v_mad_u32_u24 v21, v28, s82, v19
	v_mad_u32_u24 v32, v28, s82, v31
	v_and_b32_e32 v29, s18, v23
	v_cmp_ne_u32_e64 s[54:55], 0, v29
	s_and_b64 s[54:55], s[54:55], s[94:95]
	s_min_u32 s14, s85, 63
	s_nop 3
	v_readlane_b32 s30, v26, s14
	v_readlane_b32 s31, v27, s14
	s_nop 1
	v_bfe_u32 v28, s31, v18, 6
	v_lshl_add_u32 v29, s99, 6, v28
	v_mad_u32_u24 v29, v29, s47, v20
	global_load_dwordx4 v[238:241], v29, s[20:21]
	global_load_dwordx4 v[242:245], v29, s[20:21] offset:32
	global_load_dwordx4 v[246:249], v29, s[20:21] offset:64
	global_load_dwordx4 v[250:253], v29, s[20:21] offset:96
	s_lshl_b32 s0, s100, 6
	v_or_b32_e32 v237, s0, v206
	v_mov_b32_e32 v221, 0
	s_cmp_lg_u32 s100, s99
	s_cbranch_scc1 .Lq_s0n_k1p0
	v_and_b32_e32 v82, s18, v23
	v_cmp_ne_u32_e32 vcc, 0, v82
	s_and_b64 vcc, s[94:95], vcc
	v_mov_b32 v83, 0
	v_or_b32_e32 v16, 2, v237
	v_cndmask_b32_e32 v82, v236, v222, vcc
	v_sub_f32_e32 v82, v83, v82
	v_mov_b32_e32 v83, v82
	v_mov_b64_e32 v[84:85], v[82:83]
	v_mov_b64_e32 v[86:87], v[82:83]
	v_mov_b64_e32 v[88:89], v[82:83]
	v_mov_b64_e32 v[90:91], v[82:83]
	v_mov_b64_e32 v[92:93], v[82:83]
	v_mov_b64_e32 v[94:95], v[82:83]
	v_mov_b64_e32 v[96:97], v[82:83]
	v_cmp_le_i32_e32 vcc, v237, v218
	v_or_b32_e32 v17, 3, v237
	v_mfma_f32_32x32x16_bf16 v[82:97], v[194:197], v[4:7], v[82:97]
	v_or_b32_e32 v30, 8, v237
	v_mfma_f32_32x32x16_bf16 v[82:97], v[190:193], v[8:11], v[82:97]
	v_mfma_f32_32x32x16_bf16 v[82:97], v[186:189], v[12:15], v[82:97]
	v_mfma_f32_32x32x16_bf16 v[82:97], v[182:185], v[98:101], v[82:97]
	s_nop 11
	v_exp_f32_e32 v82, v82
	v_exp_f32_e32 v83, v83
	v_exp_f32_e32 v84, v84
	v_exp_f32_e32 v85, v85
	v_exp_f32_e32 v86, v86
	v_cndmask_b32_e32 v82, 0, v82, vcc
	v_cmp_lt_i32_e32 vcc, v237, v218
	v_exp_f32_e32 v87, v87
	v_exp_f32_e32 v88, v88
	v_cndmask_b32_e32 v83, 0, v83, vcc
	v_cmp_le_i32_e32 vcc, v16, v218
	v_or_b32_e32 v16, 9, v237
	v_exp_f32_e32 v89, v89
	v_cndmask_b32_e32 v84, 0, v84, vcc
	v_cmp_le_i32_e32 vcc, v17, v218
	v_exp_f32_e32 v90, v90
	v_exp_f32_e32 v91, v91
	v_cndmask_b32_e32 v85, 0, v85, vcc
	v_cmp_le_i32_e32 vcc, v30, v218
	v_add_f32_e32 v221, v221, v82
	v_exp_f32_e32 v92, v92
	v_cndmask_b32_e32 v86, 0, v86, vcc
	v_cmp_le_i32_e32 vcc, v16, v218
	v_or_b32_e32 v16, 10, v237
	v_add_f32_e32 v221, v83, v221
	v_cndmask_b32_e32 v87, 0, v87, vcc
	v_cmp_le_i32_e32 vcc, v16, v218
	v_or_b32_e32 v16, 11, v237
	v_exp_f32_e32 v93, v93
	v_cndmask_b32_e32 v88, 0, v88, vcc
	v_cmp_le_i32_e32 vcc, v16, v218
	v_or_b32_e32 v16, 16, v237
	v_add_f32_e32 v221, v84, v221
	v_cndmask_b32_e32 v89, 0, v89, vcc
	v_cmp_le_i32_e32 vcc, v16, v218
	v_or_b32_e32 v16, 17, v237
	v_exp_f32_e32 v94, v94
	v_cndmask_b32_e32 v90, 0, v90, vcc
	v_cmp_le_i32_e32 vcc, v16, v218
	v_or_b32_e32 v16, 18, v237
	v_add_f32_e32 v221, v85, v221
	v_cndmask_b32_e32 v91, 0, v91, vcc
	v_cmp_le_i32_e32 vcc, v16, v218
	v_or_b32_e32 v16, 19, v237
	v_exp_f32_e32 v95, v95
	v_add_f32_e32 v221, v86, v221
	v_cndmask_b32_e32 v92, 0, v92, vcc
	v_cmp_le_i32_e32 vcc, v16, v218
	v_or_b32_e32 v16, 24, v237
	v_cvt_pk_bf16_f32 v82, v82, v83
	v_cvt_pk_bf16_f32 v83, v84, v85
	v_cvt_pk_bf16_f32 v84, v86, v87
	v_cvt_pk_bf16_f32 v85, v88, v89
	v_add_f32_e32 v221, v87, v221
	v_cndmask_b32_e32 v93, 0, v93, vcc
	v_cmp_le_i32_e32 vcc, v16, v218
	v_or_b32_e32 v16, 25, v237
	v_mfma_f32_32x32x16_bf16 v[66:81], v[134:137], v[82:85], 0
	v_add_f32_e32 v221, v88, v221
	v_cndmask_b32_e32 v94, 0, v94, vcc
	v_exp_f32_e32 v86, v96
	v_cmp_le_i32_e32 vcc, v16, v218
	v_or_b32_e32 v88, 26, v237
	v_add_f32_e32 v221, v89, v221
	v_cndmask_b32_e32 v87, 0, v95, vcc
	v_mfma_f32_32x32x16_bf16 v[50:65], v[130:133], v[82:85], 0
	v_cmp_le_i32_e32 vcc, v88, v218
	v_exp_f32_e32 v88, v97
	v_or_b32_e32 v82, 27, v237
	v_cndmask_b32_e32 v86, 0, v86, vcc
	v_cmp_le_i32_e32 vcc, v82, v218
	v_cvt_pk_bf16_f32 v82, v90, v91
	v_cvt_pk_bf16_f32 v83, v92, v93
	v_cndmask_b32_e32 v88, 0, v88, vcc
	v_cvt_pk_bf16_f32 v84, v94, v87
	v_cvt_pk_bf16_f32 v85, v86, v88
	v_add_f32_e32 v221, v90, v221
	v_add_f32_e32 v89, v91, v221
	v_mfma_f32_32x32x16_bf16 v[66:81], v[118:121], v[82:85], v[66:81]
	v_add_f32_e32 v89, v92, v89
	v_add_f32_e32 v89, v93, v89
	v_add_f32_e32 v89, v94, v89
	v_add_f32_e32 v87, v87, v89
	v_add_f32_e32 v86, v86, v87
	v_add_f32_e32 v221, v88, v86
	v_mfma_f32_32x32x16_bf16 v[50:65], v[102:105], v[82:85], v[50:65]
	s_cmp_lg_u32 s85, s86
	s_cbranch_scc1 .Lq_nl0_k1p0
	s_min_u32 s14, s87, 63
	s_nop 3
	v_readlane_b32 s30, v33, s14
	s_and_b32 s30, s30, 0xff
	s_lshl_b32 s30, s30, 13
	s_or_b32 s30, s30, 0x1000
	s_add_u32 s64, s11, s30
	s_addc_u32 s65, s12, 0
	s_add_u32 s66, s8, s30
	s_addc_u32 s67, s9, 0
	global_load_dwordx4 v[194:197], v2, s[64:65]
	global_load_dwordx4 v[190:193], v2, s[64:65] offset:1024
	global_load_dwordx4 v[186:189], v2, s[64:65] offset:2048
	global_load_dwordx4 v[182:185], v2, s[64:65] offset:3072
	global_load_dwordx4 v[134:137], v2, s[66:67]
	global_load_dwordx4 v[130:133], v2, s[66:67] offset:1024
	global_load_dwordx4 v[118:121], v2, s[66:67] offset:2048
	global_load_dwordx4 v[102:105], v2, s[66:67] offset:3072
	s_waitcnt vmcnt(20)
	s_branch .Lq_nl0d_k1p0

.Lq_nl0d_k1p0:
	s_lshl_b32 s0, s100, 6
	s_or_b32 s0, s0, 32
	v_or_b32_e32 v237, s0, v206
	v_and_b32_e32 v82, s18, v23
	v_cmp_ne_u32_e32 vcc, 0, v82
	s_and_b64 vcc, s[94:95], vcc
	v_mov_b32 v83, 0
	v_or_b32_e32 v16, 2, v237
	v_cndmask_b32_e32 v82, v236, v222, vcc
	v_sub_f32_e32 v82, v83, v82
	v_mov_b32_e32 v83, v82
	v_mov_b64_e32 v[84:85], v[82:83]
	v_mov_b64_e32 v[86:87], v[82:83]
	v_mov_b64_e32 v[88:89], v[82:83]
	v_mov_b64_e32 v[90:91], v[82:83]
	v_mov_b64_e32 v[92:93], v[82:83]
	v_mov_b64_e32 v[94:95], v[82:83]
	v_mov_b64_e32 v[96:97], v[82:83]
	v_cmp_le_i32_e32 vcc, v237, v218
	v_or_b32_e32 v17, 3, v237
	v_mfma_f32_32x32x16_bf16 v[82:97], v[178:181], v[4:7], v[82:97]
	v_or_b32_e32 v30, 8, v237
	v_mfma_f32_32x32x16_bf16 v[82:97], v[174:177], v[8:11], v[82:97]
	v_mfma_f32_32x32x16_bf16 v[82:97], v[170:173], v[12:15], v[82:97]
	v_mfma_f32_32x32x16_bf16 v[82:97], v[166:169], v[98:101], v[82:97]
	s_nop 11
	v_exp_f32_e32 v82, v82
	v_exp_f32_e32 v83, v83
	v_exp_f32_e32 v84, v84
	v_exp_f32_e32 v85, v85
	v_exp_f32_e32 v86, v86
	v_cndmask_b32_e32 v82, 0, v82, vcc
	v_cmp_lt_i32_e32 vcc, v237, v218
	v_exp_f32_e32 v87, v87
	v_exp_f32_e32 v88, v88
	v_cndmask_b32_e32 v83, 0, v83, vcc
	v_cmp_le_i32_e32 vcc, v16, v218
	v_or_b32_e32 v16, 9, v237
	v_exp_f32_e32 v89, v89
	v_cndmask_b32_e32 v84, 0, v84, vcc
	v_cmp_le_i32_e32 vcc, v17, v218
	v_exp_f32_e32 v90, v90
	v_exp_f32_e32 v91, v91
	v_cndmask_b32_e32 v85, 0, v85, vcc
	v_cmp_le_i32_e32 vcc, v30, v218
	v_add_f32_e32 v221, v221, v82
	v_exp_f32_e32 v92, v92
	v_cndmask_b32_e32 v86, 0, v86, vcc
	v_cmp_le_i32_e32 vcc, v16, v218
	v_or_b32_e32 v16, 10, v237
	v_add_f32_e32 v221, v83, v221
	v_cndmask_b32_e32 v87, 0, v87, vcc
	v_cmp_le_i32_e32 vcc, v16, v218
	v_or_b32_e32 v16, 11, v237
	v_exp_f32_e32 v93, v93
	v_cndmask_b32_e32 v88, 0, v88, vcc
	v_cmp_le_i32_e32 vcc, v16, v218
	v_or_b32_e32 v16, 16, v237
	v_add_f32_e32 v221, v84, v221
	v_cndmask_b32_e32 v89, 0, v89, vcc
	v_cmp_le_i32_e32 vcc, v16, v218
	v_or_b32_e32 v16, 17, v237
	v_exp_f32_e32 v94, v94
	v_cndmask_b32_e32 v90, 0, v90, vcc
	v_cmp_le_i32_e32 vcc, v16, v218
	v_or_b32_e32 v16, 18, v237
	v_add_f32_e32 v221, v85, v221
	v_cndmask_b32_e32 v91, 0, v91, vcc
	v_cmp_le_i32_e32 vcc, v16, v218
	v_or_b32_e32 v16, 19, v237
	v_exp_f32_e32 v95, v95
	v_add_f32_e32 v221, v86, v221
	v_cndmask_b32_e32 v92, 0, v92, vcc
	v_cmp_le_i32_e32 vcc, v16, v218
	v_or_b32_e32 v16, 24, v237
	v_cvt_pk_bf16_f32 v82, v82, v83
	v_cvt_pk_bf16_f32 v83, v84, v85
	v_cvt_pk_bf16_f32 v84, v86, v87
	v_cvt_pk_bf16_f32 v85, v88, v89
	v_add_f32_e32 v221, v87, v221
	v_cndmask_b32_e32 v93, 0, v93, vcc
	v_cmp_le_i32_e32 vcc, v16, v218
	v_or_b32_e32 v16, 25, v237
	v_mfma_f32_32x32x16_bf16 v[66:81], v[146:149], v[82:85], v[66:81]
	v_add_f32_e32 v221, v88, v221
	v_cndmask_b32_e32 v94, 0, v94, vcc
	v_exp_f32_e32 v86, v96
	v_cmp_le_i32_e32 vcc, v16, v218
	v_or_b32_e32 v88, 26, v237
	v_add_f32_e32 v221, v89, v221
	v_cndmask_b32_e32 v87, 0, v95, vcc
	v_mfma_f32_32x32x16_bf16 v[50:65], v[142:145], v[82:85], v[50:65]
	v_cmp_le_i32_e32 vcc, v88, v218
	v_exp_f32_e32 v88, v97
	v_or_b32_e32 v82, 27, v237
	v_cndmask_b32_e32 v86, 0, v86, vcc
	v_cmp_le_i32_e32 vcc, v82, v218
	v_cvt_pk_bf16_f32 v82, v90, v91
	v_cvt_pk_bf16_f32 v83, v92, v93
	v_cndmask_b32_e32 v88, 0, v88, vcc
	v_cvt_pk_bf16_f32 v84, v94, v87
	v_cvt_pk_bf16_f32 v85, v86, v88
	v_add_f32_e32 v221, v90, v221
	v_add_f32_e32 v89, v91, v221
	v_mfma_f32_32x32x16_bf16 v[66:81], v[126:129], v[82:85], v[66:81]
	v_add_f32_e32 v89, v92, v89
	v_add_f32_e32 v89, v93, v89
	v_add_f32_e32 v89, v94, v89
	v_add_f32_e32 v87, v87, v89
	v_add_f32_e32 v86, v86, v87
	v_add_f32_e32 v221, v88, v86
	v_mfma_f32_32x32x16_bf16 v[50:65], v[114:117], v[82:85], v[50:65]
	s_cmp_lg_u32 s85, s86
	s_cbranch_scc1 .Lq_nl1_k1p0
	s_min_u32 s14, s88, 63
	s_nop 3
	v_readlane_b32 s30, v33, s14
	s_and_b32 s30, s30, 0xff
	s_lshl_b32 s30, s30, 13
	s_add_u32 s64, s11, s30
	s_addc_u32 s65, s12, 0
	s_add_u32 s66, s8, s30
	s_addc_u32 s67, s9, 0
	global_load_dwordx4 v[178:181], v2, s[64:65]
	global_load_dwordx4 v[174:177], v2, s[64:65] offset:1024
	global_load_dwordx4 v[170:173], v2, s[64:65] offset:2048
	global_load_dwordx4 v[166:169], v2, s[64:65] offset:3072
	global_load_dwordx4 v[146:149], v2, s[66:67]
	global_load_dwordx4 v[142:145], v2, s[66:67] offset:1024
	global_load_dwordx4 v[126:129], v2, s[66:67] offset:2048
	global_load_dwordx4 v[114:117], v2, s[66:67] offset:3072
	s_branch .Lq_nl1_k1p0
.Lq_s0n_k1p0:
	v_and_b32_e32 v82, s18, v23
	v_cmp_ne_u32_e32 vcc, 0, v82
	s_and_b64 vcc, s[94:95], vcc
	v_mov_b32 v83, 0
	v_cndmask_b32_e32 v82, v236, v222, vcc
	v_sub_f32_e32 v82, v83, v82
	v_mov_b32_e32 v83, v82
	v_mov_b64_e32 v[84:85], v[82:83]
	v_mov_b64_e32 v[86:87], v[82:83]
	v_mov_b64_e32 v[88:89], v[82:83]
	v_mov_b64_e32 v[90:91], v[82:83]
	v_mov_b64_e32 v[92:93], v[82:83]
	v_mov_b64_e32 v[94:95], v[82:83]
	v_mov_b64_e32 v[96:97], v[82:83]
	s_nop 1
	v_mfma_f32_32x32x16_bf16 v[82:97], v[194:197], v[4:7], v[82:97]
	v_mfma_f32_32x32x16_bf16 v[82:97], v[190:193], v[8:11], v[82:97]
	v_mfma_f32_32x32x16_bf16 v[82:97], v[186:189], v[12:15], v[82:97]
	v_mfma_f32_32x32x16_bf16 v[82:97], v[182:185], v[98:101], v[82:97]
	s_waitcnt vmcnt(12)
	v_mov_b32_e32 v28, 0
	v_and_b32_e32 v34, s18, v23
	v_cmp_ne_u32_e32 vcc, 0, v34
	s_and_b64 vcc, s[94:95], vcc
	v_mov_b32 v35, 0
	v_cndmask_b32_e32 v34, v236, v222, vcc
	v_sub_f32_e32 v34, v35, v34
	v_mov_b32_e32 v35, v34
	v_mov_b64_e32 v[36:37], v[34:35]
	v_mov_b64_e32 v[38:39], v[34:35]
	v_mov_b64_e32 v[40:41], v[34:35]
	v_mov_b64_e32 v[42:43], v[34:35]
	v_mov_b64_e32 v[44:45], v[34:35]
	v_mov_b64_e32 v[46:47], v[34:35]
	v_mov_b64_e32 v[48:49], v[34:35]
	s_nop 1
	v_mfma_f32_32x32x16_bf16 v[34:49], v[178:181], v[4:7], v[34:49]
	v_mfma_f32_32x32x16_bf16 v[34:49], v[174:177], v[8:11], v[34:49]
	v_mfma_f32_32x32x16_bf16 v[34:49], v[170:173], v[12:15], v[34:49]
	v_mfma_f32_32x32x16_bf16 v[34:49], v[166:169], v[98:101], v[34:49]
	v_exp_f32_e32 v82, v82
	v_exp_f32_e32 v83, v83
	v_exp_f32_e32 v84, v84
	v_exp_f32_e32 v85, v85
	v_exp_f32_e32 v86, v86
	v_exp_f32_e32 v87, v87
	v_exp_f32_e32 v88, v88
	v_exp_f32_e32 v89, v89
	v_exp_f32_e32 v90, v90
	v_exp_f32_e32 v91, v91
	v_add_f32_e32 v221, v221, v82
	v_exp_f32_e32 v92, v92
	v_exp_f32_e32 v34, v34
	v_add_f32_e32 v221, v83, v221
	v_exp_f32_e32 v35, v35
	v_exp_f32_e32 v93, v93
	v_exp_f32_e32 v36, v36
	v_add_f32_e32 v221, v84, v221
	v_exp_f32_e32 v37, v37
	v_exp_f32_e32 v94, v94
	v_exp_f32_e32 v38, v38
	v_add_f32_e32 v221, v85, v221
	v_exp_f32_e32 v39, v39
	v_exp_f32_e32 v95, v95
	v_exp_f32_e32 v40, v40
	v_add_f32_e32 v221, v86, v221
	v_exp_f32_e32 v41, v41
	v_cvt_pk_bf16_f32 v82, v82, v83
	v_exp_f32_e32 v42, v42
	v_cvt_pk_bf16_f32 v83, v84, v85
	v_exp_f32_e32 v43, v43
	v_cvt_pk_bf16_f32 v84, v86, v87
	v_add_f32_e32 v28, v28, v34
	v_cvt_pk_bf16_f32 v85, v88, v89
	v_exp_f32_e32 v44, v44
	v_add_f32_e32 v221, v87, v221
	v_add_f32_e32 v28, v35, v28
	v_mfma_f32_32x32x16_bf16 v[66:81], v[134:137], v[82:85], 0
	v_exp_f32_e32 v45, v45
	v_add_f32_e32 v221, v88, v221
	v_add_f32_e32 v28, v36, v28
	v_exp_f32_e32 v86, v96
	v_exp_f32_e32 v46, v46
	v_add_f32_e32 v221, v89, v221
	v_add_f32_e32 v28, v37, v28
	v_mov_b32_e32 v87, v95
	v_exp_f32_e32 v47, v47
	v_mfma_f32_32x32x16_bf16 v[50:65], v[130:133], v[82:85], 0
	v_add_f32_e32 v28, v38, v28
	v_exp_f32_e32 v88, v97
	v_cvt_pk_bf16_f32 v34, v34, v35
	v_cvt_pk_bf16_f32 v82, v90, v91
	v_cvt_pk_bf16_f32 v35, v36, v37
	v_cvt_pk_bf16_f32 v83, v92, v93
	v_cvt_pk_bf16_f32 v36, v38, v39
	v_cvt_pk_bf16_f32 v84, v94, v87
	v_cvt_pk_bf16_f32 v37, v40, v41
	v_cvt_pk_bf16_f32 v85, v86, v88
	v_add_f32_e32 v28, v39, v28
	v_add_f32_e32 v221, v90, v221
	v_mfma_f32_32x32x16_bf16 v[66:81], v[146:149], v[34:37], v[66:81]
	v_add_f32_e32 v89, v91, v221
	v_add_f32_e32 v28, v40, v28
	v_mfma_f32_32x32x16_bf16 v[66:81], v[118:121], v[82:85], v[66:81]
	v_exp_f32_e32 v38, v48
	v_add_f32_e32 v89, v92, v89
	v_add_f32_e32 v28, v41, v28
	v_add_f32_e32 v89, v93, v89
	v_mov_b32_e32 v39, v47
	v_add_f32_e32 v89, v94, v89
	v_mfma_f32_32x32x16_bf16 v[50:65], v[142:145], v[34:37], v[50:65]
	v_add_f32_e32 v87, v87, v89
	v_exp_f32_e32 v40, v49
	v_add_f32_e32 v86, v86, v87
	v_cvt_pk_bf16_f32 v34, v42, v43
	v_add_f32_e32 v221, v88, v86
	v_cvt_pk_bf16_f32 v35, v44, v45
	v_mfma_f32_32x32x16_bf16 v[50:65], v[102:105], v[82:85], v[50:65]
	v_cvt_pk_bf16_f32 v36, v46, v39
	v_cvt_pk_bf16_f32 v37, v38, v40
	v_add_f32_e32 v28, v42, v28
	v_add_f32_e32 v41, v43, v28
	v_mfma_f32_32x32x16_bf16 v[66:81], v[126:129], v[34:37], v[66:81]
	v_add_f32_e32 v41, v44, v41
	v_add_f32_e32 v41, v45, v41
	v_add_f32_e32 v41, v46, v41
	v_add_f32_e32 v39, v39, v41
	v_add_f32_e32 v38, v38, v39
	v_add_f32_e32 v28, v40, v38
	v_mfma_f32_32x32x16_bf16 v[50:65], v[114:117], v[34:37], v[50:65]
	v_add_f32_e32 v221, v221, v28
	s_cmp_lg_u32 s85, s86
	s_cbranch_scc1 .Lq_nl1_k1p0
	s_min_u32 s14, s87, 63
	s_nop 3
	v_readlane_b32 s30, v33, s14
	s_and_b32 s30, s30, 0xff
	s_lshl_b32 s30, s30, 13
	s_or_b32 s30, s30, 0x1000
	s_add_u32 s64, s11, s30
	s_addc_u32 s65, s12, 0
	s_add_u32 s66, s8, s30
	s_addc_u32 s67, s9, 0
	global_load_dwordx4 v[194:197], v2, s[64:65]
	global_load_dwordx4 v[190:193], v2, s[64:65] offset:1024
	global_load_dwordx4 v[186:189], v2, s[64:65] offset:2048
	global_load_dwordx4 v[182:185], v2, s[64:65] offset:3072
	global_load_dwordx4 v[134:137], v2, s[66:67]
	global_load_dwordx4 v[130:133], v2, s[66:67] offset:1024
	global_load_dwordx4 v[118:121], v2, s[66:67] offset:2048
	global_load_dwordx4 v[102:105], v2, s[66:67] offset:3072
	s_min_u32 s14, s88, 63
	s_nop 3
	v_readlane_b32 s30, v33, s14
	s_and_b32 s30, s30, 0xff
	s_lshl_b32 s30, s30, 13
	s_add_u32 s64, s11, s30
	s_addc_u32 s65, s12, 0
	s_add_u32 s66, s8, s30
	s_addc_u32 s67, s9, 0
	global_load_dwordx4 v[178:181], v2, s[64:65]
	global_load_dwordx4 v[174:177], v2, s[64:65] offset:1024
	global_load_dwordx4 v[170:173], v2, s[64:65] offset:2048
	global_load_dwordx4 v[166:169], v2, s[64:65] offset:3072
	global_load_dwordx4 v[146:149], v2, s[66:67]
	global_load_dwordx4 v[142:145], v2, s[66:67] offset:1024
	global_load_dwordx4 v[126:129], v2, s[66:67] offset:2048
	global_load_dwordx4 v[114:117], v2, s[66:67] offset:3072

.Lq_wd_k1p1:
	v_bfe_u32 v28, s57, v18, 6
	v_lshl_add_u32 v218, s99, 6, v28
	v_mad_u32_u24 v21, v28, s82, v19
	v_mad_u32_u24 v32, v28, s82, v31
	v_and_b32_e32 v29, s18, v23
	v_cmp_ne_u32_e64 s[54:55], 0, v29
	s_and_b64 s[54:55], s[54:55], s[94:95]
	s_min_u32 s14, s85, 63
	s_nop 3
	v_readlane_b32 s30, v26, s14
	v_readlane_b32 s31, v27, s14
	s_nop 1
	v_bfe_u32 v28, s31, v18, 6
	v_lshl_add_u32 v29, s99, 6, v28
	v_mad_u32_u24 v29, v29, s47, v20
	global_load_dwordx4 v[4:7], v29, s[20:21]
	global_load_dwordx4 v[8:11], v29, s[20:21] offset:32
	global_load_dwordx4 v[12:15], v29, s[20:21] offset:64
	global_load_dwordx4 v[98:101], v29, s[20:21] offset:96
	s_lshl_b32 s0, s100, 6
	v_or_b32_e32 v237, s0, v206
	v_mov_b32_e32 v221, 0
	s_cmp_lg_u32 s100, s99
	s_cbranch_scc1 .Lq_s0n_k1p1
	v_and_b32_e32 v82, s18, v23
	v_cmp_ne_u32_e32 vcc, 0, v82
	s_and_b64 vcc, s[94:95], vcc
	v_mov_b32 v83, 0
	v_or_b32_e32 v16, 2, v237
	v_cndmask_b32_e32 v82, v236, v222, vcc
	v_sub_f32_e32 v82, v83, v82
	v_mov_b32_e32 v83, v82
	v_mov_b64_e32 v[84:85], v[82:83]
	v_mov_b64_e32 v[86:87], v[82:83]
	v_mov_b64_e32 v[88:89], v[82:83]
	v_mov_b64_e32 v[90:91], v[82:83]
	v_mov_b64_e32 v[92:93], v[82:83]
	v_mov_b64_e32 v[94:95], v[82:83]
	v_mov_b64_e32 v[96:97], v[82:83]
	v_cmp_le_i32_e32 vcc, v237, v218
	v_or_b32_e32 v17, 3, v237
	v_mfma_f32_32x32x16_bf16 v[82:97], v[194:197], v[238:241], v[82:97]
	v_or_b32_e32 v30, 8, v237
	v_mfma_f32_32x32x16_bf16 v[82:97], v[190:193], v[242:245], v[82:97]
	v_mfma_f32_32x32x16_bf16 v[82:97], v[186:189], v[246:249], v[82:97]
	v_mfma_f32_32x32x16_bf16 v[82:97], v[182:185], v[250:253], v[82:97]
	s_nop 11
	v_exp_f32_e32 v82, v82
	v_exp_f32_e32 v83, v83
	v_exp_f32_e32 v84, v84
	v_exp_f32_e32 v85, v85
	v_exp_f32_e32 v86, v86
	v_cndmask_b32_e32 v82, 0, v82, vcc
	v_cmp_lt_i32_e32 vcc, v237, v218
	v_exp_f32_e32 v87, v87
	v_exp_f32_e32 v88, v88
	v_cndmask_b32_e32 v83, 0, v83, vcc
	v_cmp_le_i32_e32 vcc, v16, v218
	v_or_b32_e32 v16, 9, v237
	v_exp_f32_e32 v89, v89
	v_cndmask_b32_e32 v84, 0, v84, vcc
	v_cmp_le_i32_e32 vcc, v17, v218
	v_exp_f32_e32 v90, v90
	v_exp_f32_e32 v91, v91
	v_cndmask_b32_e32 v85, 0, v85, vcc
	v_cmp_le_i32_e32 vcc, v30, v218
	v_add_f32_e32 v221, v221, v82
	v_exp_f32_e32 v92, v92
	v_cndmask_b32_e32 v86, 0, v86, vcc
	v_cmp_le_i32_e32 vcc, v16, v218
	v_or_b32_e32 v16, 10, v237
	v_add_f32_e32 v221, v83, v221
	v_cndmask_b32_e32 v87, 0, v87, vcc
	v_cmp_le_i32_e32 vcc, v16, v218
	v_or_b32_e32 v16, 11, v237
	v_exp_f32_e32 v93, v93
	v_cndmask_b32_e32 v88, 0, v88, vcc
	v_cmp_le_i32_e32 vcc, v16, v218
	v_or_b32_e32 v16, 16, v237
	v_add_f32_e32 v221, v84, v221
	v_cndmask_b32_e32 v89, 0, v89, vcc
	v_cmp_le_i32_e32 vcc, v16, v218
	v_or_b32_e32 v16, 17, v237
	v_exp_f32_e32 v94, v94
	v_cndmask_b32_e32 v90, 0, v90, vcc
	v_cmp_le_i32_e32 vcc, v16, v218
	v_or_b32_e32 v16, 18, v237
	v_add_f32_e32 v221, v85, v221
	v_cndmask_b32_e32 v91, 0, v91, vcc
	v_cmp_le_i32_e32 vcc, v16, v218
	v_or_b32_e32 v16, 19, v237
	v_exp_f32_e32 v95, v95
	v_add_f32_e32 v221, v86, v221
	v_cndmask_b32_e32 v92, 0, v92, vcc
	v_cmp_le_i32_e32 vcc, v16, v218
	v_or_b32_e32 v16, 24, v237
	v_cvt_pk_bf16_f32 v82, v82, v83
	v_cvt_pk_bf16_f32 v83, v84, v85
	v_cvt_pk_bf16_f32 v84, v86, v87
	v_cvt_pk_bf16_f32 v85, v88, v89
	v_add_f32_e32 v221, v87, v221
	v_cndmask_b32_e32 v93, 0, v93, vcc
	v_cmp_le_i32_e32 vcc, v16, v218
	v_or_b32_e32 v16, 25, v237
	v_mfma_f32_32x32x16_bf16 v[66:81], v[134:137], v[82:85], 0
	v_add_f32_e32 v221, v88, v221
	v_cndmask_b32_e32 v94, 0, v94, vcc
	v_exp_f32_e32 v86, v96
	v_cmp_le_i32_e32 vcc, v16, v218
	v_or_b32_e32 v88, 26, v237
	v_add_f32_e32 v221, v89, v221
	v_cndmask_b32_e32 v87, 0, v95, vcc
	v_mfma_f32_32x32x16_bf16 v[50:65], v[130:133], v[82:85], 0
	v_cmp_le_i32_e32 vcc, v88, v218
	v_exp_f32_e32 v88, v97
	v_or_b32_e32 v82, 27, v237
	v_cndmask_b32_e32 v86, 0, v86, vcc
	v_cmp_le_i32_e32 vcc, v82, v218
	v_cvt_pk_bf16_f32 v82, v90, v91
	v_cvt_pk_bf16_f32 v83, v92, v93
	v_cndmask_b32_e32 v88, 0, v88, vcc
	v_cvt_pk_bf16_f32 v84, v94, v87
	v_cvt_pk_bf16_f32 v85, v86, v88
	v_add_f32_e32 v221, v90, v221
	v_add_f32_e32 v89, v91, v221
	v_mfma_f32_32x32x16_bf16 v[66:81], v[118:121], v[82:85], v[66:81]
	v_add_f32_e32 v89, v92, v89
	v_add_f32_e32 v89, v93, v89
	v_add_f32_e32 v89, v94, v89
	v_add_f32_e32 v87, v87, v89
	v_add_f32_e32 v86, v86, v87
	v_add_f32_e32 v221, v88, v86
	v_mfma_f32_32x32x16_bf16 v[50:65], v[102:105], v[82:85], v[50:65]
	s_cmp_lg_u32 s85, s86
	s_cbranch_scc1 .Lq_nl0_k1p1
	s_min_u32 s14, s87, 63
	s_nop 3
	v_readlane_b32 s30, v33, s14
	s_and_b32 s30, s30, 0xff
	s_lshl_b32 s30, s30, 13
	s_or_b32 s30, s30, 0x1000
	s_add_u32 s64, s11, s30
	s_addc_u32 s65, s12, 0
	s_add_u32 s66, s8, s30
	s_addc_u32 s67, s9, 0
	global_load_dwordx4 v[194:197], v2, s[64:65]
	global_load_dwordx4 v[190:193], v2, s[64:65] offset:1024
	global_load_dwordx4 v[186:189], v2, s[64:65] offset:2048
	global_load_dwordx4 v[182:185], v2, s[64:65] offset:3072
	global_load_dwordx4 v[134:137], v2, s[66:67]
	global_load_dwordx4 v[130:133], v2, s[66:67] offset:1024
	global_load_dwordx4 v[118:121], v2, s[66:67] offset:2048
	global_load_dwordx4 v[102:105], v2, s[66:67] offset:3072
	s_waitcnt vmcnt(20)
	s_branch .Lq_nl0d_k1p1

.Lq_nl0d_k1p1:
	s_lshl_b32 s0, s100, 6
	s_or_b32 s0, s0, 32
	v_or_b32_e32 v237, s0, v206
	v_and_b32_e32 v82, s18, v23
	v_cmp_ne_u32_e32 vcc, 0, v82
	s_and_b64 vcc, s[94:95], vcc
	v_mov_b32 v83, 0
	v_or_b32_e32 v16, 2, v237
	v_cndmask_b32_e32 v82, v236, v222, vcc
	v_sub_f32_e32 v82, v83, v82
	v_mov_b32_e32 v83, v82
	v_mov_b64_e32 v[84:85], v[82:83]
	v_mov_b64_e32 v[86:87], v[82:83]
	v_mov_b64_e32 v[88:89], v[82:83]
	v_mov_b64_e32 v[90:91], v[82:83]
	v_mov_b64_e32 v[92:93], v[82:83]
	v_mov_b64_e32 v[94:95], v[82:83]
	v_mov_b64_e32 v[96:97], v[82:83]
	v_cmp_le_i32_e32 vcc, v237, v218
	v_or_b32_e32 v17, 3, v237
	v_mfma_f32_32x32x16_bf16 v[82:97], v[178:181], v[238:241], v[82:97]
	v_or_b32_e32 v30, 8, v237
	v_mfma_f32_32x32x16_bf16 v[82:97], v[174:177], v[242:245], v[82:97]
	v_mfma_f32_32x32x16_bf16 v[82:97], v[170:173], v[246:249], v[82:97]
	v_mfma_f32_32x32x16_bf16 v[82:97], v[166:169], v[250:253], v[82:97]
	s_nop 11
	v_exp_f32_e32 v82, v82
	v_exp_f32_e32 v83, v83
	v_exp_f32_e32 v84, v84
	v_exp_f32_e32 v85, v85
	v_exp_f32_e32 v86, v86
	v_cndmask_b32_e32 v82, 0, v82, vcc
	v_cmp_lt_i32_e32 vcc, v237, v218
	v_exp_f32_e32 v87, v87
	v_exp_f32_e32 v88, v88
	v_cndmask_b32_e32 v83, 0, v83, vcc
	v_cmp_le_i32_e32 vcc, v16, v218
	v_or_b32_e32 v16, 9, v237
	v_exp_f32_e32 v89, v89
	v_cndmask_b32_e32 v84, 0, v84, vcc
	v_cmp_le_i32_e32 vcc, v17, v218
	v_exp_f32_e32 v90, v90
	v_exp_f32_e32 v91, v91
	v_cndmask_b32_e32 v85, 0, v85, vcc
	v_cmp_le_i32_e32 vcc, v30, v218
	v_add_f32_e32 v221, v221, v82
	v_exp_f32_e32 v92, v92
	v_cndmask_b32_e32 v86, 0, v86, vcc
	v_cmp_le_i32_e32 vcc, v16, v218
	v_or_b32_e32 v16, 10, v237
	v_add_f32_e32 v221, v83, v221
	v_cndmask_b32_e32 v87, 0, v87, vcc
	v_cmp_le_i32_e32 vcc, v16, v218
	v_or_b32_e32 v16, 11, v237
	v_exp_f32_e32 v93, v93
	v_cndmask_b32_e32 v88, 0, v88, vcc
	v_cmp_le_i32_e32 vcc, v16, v218
	v_or_b32_e32 v16, 16, v237
	v_add_f32_e32 v221, v84, v221
	v_cndmask_b32_e32 v89, 0, v89, vcc
	v_cmp_le_i32_e32 vcc, v16, v218
	v_or_b32_e32 v16, 17, v237
	v_exp_f32_e32 v94, v94
	v_cndmask_b32_e32 v90, 0, v90, vcc
	v_cmp_le_i32_e32 vcc, v16, v218
	v_or_b32_e32 v16, 18, v237
	v_add_f32_e32 v221, v85, v221
	v_cndmask_b32_e32 v91, 0, v91, vcc
	v_cmp_le_i32_e32 vcc, v16, v218
	v_or_b32_e32 v16, 19, v237
	v_exp_f32_e32 v95, v95
	v_add_f32_e32 v221, v86, v221
	v_cndmask_b32_e32 v92, 0, v92, vcc
	v_cmp_le_i32_e32 vcc, v16, v218
	v_or_b32_e32 v16, 24, v237
	v_cvt_pk_bf16_f32 v82, v82, v83
	v_cvt_pk_bf16_f32 v83, v84, v85
	v_cvt_pk_bf16_f32 v84, v86, v87
	v_cvt_pk_bf16_f32 v85, v88, v89
	v_add_f32_e32 v221, v87, v221
	v_cndmask_b32_e32 v93, 0, v93, vcc
	v_cmp_le_i32_e32 vcc, v16, v218
	v_or_b32_e32 v16, 25, v237
	v_mfma_f32_32x32x16_bf16 v[66:81], v[146:149], v[82:85], v[66:81]
	v_add_f32_e32 v221, v88, v221
	v_cndmask_b32_e32 v94, 0, v94, vcc
	v_exp_f32_e32 v86, v96
	v_cmp_le_i32_e32 vcc, v16, v218
	v_or_b32_e32 v88, 26, v237
	v_add_f32_e32 v221, v89, v221
	v_cndmask_b32_e32 v87, 0, v95, vcc
	v_mfma_f32_32x32x16_bf16 v[50:65], v[142:145], v[82:85], v[50:65]
	v_cmp_le_i32_e32 vcc, v88, v218
	v_exp_f32_e32 v88, v97
	v_or_b32_e32 v82, 27, v237
	v_cndmask_b32_e32 v86, 0, v86, vcc
	v_cmp_le_i32_e32 vcc, v82, v218
	v_cvt_pk_bf16_f32 v82, v90, v91
	v_cvt_pk_bf16_f32 v83, v92, v93
	v_cndmask_b32_e32 v88, 0, v88, vcc
	v_cvt_pk_bf16_f32 v84, v94, v87
	v_cvt_pk_bf16_f32 v85, v86, v88
	v_add_f32_e32 v221, v90, v221
	v_add_f32_e32 v89, v91, v221
	v_mfma_f32_32x32x16_bf16 v[66:81], v[126:129], v[82:85], v[66:81]
	v_add_f32_e32 v89, v92, v89
	v_add_f32_e32 v89, v93, v89
	v_add_f32_e32 v89, v94, v89
	v_add_f32_e32 v87, v87, v89
	v_add_f32_e32 v86, v86, v87
	v_add_f32_e32 v221, v88, v86
	v_mfma_f32_32x32x16_bf16 v[50:65], v[114:117], v[82:85], v[50:65]
	s_cmp_lg_u32 s85, s86
	s_cbranch_scc1 .Lq_nl1_k1p1
	s_min_u32 s14, s88, 63
	s_nop 3
	v_readlane_b32 s30, v33, s14
	s_and_b32 s30, s30, 0xff
	s_lshl_b32 s30, s30, 13
	s_add_u32 s64, s11, s30
	s_addc_u32 s65, s12, 0
	s_add_u32 s66, s8, s30
	s_addc_u32 s67, s9, 0
	global_load_dwordx4 v[178:181], v2, s[64:65]
	global_load_dwordx4 v[174:177], v2, s[64:65] offset:1024
	global_load_dwordx4 v[170:173], v2, s[64:65] offset:2048
	global_load_dwordx4 v[166:169], v2, s[64:65] offset:3072
	global_load_dwordx4 v[146:149], v2, s[66:67]
	global_load_dwordx4 v[142:145], v2, s[66:67] offset:1024
	global_load_dwordx4 v[126:129], v2, s[66:67] offset:2048
	global_load_dwordx4 v[114:117], v2, s[66:67] offset:3072
	s_branch .Lq_nl1_k1p1
.Lq_s0n_k1p1:
	v_and_b32_e32 v82, s18, v23
	v_cmp_ne_u32_e32 vcc, 0, v82
	s_and_b64 vcc, s[94:95], vcc
	v_mov_b32 v83, 0
	v_cndmask_b32_e32 v82, v236, v222, vcc
	v_sub_f32_e32 v82, v83, v82
	v_mov_b32_e32 v83, v82
	v_mov_b64_e32 v[84:85], v[82:83]
	v_mov_b64_e32 v[86:87], v[82:83]
	v_mov_b64_e32 v[88:89], v[82:83]
	v_mov_b64_e32 v[90:91], v[82:83]
	v_mov_b64_e32 v[92:93], v[82:83]
	v_mov_b64_e32 v[94:95], v[82:83]
	v_mov_b64_e32 v[96:97], v[82:83]
	s_nop 1
	v_mfma_f32_32x32x16_bf16 v[82:97], v[194:197], v[238:241], v[82:97]
	v_mfma_f32_32x32x16_bf16 v[82:97], v[190:193], v[242:245], v[82:97]
	v_mfma_f32_32x32x16_bf16 v[82:97], v[186:189], v[246:249], v[82:97]
	v_mfma_f32_32x32x16_bf16 v[82:97], v[182:185], v[250:253], v[82:97]
	s_waitcnt vmcnt(12)
	v_mov_b32_e32 v28, 0
	v_and_b32_e32 v34, s18, v23
	v_cmp_ne_u32_e32 vcc, 0, v34
	s_and_b64 vcc, s[94:95], vcc
	v_mov_b32 v35, 0
	v_cndmask_b32_e32 v34, v236, v222, vcc
	v_sub_f32_e32 v34, v35, v34
	v_mov_b32_e32 v35, v34
	v_mov_b64_e32 v[36:37], v[34:35]
	v_mov_b64_e32 v[38:39], v[34:35]
	v_mov_b64_e32 v[40:41], v[34:35]
	v_mov_b64_e32 v[42:43], v[34:35]
	v_mov_b64_e32 v[44:45], v[34:35]
	v_mov_b64_e32 v[46:47], v[34:35]
	v_mov_b64_e32 v[48:49], v[34:35]
	s_nop 1
	v_mfma_f32_32x32x16_bf16 v[34:49], v[178:181], v[238:241], v[34:49]
	v_mfma_f32_32x32x16_bf16 v[34:49], v[174:177], v[242:245], v[34:49]
	v_mfma_f32_32x32x16_bf16 v[34:49], v[170:173], v[246:249], v[34:49]
	v_mfma_f32_32x32x16_bf16 v[34:49], v[166:169], v[250:253], v[34:49]
	v_exp_f32_e32 v82, v82
	v_exp_f32_e32 v83, v83
	v_exp_f32_e32 v84, v84
	v_exp_f32_e32 v85, v85
	v_exp_f32_e32 v86, v86
	v_exp_f32_e32 v87, v87
	v_exp_f32_e32 v88, v88
	v_exp_f32_e32 v89, v89
	v_exp_f32_e32 v90, v90
	v_exp_f32_e32 v91, v91
	v_add_f32_e32 v221, v221, v82
	v_exp_f32_e32 v92, v92
	v_exp_f32_e32 v34, v34
	v_add_f32_e32 v221, v83, v221
	v_exp_f32_e32 v35, v35
	v_exp_f32_e32 v93, v93
	v_exp_f32_e32 v36, v36
	v_add_f32_e32 v221, v84, v221
	v_exp_f32_e32 v37, v37
	v_exp_f32_e32 v94, v94
	v_exp_f32_e32 v38, v38
	v_add_f32_e32 v221, v85, v221
	v_exp_f32_e32 v39, v39
	v_exp_f32_e32 v95, v95
	v_exp_f32_e32 v40, v40
	v_add_f32_e32 v221, v86, v221
	v_exp_f32_e32 v41, v41
	v_cvt_pk_bf16_f32 v82, v82, v83
	v_exp_f32_e32 v42, v42
	v_cvt_pk_bf16_f32 v83, v84, v85
	v_exp_f32_e32 v43, v43
	v_cvt_pk_bf16_f32 v84, v86, v87
	v_add_f32_e32 v28, v28, v34
	v_cvt_pk_bf16_f32 v85, v88, v89
	v_exp_f32_e32 v44, v44
	v_add_f32_e32 v221, v87, v221
	v_add_f32_e32 v28, v35, v28
	v_mfma_f32_32x32x16_bf16 v[66:81], v[134:137], v[82:85], 0
	v_exp_f32_e32 v45, v45
	v_add_f32_e32 v221, v88, v221
	v_add_f32_e32 v28, v36, v28
	v_exp_f32_e32 v86, v96
	v_exp_f32_e32 v46, v46
	v_add_f32_e32 v221, v89, v221
	v_add_f32_e32 v28, v37, v28
	v_mov_b32_e32 v87, v95
	v_exp_f32_e32 v47, v47
	v_mfma_f32_32x32x16_bf16 v[50:65], v[130:133], v[82:85], 0
	v_add_f32_e32 v28, v38, v28
	v_exp_f32_e32 v88, v97
	v_cvt_pk_bf16_f32 v34, v34, v35
	v_cvt_pk_bf16_f32 v82, v90, v91
	v_cvt_pk_bf16_f32 v35, v36, v37
	v_cvt_pk_bf16_f32 v83, v92, v93
	v_cvt_pk_bf16_f32 v36, v38, v39
	v_cvt_pk_bf16_f32 v84, v94, v87
	v_cvt_pk_bf16_f32 v37, v40, v41
	v_cvt_pk_bf16_f32 v85, v86, v88
	v_add_f32_e32 v28, v39, v28
	v_add_f32_e32 v221, v90, v221
	v_mfma_f32_32x32x16_bf16 v[66:81], v[146:149], v[34:37], v[66:81]
	v_add_f32_e32 v89, v91, v221
	v_add_f32_e32 v28, v40, v28
	v_mfma_f32_32x32x16_bf16 v[66:81], v[118:121], v[82:85], v[66:81]
	v_exp_f32_e32 v38, v48
	v_add_f32_e32 v89, v92, v89
	v_add_f32_e32 v28, v41, v28
	v_add_f32_e32 v89, v93, v89
	v_mov_b32_e32 v39, v47
	v_add_f32_e32 v89, v94, v89
	v_mfma_f32_32x32x16_bf16 v[50:65], v[142:145], v[34:37], v[50:65]
	v_add_f32_e32 v87, v87, v89
	v_exp_f32_e32 v40, v49
	v_add_f32_e32 v86, v86, v87
	v_cvt_pk_bf16_f32 v34, v42, v43
	v_add_f32_e32 v221, v88, v86
	v_cvt_pk_bf16_f32 v35, v44, v45
	v_mfma_f32_32x32x16_bf16 v[50:65], v[102:105], v[82:85], v[50:65]
	v_cvt_pk_bf16_f32 v36, v46, v39
	v_cvt_pk_bf16_f32 v37, v38, v40
	v_add_f32_e32 v28, v42, v28
	v_add_f32_e32 v41, v43, v28
	v_mfma_f32_32x32x16_bf16 v[66:81], v[126:129], v[34:37], v[66:81]
	v_add_f32_e32 v41, v44, v41
	v_add_f32_e32 v41, v45, v41
	v_add_f32_e32 v41, v46, v41
	v_add_f32_e32 v39, v39, v41
	v_add_f32_e32 v38, v38, v39
	v_add_f32_e32 v28, v40, v38
	v_mfma_f32_32x32x16_bf16 v[50:65], v[114:117], v[34:37], v[50:65]
	v_add_f32_e32 v221, v221, v28
	s_cmp_lg_u32 s85, s86
	s_cbranch_scc1 .Lq_nl1_k1p1
	s_min_u32 s14, s87, 63
	s_nop 3
	v_readlane_b32 s30, v33, s14
	s_and_b32 s30, s30, 0xff
	s_lshl_b32 s30, s30, 13
	s_or_b32 s30, s30, 0x1000
	s_add_u32 s64, s11, s30
	s_addc_u32 s65, s12, 0
	s_add_u32 s66, s8, s30
	s_addc_u32 s67, s9, 0
	global_load_dwordx4 v[194:197], v2, s[64:65]
	global_load_dwordx4 v[190:193], v2, s[64:65] offset:1024
	global_load_dwordx4 v[186:189], v2, s[64:65] offset:2048
	global_load_dwordx4 v[182:185], v2, s[64:65] offset:3072
	global_load_dwordx4 v[134:137], v2, s[66:67]
	global_load_dwordx4 v[130:133], v2, s[66:67] offset:1024
	global_load_dwordx4 v[118:121], v2, s[66:67] offset:2048
	global_load_dwordx4 v[102:105], v2, s[66:67] offset:3072
	s_min_u32 s14, s88, 63
	s_nop 3
	v_readlane_b32 s30, v33, s14
	s_and_b32 s30, s30, 0xff
	s_lshl_b32 s30, s30, 13
	s_add_u32 s64, s11, s30
	s_addc_u32 s65, s12, 0
	s_add_u32 s66, s8, s30
	s_addc_u32 s67, s9, 0
	global_load_dwordx4 v[178:181], v2, s[64:65]
	global_load_dwordx4 v[174:177], v2, s[64:65] offset:1024
	global_load_dwordx4 v[170:173], v2, s[64:65] offset:2048
	global_load_dwordx4 v[166:169], v2, s[64:65] offset:3072
	global_load_dwordx4 v[146:149], v2, s[66:67]
	global_load_dwordx4 v[142:145], v2, s[66:67] offset:1024
	global_load_dwordx4 v[126:129], v2, s[66:67] offset:2048
	global_load_dwordx4 v[114:117], v2, s[66:67] offset:3072

.Lq_wd_k2p0:
	v_bfe_u32 v28, s57, v18, 6
	v_lshl_add_u32 v218, s99, 6, v28
	v_mad_u32_u24 v21, v28, s82, v19
	v_mad_u32_u24 v32, v28, s82, v31
	v_and_b32_e32 v29, s18, v23
	v_cmp_ne_u32_e64 s[54:55], 0, v29
	s_and_b64 s[54:55], s[54:55], s[94:95]
	s_min_u32 s14, s85, 63
	s_nop 3
	v_readlane_b32 s30, v26, s14
	v_readlane_b32 s31, v27, s14
	s_nop 1
	v_bfe_u32 v28, s31, v18, 6
	v_lshl_add_u32 v29, s99, 6, v28
	v_mad_u32_u24 v29, v29, s47, v20
	global_load_dwordx4 v[238:241], v29, s[20:21]
	global_load_dwordx4 v[242:245], v29, s[20:21] offset:32
	global_load_dwordx4 v[246:249], v29, s[20:21] offset:64
	global_load_dwordx4 v[250:253], v29, s[20:21] offset:96
	s_lshl_b32 s0, s100, 6
	v_or_b32_e32 v237, s0, v206
	v_mov_b32_e32 v221, 0
	s_cmp_lg_u32 s100, s99
	s_cbranch_scc1 .Lq_s0n_k2p0
	v_and_b32_e32 v82, s18, v23
	v_cmp_ne_u32_e32 vcc, 0, v82
	s_and_b64 vcc, s[94:95], vcc
	v_mov_b32 v83, 0
	v_or_b32_e32 v16, 2, v237
	v_cndmask_b32_e32 v82, v236, v222, vcc
	v_sub_f32_e32 v82, v83, v82
	v_mov_b32_e32 v83, v82
	v_mov_b64_e32 v[84:85], v[82:83]
	v_mov_b64_e32 v[86:87], v[82:83]
	v_mov_b64_e32 v[88:89], v[82:83]
	v_mov_b64_e32 v[90:91], v[82:83]
	v_mov_b64_e32 v[92:93], v[82:83]
	v_mov_b64_e32 v[94:95], v[82:83]
	v_mov_b64_e32 v[96:97], v[82:83]
	v_cmp_le_i32_e32 vcc, v237, v218
	v_or_b32_e32 v17, 3, v237
	v_mfma_f32_32x32x16_bf16 v[82:97], v[162:165], v[4:7], v[82:97]
	v_or_b32_e32 v30, 8, v237
	v_mfma_f32_32x32x16_bf16 v[82:97], v[154:157], v[8:11], v[82:97]
	v_mfma_f32_32x32x16_bf16 v[82:97], v[150:153], v[12:15], v[82:97]
	v_mfma_f32_32x32x16_bf16 v[82:97], v[158:161], v[98:101], v[82:97]
	s_nop 11
	v_exp_f32_e32 v82, v82
	v_exp_f32_e32 v83, v83
	v_exp_f32_e32 v84, v84
	v_exp_f32_e32 v85, v85
	v_exp_f32_e32 v86, v86
	v_cndmask_b32_e32 v82, 0, v82, vcc
	v_cmp_lt_i32_e32 vcc, v237, v218
	v_exp_f32_e32 v87, v87
	v_exp_f32_e32 v88, v88
	v_cndmask_b32_e32 v83, 0, v83, vcc
	v_cmp_le_i32_e32 vcc, v16, v218
	v_or_b32_e32 v16, 9, v237
	v_exp_f32_e32 v89, v89
	v_cndmask_b32_e32 v84, 0, v84, vcc
	v_cmp_le_i32_e32 vcc, v17, v218
	v_exp_f32_e32 v90, v90
	v_exp_f32_e32 v91, v91
	v_cndmask_b32_e32 v85, 0, v85, vcc
	v_cmp_le_i32_e32 vcc, v30, v218
	v_add_f32_e32 v221, v221, v82
	v_exp_f32_e32 v92, v92
	v_cndmask_b32_e32 v86, 0, v86, vcc
	v_cmp_le_i32_e32 vcc, v16, v218
	v_or_b32_e32 v16, 10, v237
	v_add_f32_e32 v221, v83, v221
	v_cndmask_b32_e32 v87, 0, v87, vcc
	v_cmp_le_i32_e32 vcc, v16, v218
	v_or_b32_e32 v16, 11, v237
	v_exp_f32_e32 v93, v93
	v_cndmask_b32_e32 v88, 0, v88, vcc
	v_cmp_le_i32_e32 vcc, v16, v218
	v_or_b32_e32 v16, 16, v237
	v_add_f32_e32 v221, v84, v221
	v_cndmask_b32_e32 v89, 0, v89, vcc
	v_cmp_le_i32_e32 vcc, v16, v218
	v_or_b32_e32 v16, 17, v237
	v_exp_f32_e32 v94, v94
	v_cndmask_b32_e32 v90, 0, v90, vcc
	v_cmp_le_i32_e32 vcc, v16, v218
	v_or_b32_e32 v16, 18, v237
	v_add_f32_e32 v221, v85, v221
	v_cndmask_b32_e32 v91, 0, v91, vcc
	v_cmp_le_i32_e32 vcc, v16, v218
	v_or_b32_e32 v16, 19, v237
	v_exp_f32_e32 v95, v95
	v_add_f32_e32 v221, v86, v221
	v_cndmask_b32_e32 v92, 0, v92, vcc
	v_cmp_le_i32_e32 vcc, v16, v218
	v_or_b32_e32 v16, 24, v237
	v_cvt_pk_bf16_f32 v82, v82, v83
	v_cvt_pk_bf16_f32 v83, v84, v85
	v_cvt_pk_bf16_f32 v84, v86, v87
	v_cvt_pk_bf16_f32 v85, v88, v89
	v_add_f32_e32 v221, v87, v221
	v_cndmask_b32_e32 v93, 0, v93, vcc
	v_cmp_le_i32_e32 vcc, v16, v218
	v_or_b32_e32 v16, 25, v237
	v_mfma_f32_32x32x16_bf16 v[66:81], v[138:141], v[82:85], 0
	v_add_f32_e32 v221, v88, v221
	v_cndmask_b32_e32 v94, 0, v94, vcc
	v_exp_f32_e32 v86, v96
	v_cmp_le_i32_e32 vcc, v16, v218
	v_or_b32_e32 v88, 26, v237
	v_add_f32_e32 v221, v89, v221
	v_cndmask_b32_e32 v87, 0, v95, vcc
	v_mfma_f32_32x32x16_bf16 v[50:65], v[122:125], v[82:85], 0
	v_cmp_le_i32_e32 vcc, v88, v218
	v_exp_f32_e32 v88, v97
	v_or_b32_e32 v82, 27, v237
	v_cndmask_b32_e32 v86, 0, v86, vcc
	v_cmp_le_i32_e32 vcc, v82, v218
	v_cvt_pk_bf16_f32 v82, v90, v91
	v_cvt_pk_bf16_f32 v83, v92, v93
	v_cndmask_b32_e32 v88, 0, v88, vcc
	v_cvt_pk_bf16_f32 v84, v94, v87
	v_cvt_pk_bf16_f32 v85, v86, v88
	v_add_f32_e32 v221, v90, v221
	v_add_f32_e32 v89, v91, v221
	v_mfma_f32_32x32x16_bf16 v[66:81], v[110:113], v[82:85], v[66:81]
	v_add_f32_e32 v89, v92, v89
	v_add_f32_e32 v89, v93, v89
	v_add_f32_e32 v89, v94, v89
	v_add_f32_e32 v87, v87, v89
	v_add_f32_e32 v86, v86, v87
	v_add_f32_e32 v221, v88, v86
	v_mfma_f32_32x32x16_bf16 v[50:65], v[106:109], v[82:85], v[50:65]
	s_cmp_lg_u32 s85, s86
	s_cbranch_scc1 .Lq_nl0_k2p0
	s_min_u32 s14, s87, 63
	s_nop 3
	v_readlane_b32 s30, v33, s14
	s_and_b32 s30, s30, 0xff
	s_lshl_b32 s30, s30, 13
	s_or_b32 s30, s30, 0x1000
	s_add_u32 s64, s11, s30
	s_addc_u32 s65, s12, 0
	s_add_u32 s66, s8, s30
	s_addc_u32 s67, s9, 0
	global_load_dwordx4 v[162:165], v2, s[64:65]
	global_load_dwordx4 v[154:157], v2, s[64:65] offset:1024
	global_load_dwordx4 v[150:153], v2, s[64:65] offset:2048
	global_load_dwordx4 v[158:161], v2, s[64:65] offset:3072
	global_load_dwordx4 v[138:141], v2, s[66:67]
	global_load_dwordx4 v[122:125], v2, s[66:67] offset:1024
	global_load_dwordx4 v[110:113], v2, s[66:67] offset:2048
	global_load_dwordx4 v[106:109], v2, s[66:67] offset:3072
	s_waitcnt vmcnt(20)
	s_branch .Lq_nl0d_k2p0

.Lq_nl0d_k2p0:
	s_lshl_b32 s0, s100, 6
	s_or_b32 s0, s0, 32
	v_or_b32_e32 v237, s0, v206
	v_and_b32_e32 v82, s18, v23
	v_cmp_ne_u32_e32 vcc, 0, v82
	s_and_b64 vcc, s[94:95], vcc
	v_mov_b32 v83, 0
	v_or_b32_e32 v16, 2, v237
	v_cndmask_b32_e32 v82, v236, v222, vcc
	v_sub_f32_e32 v82, v83, v82
	v_mov_b32_e32 v83, v82
	v_mov_b64_e32 v[84:85], v[82:83]
	v_mov_b64_e32 v[86:87], v[82:83]
	v_mov_b64_e32 v[88:89], v[82:83]
	v_mov_b64_e32 v[90:91], v[82:83]
	v_mov_b64_e32 v[92:93], v[82:83]
	v_mov_b64_e32 v[94:95], v[82:83]
	v_mov_b64_e32 v[96:97], v[82:83]
	v_cmp_le_i32_e32 vcc, v237, v218
	v_or_b32_e32 v17, 3, v237
	v_mfma_f32_32x32x16_bf16 v[82:97], v[194:197], v[4:7], v[82:97]
	v_or_b32_e32 v30, 8, v237
	v_mfma_f32_32x32x16_bf16 v[82:97], v[190:193], v[8:11], v[82:97]
	v_mfma_f32_32x32x16_bf16 v[82:97], v[186:189], v[12:15], v[82:97]
	v_mfma_f32_32x32x16_bf16 v[82:97], v[182:185], v[98:101], v[82:97]
	s_nop 11
	v_exp_f32_e32 v82, v82
	v_exp_f32_e32 v83, v83
	v_exp_f32_e32 v84, v84
	v_exp_f32_e32 v85, v85
	v_exp_f32_e32 v86, v86
	v_cndmask_b32_e32 v82, 0, v82, vcc
	v_cmp_lt_i32_e32 vcc, v237, v218
	v_exp_f32_e32 v87, v87
	v_exp_f32_e32 v88, v88
	v_cndmask_b32_e32 v83, 0, v83, vcc
	v_cmp_le_i32_e32 vcc, v16, v218
	v_or_b32_e32 v16, 9, v237
	v_exp_f32_e32 v89, v89
	v_cndmask_b32_e32 v84, 0, v84, vcc
	v_cmp_le_i32_e32 vcc, v17, v218
	v_exp_f32_e32 v90, v90
	v_exp_f32_e32 v91, v91
	v_cndmask_b32_e32 v85, 0, v85, vcc
	v_cmp_le_i32_e32 vcc, v30, v218
	v_add_f32_e32 v221, v221, v82
	v_exp_f32_e32 v92, v92
	v_cndmask_b32_e32 v86, 0, v86, vcc
	v_cmp_le_i32_e32 vcc, v16, v218
	v_or_b32_e32 v16, 10, v237
	v_add_f32_e32 v221, v83, v221
	v_cndmask_b32_e32 v87, 0, v87, vcc
	v_cmp_le_i32_e32 vcc, v16, v218
	v_or_b32_e32 v16, 11, v237
	v_exp_f32_e32 v93, v93
	v_cndmask_b32_e32 v88, 0, v88, vcc
	v_cmp_le_i32_e32 vcc, v16, v218
	v_or_b32_e32 v16, 16, v237
	v_add_f32_e32 v221, v84, v221
	v_cndmask_b32_e32 v89, 0, v89, vcc
	v_cmp_le_i32_e32 vcc, v16, v218
	v_or_b32_e32 v16, 17, v237
	v_exp_f32_e32 v94, v94
	v_cndmask_b32_e32 v90, 0, v90, vcc
	v_cmp_le_i32_e32 vcc, v16, v218
	v_or_b32_e32 v16, 18, v237
	v_add_f32_e32 v221, v85, v221
	v_cndmask_b32_e32 v91, 0, v91, vcc
	v_cmp_le_i32_e32 vcc, v16, v218
	v_or_b32_e32 v16, 19, v237
	v_exp_f32_e32 v95, v95
	v_add_f32_e32 v221, v86, v221
	v_cndmask_b32_e32 v92, 0, v92, vcc
	v_cmp_le_i32_e32 vcc, v16, v218
	v_or_b32_e32 v16, 24, v237
	v_cvt_pk_bf16_f32 v82, v82, v83
	v_cvt_pk_bf16_f32 v83, v84, v85
	v_cvt_pk_bf16_f32 v84, v86, v87
	v_cvt_pk_bf16_f32 v85, v88, v89
	v_add_f32_e32 v221, v87, v221
	v_cndmask_b32_e32 v93, 0, v93, vcc
	v_cmp_le_i32_e32 vcc, v16, v218
	v_or_b32_e32 v16, 25, v237
	v_mfma_f32_32x32x16_bf16 v[66:81], v[134:137], v[82:85], v[66:81]
	v_add_f32_e32 v221, v88, v221
	v_cndmask_b32_e32 v94, 0, v94, vcc
	v_exp_f32_e32 v86, v96
	v_cmp_le_i32_e32 vcc, v16, v218
	v_or_b32_e32 v88, 26, v237
	v_add_f32_e32 v221, v89, v221
	v_cndmask_b32_e32 v87, 0, v95, vcc
	v_mfma_f32_32x32x16_bf16 v[50:65], v[130:133], v[82:85], v[50:65]
	v_cmp_le_i32_e32 vcc, v88, v218
	v_exp_f32_e32 v88, v97
	v_or_b32_e32 v82, 27, v237
	v_cndmask_b32_e32 v86, 0, v86, vcc
	v_cmp_le_i32_e32 vcc, v82, v218
	v_cvt_pk_bf16_f32 v82, v90, v91
	v_cvt_pk_bf16_f32 v83, v92, v93
	v_cndmask_b32_e32 v88, 0, v88, vcc
	v_cvt_pk_bf16_f32 v84, v94, v87
	v_cvt_pk_bf16_f32 v85, v86, v88
	v_add_f32_e32 v221, v90, v221
	v_add_f32_e32 v89, v91, v221
	v_mfma_f32_32x32x16_bf16 v[66:81], v[118:121], v[82:85], v[66:81]
	v_add_f32_e32 v89, v92, v89
	v_add_f32_e32 v89, v93, v89
	v_add_f32_e32 v89, v94, v89
	v_add_f32_e32 v87, v87, v89
	v_add_f32_e32 v86, v86, v87
	v_add_f32_e32 v221, v88, v86
	v_mfma_f32_32x32x16_bf16 v[50:65], v[102:105], v[82:85], v[50:65]
	s_cmp_lg_u32 s85, s86
	s_cbranch_scc1 .Lq_nl1_k2p0
	s_min_u32 s14, s88, 63
	s_nop 3
	v_readlane_b32 s30, v33, s14
	s_and_b32 s30, s30, 0xff
	s_lshl_b32 s30, s30, 13
	s_add_u32 s64, s11, s30
	s_addc_u32 s65, s12, 0
	s_add_u32 s66, s8, s30
	s_addc_u32 s67, s9, 0
	global_load_dwordx4 v[194:197], v2, s[64:65]
	global_load_dwordx4 v[190:193], v2, s[64:65] offset:1024
	global_load_dwordx4 v[186:189], v2, s[64:65] offset:2048
	global_load_dwordx4 v[182:185], v2, s[64:65] offset:3072
	global_load_dwordx4 v[134:137], v2, s[66:67]
	global_load_dwordx4 v[130:133], v2, s[66:67] offset:1024
	global_load_dwordx4 v[118:121], v2, s[66:67] offset:2048
	global_load_dwordx4 v[102:105], v2, s[66:67] offset:3072
	s_branch .Lq_nl1_k2p0
.Lq_s0n_k2p0:
	v_and_b32_e32 v82, s18, v23
	v_cmp_ne_u32_e32 vcc, 0, v82
	s_and_b64 vcc, s[94:95], vcc
	v_mov_b32 v83, 0
	v_cndmask_b32_e32 v82, v236, v222, vcc
	v_sub_f32_e32 v82, v83, v82
	v_mov_b32_e32 v83, v82
	v_mov_b64_e32 v[84:85], v[82:83]
	v_mov_b64_e32 v[86:87], v[82:83]
	v_mov_b64_e32 v[88:89], v[82:83]
	v_mov_b64_e32 v[90:91], v[82:83]
	v_mov_b64_e32 v[92:93], v[82:83]
	v_mov_b64_e32 v[94:95], v[82:83]
	v_mov_b64_e32 v[96:97], v[82:83]
	s_nop 1
	v_mfma_f32_32x32x16_bf16 v[82:97], v[162:165], v[4:7], v[82:97]
	v_mfma_f32_32x32x16_bf16 v[82:97], v[154:157], v[8:11], v[82:97]
	v_mfma_f32_32x32x16_bf16 v[82:97], v[150:153], v[12:15], v[82:97]
	v_mfma_f32_32x32x16_bf16 v[82:97], v[158:161], v[98:101], v[82:97]
	s_waitcnt vmcnt(12)
	v_mov_b32_e32 v28, 0
	v_and_b32_e32 v34, s18, v23
	v_cmp_ne_u32_e32 vcc, 0, v34
	s_and_b64 vcc, s[94:95], vcc
	v_mov_b32 v35, 0
	v_cndmask_b32_e32 v34, v236, v222, vcc
	v_sub_f32_e32 v34, v35, v34
	v_mov_b32_e32 v35, v34
	v_mov_b64_e32 v[36:37], v[34:35]
	v_mov_b64_e32 v[38:39], v[34:35]
	v_mov_b64_e32 v[40:41], v[34:35]
	v_mov_b64_e32 v[42:43], v[34:35]
	v_mov_b64_e32 v[44:45], v[34:35]
	v_mov_b64_e32 v[46:47], v[34:35]
	v_mov_b64_e32 v[48:49], v[34:35]
	s_nop 1
	v_mfma_f32_32x32x16_bf16 v[34:49], v[194:197], v[4:7], v[34:49]
	v_mfma_f32_32x32x16_bf16 v[34:49], v[190:193], v[8:11], v[34:49]
	v_mfma_f32_32x32x16_bf16 v[34:49], v[186:189], v[12:15], v[34:49]
	v_mfma_f32_32x32x16_bf16 v[34:49], v[182:185], v[98:101], v[34:49]
	v_exp_f32_e32 v82, v82
	v_exp_f32_e32 v83, v83
	v_exp_f32_e32 v84, v84
	v_exp_f32_e32 v85, v85
	v_exp_f32_e32 v86, v86
	v_exp_f32_e32 v87, v87
	v_exp_f32_e32 v88, v88
	v_exp_f32_e32 v89, v89
	v_exp_f32_e32 v90, v90
	v_exp_f32_e32 v91, v91
	v_add_f32_e32 v221, v221, v82
	v_exp_f32_e32 v92, v92
	v_exp_f32_e32 v34, v34
	v_add_f32_e32 v221, v83, v221
	v_exp_f32_e32 v35, v35
	v_exp_f32_e32 v93, v93
	v_exp_f32_e32 v36, v36
	v_add_f32_e32 v221, v84, v221
	v_exp_f32_e32 v37, v37
	v_exp_f32_e32 v94, v94
	v_exp_f32_e32 v38, v38
	v_add_f32_e32 v221, v85, v221
	v_exp_f32_e32 v39, v39
	v_exp_f32_e32 v95, v95
	v_exp_f32_e32 v40, v40
	v_add_f32_e32 v221, v86, v221
	v_exp_f32_e32 v41, v41
	v_cvt_pk_bf16_f32 v82, v82, v83
	v_exp_f32_e32 v42, v42
	v_cvt_pk_bf16_f32 v83, v84, v85
	v_exp_f32_e32 v43, v43
	v_cvt_pk_bf16_f32 v84, v86, v87
	v_add_f32_e32 v28, v28, v34
	v_cvt_pk_bf16_f32 v85, v88, v89
	v_exp_f32_e32 v44, v44
	v_add_f32_e32 v221, v87, v221
	v_add_f32_e32 v28, v35, v28
	v_mfma_f32_32x32x16_bf16 v[66:81], v[138:141], v[82:85], 0
	v_exp_f32_e32 v45, v45
	v_add_f32_e32 v221, v88, v221
	v_add_f32_e32 v28, v36, v28
	v_exp_f32_e32 v86, v96
	v_exp_f32_e32 v46, v46
	v_add_f32_e32 v221, v89, v221
	v_add_f32_e32 v28, v37, v28
	v_mov_b32_e32 v87, v95
	v_exp_f32_e32 v47, v47
	v_mfma_f32_32x32x16_bf16 v[50:65], v[122:125], v[82:85], 0
	v_add_f32_e32 v28, v38, v28
	v_exp_f32_e32 v88, v97
	v_cvt_pk_bf16_f32 v34, v34, v35
	v_cvt_pk_bf16_f32 v82, v90, v91
	v_cvt_pk_bf16_f32 v35, v36, v37
	v_cvt_pk_bf16_f32 v83, v92, v93
	v_cvt_pk_bf16_f32 v36, v38, v39
	v_cvt_pk_bf16_f32 v84, v94, v87
	v_cvt_pk_bf16_f32 v37, v40, v41
	v_cvt_pk_bf16_f32 v85, v86, v88
	v_add_f32_e32 v28, v39, v28
	v_add_f32_e32 v221, v90, v221
	v_mfma_f32_32x32x16_bf16 v[66:81], v[134:137], v[34:37], v[66:81]
	v_add_f32_e32 v89, v91, v221
	v_add_f32_e32 v28, v40, v28
	v_mfma_f32_32x32x16_bf16 v[66:81], v[110:113], v[82:85], v[66:81]
	v_exp_f32_e32 v38, v48
	v_add_f32_e32 v89, v92, v89
	v_add_f32_e32 v28, v41, v28
	v_add_f32_e32 v89, v93, v89
	v_mov_b32_e32 v39, v47
	v_add_f32_e32 v89, v94, v89
	v_mfma_f32_32x32x16_bf16 v[50:65], v[130:133], v[34:37], v[50:65]
	v_add_f32_e32 v87, v87, v89
	v_exp_f32_e32 v40, v49
	v_add_f32_e32 v86, v86, v87
	v_cvt_pk_bf16_f32 v34, v42, v43
	v_add_f32_e32 v221, v88, v86
	v_cvt_pk_bf16_f32 v35, v44, v45
	v_mfma_f32_32x32x16_bf16 v[50:65], v[106:109], v[82:85], v[50:65]
	v_cvt_pk_bf16_f32 v36, v46, v39
	v_cvt_pk_bf16_f32 v37, v38, v40
	v_add_f32_e32 v28, v42, v28
	v_add_f32_e32 v41, v43, v28
	v_mfma_f32_32x32x16_bf16 v[66:81], v[118:121], v[34:37], v[66:81]
	v_add_f32_e32 v41, v44, v41
	v_add_f32_e32 v41, v45, v41
	v_add_f32_e32 v41, v46, v41
	v_add_f32_e32 v39, v39, v41
	v_add_f32_e32 v38, v38, v39
	v_add_f32_e32 v28, v40, v38
	v_mfma_f32_32x32x16_bf16 v[50:65], v[102:105], v[34:37], v[50:65]
	v_add_f32_e32 v221, v221, v28
	s_cmp_lg_u32 s85, s86
	s_cbranch_scc1 .Lq_nl1_k2p0
	s_min_u32 s14, s87, 63
	s_nop 3
	v_readlane_b32 s30, v33, s14
	s_and_b32 s30, s30, 0xff
	s_lshl_b32 s30, s30, 13
	s_or_b32 s30, s30, 0x1000
	s_add_u32 s64, s11, s30
	s_addc_u32 s65, s12, 0
	s_add_u32 s66, s8, s30
	s_addc_u32 s67, s9, 0
	global_load_dwordx4 v[162:165], v2, s[64:65]
	global_load_dwordx4 v[154:157], v2, s[64:65] offset:1024
	global_load_dwordx4 v[150:153], v2, s[64:65] offset:2048
	global_load_dwordx4 v[158:161], v2, s[64:65] offset:3072
	global_load_dwordx4 v[138:141], v2, s[66:67]
	global_load_dwordx4 v[122:125], v2, s[66:67] offset:1024
	global_load_dwordx4 v[110:113], v2, s[66:67] offset:2048
	global_load_dwordx4 v[106:109], v2, s[66:67] offset:3072
	s_min_u32 s14, s88, 63
	s_nop 3
	v_readlane_b32 s30, v33, s14
	s_and_b32 s30, s30, 0xff
	s_lshl_b32 s30, s30, 13
	s_add_u32 s64, s11, s30
	s_addc_u32 s65, s12, 0
	s_add_u32 s66, s8, s30
	s_addc_u32 s67, s9, 0
	global_load_dwordx4 v[194:197], v2, s[64:65]
	global_load_dwordx4 v[190:193], v2, s[64:65] offset:1024
	global_load_dwordx4 v[186:189], v2, s[64:65] offset:2048
	global_load_dwordx4 v[182:185], v2, s[64:65] offset:3072
	global_load_dwordx4 v[134:137], v2, s[66:67]
	global_load_dwordx4 v[130:133], v2, s[66:67] offset:1024
	global_load_dwordx4 v[118:121], v2, s[66:67] offset:2048
	global_load_dwordx4 v[102:105], v2, s[66:67] offset:3072

.Lq_wd_k2p1:
	v_bfe_u32 v28, s57, v18, 6
	v_lshl_add_u32 v218, s99, 6, v28
	v_mad_u32_u24 v21, v28, s82, v19
	v_mad_u32_u24 v32, v28, s82, v31
	v_and_b32_e32 v29, s18, v23
	v_cmp_ne_u32_e64 s[54:55], 0, v29
	s_and_b64 s[54:55], s[54:55], s[94:95]
	s_min_u32 s14, s85, 63
	s_nop 3
	v_readlane_b32 s30, v26, s14
	v_readlane_b32 s31, v27, s14
	s_nop 1
	v_bfe_u32 v28, s31, v18, 6
	v_lshl_add_u32 v29, s99, 6, v28
	v_mad_u32_u24 v29, v29, s47, v20
	global_load_dwordx4 v[4:7], v29, s[20:21]
	global_load_dwordx4 v[8:11], v29, s[20:21] offset:32
	global_load_dwordx4 v[12:15], v29, s[20:21] offset:64
	global_load_dwordx4 v[98:101], v29, s[20:21] offset:96
	s_lshl_b32 s0, s100, 6
	v_or_b32_e32 v237, s0, v206
	v_mov_b32_e32 v221, 0
	s_cmp_lg_u32 s100, s99
	s_cbranch_scc1 .Lq_s0n_k2p1
	v_and_b32_e32 v82, s18, v23
	v_cmp_ne_u32_e32 vcc, 0, v82
	s_and_b64 vcc, s[94:95], vcc
	v_mov_b32 v83, 0
	v_or_b32_e32 v16, 2, v237
	v_cndmask_b32_e32 v82, v236, v222, vcc
	v_sub_f32_e32 v82, v83, v82
	v_mov_b32_e32 v83, v82
	v_mov_b64_e32 v[84:85], v[82:83]
	v_mov_b64_e32 v[86:87], v[82:83]
	v_mov_b64_e32 v[88:89], v[82:83]
	v_mov_b64_e32 v[90:91], v[82:83]
	v_mov_b64_e32 v[92:93], v[82:83]
	v_mov_b64_e32 v[94:95], v[82:83]
	v_mov_b64_e32 v[96:97], v[82:83]
	v_cmp_le_i32_e32 vcc, v237, v218
	v_or_b32_e32 v17, 3, v237
	v_mfma_f32_32x32x16_bf16 v[82:97], v[162:165], v[238:241], v[82:97]
	v_or_b32_e32 v30, 8, v237
	v_mfma_f32_32x32x16_bf16 v[82:97], v[154:157], v[242:245], v[82:97]
	v_mfma_f32_32x32x16_bf16 v[82:97], v[150:153], v[246:249], v[82:97]
	v_mfma_f32_32x32x16_bf16 v[82:97], v[158:161], v[250:253], v[82:97]
	s_nop 11
	v_exp_f32_e32 v82, v82
	v_exp_f32_e32 v83, v83
	v_exp_f32_e32 v84, v84
	v_exp_f32_e32 v85, v85
	v_exp_f32_e32 v86, v86
	v_cndmask_b32_e32 v82, 0, v82, vcc
	v_cmp_lt_i32_e32 vcc, v237, v218
	v_exp_f32_e32 v87, v87
	v_exp_f32_e32 v88, v88
	v_cndmask_b32_e32 v83, 0, v83, vcc
	v_cmp_le_i32_e32 vcc, v16, v218
	v_or_b32_e32 v16, 9, v237
	v_exp_f32_e32 v89, v89
	v_cndmask_b32_e32 v84, 0, v84, vcc
	v_cmp_le_i32_e32 vcc, v17, v218
	v_exp_f32_e32 v90, v90
	v_exp_f32_e32 v91, v91
	v_cndmask_b32_e32 v85, 0, v85, vcc
	v_cmp_le_i32_e32 vcc, v30, v218
	v_add_f32_e32 v221, v221, v82
	v_exp_f32_e32 v92, v92
	v_cndmask_b32_e32 v86, 0, v86, vcc
	v_cmp_le_i32_e32 vcc, v16, v218
	v_or_b32_e32 v16, 10, v237
	v_add_f32_e32 v221, v83, v221
	v_cndmask_b32_e32 v87, 0, v87, vcc
	v_cmp_le_i32_e32 vcc, v16, v218
	v_or_b32_e32 v16, 11, v237
	v_exp_f32_e32 v93, v93
	v_cndmask_b32_e32 v88, 0, v88, vcc
	v_cmp_le_i32_e32 vcc, v16, v218
	v_or_b32_e32 v16, 16, v237
	v_add_f32_e32 v221, v84, v221
	v_cndmask_b32_e32 v89, 0, v89, vcc
	v_cmp_le_i32_e32 vcc, v16, v218
	v_or_b32_e32 v16, 17, v237
	v_exp_f32_e32 v94, v94
	v_cndmask_b32_e32 v90, 0, v90, vcc
	v_cmp_le_i32_e32 vcc, v16, v218
	v_or_b32_e32 v16, 18, v237
	v_add_f32_e32 v221, v85, v221
	v_cndmask_b32_e32 v91, 0, v91, vcc
	v_cmp_le_i32_e32 vcc, v16, v218
	v_or_b32_e32 v16, 19, v237
	v_exp_f32_e32 v95, v95
	v_add_f32_e32 v221, v86, v221
	v_cndmask_b32_e32 v92, 0, v92, vcc
	v_cmp_le_i32_e32 vcc, v16, v218
	v_or_b32_e32 v16, 24, v237
	v_cvt_pk_bf16_f32 v82, v82, v83
	v_cvt_pk_bf16_f32 v83, v84, v85
	v_cvt_pk_bf16_f32 v84, v86, v87
	v_cvt_pk_bf16_f32 v85, v88, v89
	v_add_f32_e32 v221, v87, v221
	v_cndmask_b32_e32 v93, 0, v93, vcc
	v_cmp_le_i32_e32 vcc, v16, v218
	v_or_b32_e32 v16, 25, v237
	v_mfma_f32_32x32x16_bf16 v[66:81], v[138:141], v[82:85], 0
	v_add_f32_e32 v221, v88, v221
	v_cndmask_b32_e32 v94, 0, v94, vcc
	v_exp_f32_e32 v86, v96
	v_cmp_le_i32_e32 vcc, v16, v218
	v_or_b32_e32 v88, 26, v237
	v_add_f32_e32 v221, v89, v221
	v_cndmask_b32_e32 v87, 0, v95, vcc
	v_mfma_f32_32x32x16_bf16 v[50:65], v[122:125], v[82:85], 0
	v_cmp_le_i32_e32 vcc, v88, v218
	v_exp_f32_e32 v88, v97
	v_or_b32_e32 v82, 27, v237
	v_cndmask_b32_e32 v86, 0, v86, vcc
	v_cmp_le_i32_e32 vcc, v82, v218
	v_cvt_pk_bf16_f32 v82, v90, v91
	v_cvt_pk_bf16_f32 v83, v92, v93
	v_cndmask_b32_e32 v88, 0, v88, vcc
	v_cvt_pk_bf16_f32 v84, v94, v87
	v_cvt_pk_bf16_f32 v85, v86, v88
	v_add_f32_e32 v221, v90, v221
	v_add_f32_e32 v89, v91, v221
	v_mfma_f32_32x32x16_bf16 v[66:81], v[110:113], v[82:85], v[66:81]
	v_add_f32_e32 v89, v92, v89
	v_add_f32_e32 v89, v93, v89
	v_add_f32_e32 v89, v94, v89
	v_add_f32_e32 v87, v87, v89
	v_add_f32_e32 v86, v86, v87
	v_add_f32_e32 v221, v88, v86
	v_mfma_f32_32x32x16_bf16 v[50:65], v[106:109], v[82:85], v[50:65]
	s_cmp_lg_u32 s85, s86
	s_cbranch_scc1 .Lq_nl0_k2p1
	s_min_u32 s14, s87, 63
	s_nop 3
	v_readlane_b32 s30, v33, s14
	s_and_b32 s30, s30, 0xff
	s_lshl_b32 s30, s30, 13
	s_or_b32 s30, s30, 0x1000
	s_add_u32 s64, s11, s30
	s_addc_u32 s65, s12, 0
	s_add_u32 s66, s8, s30
	s_addc_u32 s67, s9, 0
	global_load_dwordx4 v[162:165], v2, s[64:65]
	global_load_dwordx4 v[154:157], v2, s[64:65] offset:1024
	global_load_dwordx4 v[150:153], v2, s[64:65] offset:2048
	global_load_dwordx4 v[158:161], v2, s[64:65] offset:3072
	global_load_dwordx4 v[138:141], v2, s[66:67]
	global_load_dwordx4 v[122:125], v2, s[66:67] offset:1024
	global_load_dwordx4 v[110:113], v2, s[66:67] offset:2048
	global_load_dwordx4 v[106:109], v2, s[66:67] offset:3072
	s_waitcnt vmcnt(20)
	s_branch .Lq_nl0d_k2p1

.Lq_nl0d_k2p1:
	s_lshl_b32 s0, s100, 6
	s_or_b32 s0, s0, 32
	v_or_b32_e32 v237, s0, v206
	v_and_b32_e32 v82, s18, v23
	v_cmp_ne_u32_e32 vcc, 0, v82
	s_and_b64 vcc, s[94:95], vcc
	v_mov_b32 v83, 0
	v_or_b32_e32 v16, 2, v237
	v_cndmask_b32_e32 v82, v236, v222, vcc
	v_sub_f32_e32 v82, v83, v82
	v_mov_b32_e32 v83, v82
	v_mov_b64_e32 v[84:85], v[82:83]
	v_mov_b64_e32 v[86:87], v[82:83]
	v_mov_b64_e32 v[88:89], v[82:83]
	v_mov_b64_e32 v[90:91], v[82:83]
	v_mov_b64_e32 v[92:93], v[82:83]
	v_mov_b64_e32 v[94:95], v[82:83]
	v_mov_b64_e32 v[96:97], v[82:83]
	v_cmp_le_i32_e32 vcc, v237, v218
	v_or_b32_e32 v17, 3, v237
	v_mfma_f32_32x32x16_bf16 v[82:97], v[194:197], v[238:241], v[82:97]
	v_or_b32_e32 v30, 8, v237
	v_mfma_f32_32x32x16_bf16 v[82:97], v[190:193], v[242:245], v[82:97]
	v_mfma_f32_32x32x16_bf16 v[82:97], v[186:189], v[246:249], v[82:97]
	v_mfma_f32_32x32x16_bf16 v[82:97], v[182:185], v[250:253], v[82:97]
	s_nop 11
	v_exp_f32_e32 v82, v82
	v_exp_f32_e32 v83, v83
	v_exp_f32_e32 v84, v84
	v_exp_f32_e32 v85, v85
	v_exp_f32_e32 v86, v86
	v_cndmask_b32_e32 v82, 0, v82, vcc
	v_cmp_lt_i32_e32 vcc, v237, v218
	v_exp_f32_e32 v87, v87
	v_exp_f32_e32 v88, v88
	v_cndmask_b32_e32 v83, 0, v83, vcc
	v_cmp_le_i32_e32 vcc, v16, v218
	v_or_b32_e32 v16, 9, v237
	v_exp_f32_e32 v89, v89
	v_cndmask_b32_e32 v84, 0, v84, vcc
	v_cmp_le_i32_e32 vcc, v17, v218
	v_exp_f32_e32 v90, v90
	v_exp_f32_e32 v91, v91
	v_cndmask_b32_e32 v85, 0, v85, vcc
	v_cmp_le_i32_e32 vcc, v30, v218
	v_add_f32_e32 v221, v221, v82
	v_exp_f32_e32 v92, v92
	v_cndmask_b32_e32 v86, 0, v86, vcc
	v_cmp_le_i32_e32 vcc, v16, v218
	v_or_b32_e32 v16, 10, v237
	v_add_f32_e32 v221, v83, v221
	v_cndmask_b32_e32 v87, 0, v87, vcc
	v_cmp_le_i32_e32 vcc, v16, v218
	v_or_b32_e32 v16, 11, v237
	v_exp_f32_e32 v93, v93
	v_cndmask_b32_e32 v88, 0, v88, vcc
	v_cmp_le_i32_e32 vcc, v16, v218
	v_or_b32_e32 v16, 16, v237
	v_add_f32_e32 v221, v84, v221
	v_cndmask_b32_e32 v89, 0, v89, vcc
	v_cmp_le_i32_e32 vcc, v16, v218
	v_or_b32_e32 v16, 17, v237
	v_exp_f32_e32 v94, v94
	v_cndmask_b32_e32 v90, 0, v90, vcc
	v_cmp_le_i32_e32 vcc, v16, v218
	v_or_b32_e32 v16, 18, v237
	v_add_f32_e32 v221, v85, v221
	v_cndmask_b32_e32 v91, 0, v91, vcc
	v_cmp_le_i32_e32 vcc, v16, v218
	v_or_b32_e32 v16, 19, v237
	v_exp_f32_e32 v95, v95
	v_add_f32_e32 v221, v86, v221
	v_cndmask_b32_e32 v92, 0, v92, vcc
	v_cmp_le_i32_e32 vcc, v16, v218
	v_or_b32_e32 v16, 24, v237
	v_cvt_pk_bf16_f32 v82, v82, v83
	v_cvt_pk_bf16_f32 v83, v84, v85
	v_cvt_pk_bf16_f32 v84, v86, v87
	v_cvt_pk_bf16_f32 v85, v88, v89
	v_add_f32_e32 v221, v87, v221
	v_cndmask_b32_e32 v93, 0, v93, vcc
	v_cmp_le_i32_e32 vcc, v16, v218
	v_or_b32_e32 v16, 25, v237
	v_mfma_f32_32x32x16_bf16 v[66:81], v[134:137], v[82:85], v[66:81]
	v_add_f32_e32 v221, v88, v221
	v_cndmask_b32_e32 v94, 0, v94, vcc
	v_exp_f32_e32 v86, v96
	v_cmp_le_i32_e32 vcc, v16, v218
	v_or_b32_e32 v88, 26, v237
	v_add_f32_e32 v221, v89, v221
	v_cndmask_b32_e32 v87, 0, v95, vcc
	v_mfma_f32_32x32x16_bf16 v[50:65], v[130:133], v[82:85], v[50:65]
	v_cmp_le_i32_e32 vcc, v88, v218
	v_exp_f32_e32 v88, v97
	v_or_b32_e32 v82, 27, v237
	v_cndmask_b32_e32 v86, 0, v86, vcc
	v_cmp_le_i32_e32 vcc, v82, v218
	v_cvt_pk_bf16_f32 v82, v90, v91
	v_cvt_pk_bf16_f32 v83, v92, v93
	v_cndmask_b32_e32 v88, 0, v88, vcc
	v_cvt_pk_bf16_f32 v84, v94, v87
	v_cvt_pk_bf16_f32 v85, v86, v88
	v_add_f32_e32 v221, v90, v221
	v_add_f32_e32 v89, v91, v221
	v_mfma_f32_32x32x16_bf16 v[66:81], v[118:121], v[82:85], v[66:81]
	v_add_f32_e32 v89, v92, v89
	v_add_f32_e32 v89, v93, v89
	v_add_f32_e32 v89, v94, v89
	v_add_f32_e32 v87, v87, v89
	v_add_f32_e32 v86, v86, v87
	v_add_f32_e32 v221, v88, v86
	v_mfma_f32_32x32x16_bf16 v[50:65], v[102:105], v[82:85], v[50:65]
	s_cmp_lg_u32 s85, s86
	s_cbranch_scc1 .Lq_nl1_k2p1
	s_min_u32 s14, s88, 63
	s_nop 3
	v_readlane_b32 s30, v33, s14
	s_and_b32 s30, s30, 0xff
	s_lshl_b32 s30, s30, 13
	s_add_u32 s64, s11, s30
	s_addc_u32 s65, s12, 0
	s_add_u32 s66, s8, s30
	s_addc_u32 s67, s9, 0
	global_load_dwordx4 v[194:197], v2, s[64:65]
	global_load_dwordx4 v[190:193], v2, s[64:65] offset:1024
	global_load_dwordx4 v[186:189], v2, s[64:65] offset:2048
	global_load_dwordx4 v[182:185], v2, s[64:65] offset:3072
	global_load_dwordx4 v[134:137], v2, s[66:67]
	global_load_dwordx4 v[130:133], v2, s[66:67] offset:1024
	global_load_dwordx4 v[118:121], v2, s[66:67] offset:2048
	global_load_dwordx4 v[102:105], v2, s[66:67] offset:3072
	s_branch .Lq_nl1_k2p1
.Lq_s0n_k2p1:
	v_and_b32_e32 v82, s18, v23
	v_cmp_ne_u32_e32 vcc, 0, v82
	s_and_b64 vcc, s[94:95], vcc
	v_mov_b32 v83, 0
	v_cndmask_b32_e32 v82, v236, v222, vcc
	v_sub_f32_e32 v82, v83, v82
	v_mov_b32_e32 v83, v82
	v_mov_b64_e32 v[84:85], v[82:83]
	v_mov_b64_e32 v[86:87], v[82:83]
	v_mov_b64_e32 v[88:89], v[82:83]
	v_mov_b64_e32 v[90:91], v[82:83]
	v_mov_b64_e32 v[92:93], v[82:83]
	v_mov_b64_e32 v[94:95], v[82:83]
	v_mov_b64_e32 v[96:97], v[82:83]
	s_nop 1
	v_mfma_f32_32x32x16_bf16 v[82:97], v[162:165], v[238:241], v[82:97]
	v_mfma_f32_32x32x16_bf16 v[82:97], v[154:157], v[242:245], v[82:97]
	v_mfma_f32_32x32x16_bf16 v[82:97], v[150:153], v[246:249], v[82:97]
	v_mfma_f32_32x32x16_bf16 v[82:97], v[158:161], v[250:253], v[82:97]
	s_waitcnt vmcnt(12)
	v_mov_b32_e32 v28, 0
	v_and_b32_e32 v34, s18, v23
	v_cmp_ne_u32_e32 vcc, 0, v34
	s_and_b64 vcc, s[94:95], vcc
	v_mov_b32 v35, 0
	v_cndmask_b32_e32 v34, v236, v222, vcc
	v_sub_f32_e32 v34, v35, v34
	v_mov_b32_e32 v35, v34
	v_mov_b64_e32 v[36:37], v[34:35]
	v_mov_b64_e32 v[38:39], v[34:35]
	v_mov_b64_e32 v[40:41], v[34:35]
	v_mov_b64_e32 v[42:43], v[34:35]
	v_mov_b64_e32 v[44:45], v[34:35]
	v_mov_b64_e32 v[46:47], v[34:35]
	v_mov_b64_e32 v[48:49], v[34:35]
	s_nop 1
	v_mfma_f32_32x32x16_bf16 v[34:49], v[194:197], v[238:241], v[34:49]
	v_mfma_f32_32x32x16_bf16 v[34:49], v[190:193], v[242:245], v[34:49]
	v_mfma_f32_32x32x16_bf16 v[34:49], v[186:189], v[246:249], v[34:49]
	v_mfma_f32_32x32x16_bf16 v[34:49], v[182:185], v[250:253], v[34:49]
	v_exp_f32_e32 v82, v82
	v_exp_f32_e32 v83, v83
	v_exp_f32_e32 v84, v84
	v_exp_f32_e32 v85, v85
	v_exp_f32_e32 v86, v86
	v_exp_f32_e32 v87, v87
	v_exp_f32_e32 v88, v88
	v_exp_f32_e32 v89, v89
	v_exp_f32_e32 v90, v90
	v_exp_f32_e32 v91, v91
	v_add_f32_e32 v221, v221, v82
	v_exp_f32_e32 v92, v92
	v_exp_f32_e32 v34, v34
	v_add_f32_e32 v221, v83, v221
	v_exp_f32_e32 v35, v35
	v_exp_f32_e32 v93, v93
	v_exp_f32_e32 v36, v36
	v_add_f32_e32 v221, v84, v221
	v_exp_f32_e32 v37, v37
	v_exp_f32_e32 v94, v94
	v_exp_f32_e32 v38, v38
	v_add_f32_e32 v221, v85, v221
	v_exp_f32_e32 v39, v39
	v_exp_f32_e32 v95, v95
	v_exp_f32_e32 v40, v40
	v_add_f32_e32 v221, v86, v221
	v_exp_f32_e32 v41, v41
	v_cvt_pk_bf16_f32 v82, v82, v83
	v_exp_f32_e32 v42, v42
	v_cvt_pk_bf16_f32 v83, v84, v85
	v_exp_f32_e32 v43, v43
	v_cvt_pk_bf16_f32 v84, v86, v87
	v_add_f32_e32 v28, v28, v34
	v_cvt_pk_bf16_f32 v85, v88, v89
	v_exp_f32_e32 v44, v44
	v_add_f32_e32 v221, v87, v221
	v_add_f32_e32 v28, v35, v28
	v_mfma_f32_32x32x16_bf16 v[66:81], v[138:141], v[82:85], 0
	v_exp_f32_e32 v45, v45
	v_add_f32_e32 v221, v88, v221
	v_add_f32_e32 v28, v36, v28
	v_exp_f32_e32 v86, v96
	v_exp_f32_e32 v46, v46
	v_add_f32_e32 v221, v89, v221
	v_add_f32_e32 v28, v37, v28
	v_mov_b32_e32 v87, v95
	v_exp_f32_e32 v47, v47
	v_mfma_f32_32x32x16_bf16 v[50:65], v[122:125], v[82:85], 0
	v_add_f32_e32 v28, v38, v28
	v_exp_f32_e32 v88, v97
	v_cvt_pk_bf16_f32 v34, v34, v35
	v_cvt_pk_bf16_f32 v82, v90, v91
	v_cvt_pk_bf16_f32 v35, v36, v37
	v_cvt_pk_bf16_f32 v83, v92, v93
	v_cvt_pk_bf16_f32 v36, v38, v39
	v_cvt_pk_bf16_f32 v84, v94, v87
	v_cvt_pk_bf16_f32 v37, v40, v41
	v_cvt_pk_bf16_f32 v85, v86, v88
	v_add_f32_e32 v28, v39, v28
	v_add_f32_e32 v221, v90, v221
	v_mfma_f32_32x32x16_bf16 v[66:81], v[134:137], v[34:37], v[66:81]
	v_add_f32_e32 v89, v91, v221
	v_add_f32_e32 v28, v40, v28
	v_mfma_f32_32x32x16_bf16 v[66:81], v[110:113], v[82:85], v[66:81]
	v_exp_f32_e32 v38, v48
	v_add_f32_e32 v89, v92, v89
	v_add_f32_e32 v28, v41, v28
	v_add_f32_e32 v89, v93, v89
	v_mov_b32_e32 v39, v47
	v_add_f32_e32 v89, v94, v89
	v_mfma_f32_32x32x16_bf16 v[50:65], v[130:133], v[34:37], v[50:65]
	v_add_f32_e32 v87, v87, v89
	v_exp_f32_e32 v40, v49
	v_add_f32_e32 v86, v86, v87
	v_cvt_pk_bf16_f32 v34, v42, v43
	v_add_f32_e32 v221, v88, v86
	v_cvt_pk_bf16_f32 v35, v44, v45
	v_mfma_f32_32x32x16_bf16 v[50:65], v[106:109], v[82:85], v[50:65]
	v_cvt_pk_bf16_f32 v36, v46, v39
	v_cvt_pk_bf16_f32 v37, v38, v40
	v_add_f32_e32 v28, v42, v28
	v_add_f32_e32 v41, v43, v28
	v_mfma_f32_32x32x16_bf16 v[66:81], v[118:121], v[34:37], v[66:81]
	v_add_f32_e32 v41, v44, v41
	v_add_f32_e32 v41, v45, v41
	v_add_f32_e32 v41, v46, v41
	v_add_f32_e32 v39, v39, v41
	v_add_f32_e32 v38, v38, v39
	v_add_f32_e32 v28, v40, v38
	v_mfma_f32_32x32x16_bf16 v[50:65], v[102:105], v[34:37], v[50:65]
	v_add_f32_e32 v221, v221, v28
	s_cmp_lg_u32 s85, s86
	s_cbranch_scc1 .Lq_nl1_k2p1
	s_min_u32 s14, s87, 63
	s_nop 3
	v_readlane_b32 s30, v33, s14
	s_and_b32 s30, s30, 0xff
	s_lshl_b32 s30, s30, 13
	s_or_b32 s30, s30, 0x1000
	s_add_u32 s64, s11, s30
	s_addc_u32 s65, s12, 0
	s_add_u32 s66, s8, s30
	s_addc_u32 s67, s9, 0
	global_load_dwordx4 v[162:165], v2, s[64:65]
	global_load_dwordx4 v[154:157], v2, s[64:65] offset:1024
	global_load_dwordx4 v[150:153], v2, s[64:65] offset:2048
	global_load_dwordx4 v[158:161], v2, s[64:65] offset:3072
	global_load_dwordx4 v[138:141], v2, s[66:67]
	global_load_dwordx4 v[122:125], v2, s[66:67] offset:1024
	global_load_dwordx4 v[110:113], v2, s[66:67] offset:2048
	global_load_dwordx4 v[106:109], v2, s[66:67] offset:3072
	s_min_u32 s14, s88, 63
	s_nop 3
	v_readlane_b32 s30, v33, s14
	s_and_b32 s30, s30, 0xff
	s_lshl_b32 s30, s30, 13
	s_add_u32 s64, s11, s30
	s_addc_u32 s65, s12, 0
	s_add_u32 s66, s8, s30
	s_addc_u32 s67, s9, 0
	global_load_dwordx4 v[194:197], v2, s[64:65]
	global_load_dwordx4 v[190:193], v2, s[64:65] offset:1024
	global_load_dwordx4 v[186:189], v2, s[64:65] offset:2048
	global_load_dwordx4 v[182:185], v2, s[64:65] offset:3072
	global_load_dwordx4 v[134:137], v2, s[66:67]
	global_load_dwordx4 v[130:133], v2, s[66:67] offset:1024
	global_load_dwordx4 v[118:121], v2, s[66:67] offset:2048
	global_load_dwordx4 v[102:105], v2, s[66:67] offset:3072
